# residual epilogues: accumulator fragments exchanged between lane halves (DPP row_ror:8) so each global load/store covers 8 rows x 128 contiguous bytes
# speedup vs baseline: 1.0855x; 1.0148x over previous
.LBB0_274:
	v_lshrrev_b32_e32 v132, 6, v206
	v_and_b32_e32 v143, 63, v206
	v_lshrrev_b32_e32 v142, 2, v132
	v_and_b32_e32 v132, 3, v132
	v_lshlrev_b32_e32 v142, 6, v142
	v_lshrrev_b32_e32 v146, 4, v143
	v_and_b32_e32 v211, 15, v143
	v_xor_b32_e32 v144, 16, v143
	v_xor_b32_e32 v145, 32, v143
	v_lshlrev_b32_e32 v144, 2, v144
	v_lshlrev_b32_e32 v145, 2, v145
	s_lshl_b32 vcc_lo, s24, 8
	v_add_u32_e32 v142, vcc_lo, v142
	s_lshl_b32 vcc_lo, s57, 2
	v_add_u32_e32 v204, vcc_lo, v132
	v_add_u32_e32 v147, v142, v211
	v_lshlrev_b32_e32 v147, 6, v147
	v_lshl_add_u32 v204, v204, 2, v147
	v_lshlrev_b32_e32 v143, 5, v132
	v_lshrrev_b32_e32 v147, 3, v211
	v_lshl_add_u32 v147, v147, 2, v146
	v_lshl_add_u32 v143, v147, 2, v143
	s_lshl_b32 vcc_lo, s57, 8
	v_add_u32_e32 v143, vcc_lo, v143
	v_and_b32_e32 v147, 7, v211
	v_add_u32_e32 v142, v142, v147
	v_lshlrev_b32_e32 v148, 12, v142
	v_lshl_add_u32 v148, v143, 2, v148
	v_add_u32_e32 v149, 0x8000, v148
	v_lshlrev_b32_e32 v158, 11, v142
	v_lshl_add_u32 v158, v143, 1, v158
	v_add_u32_e32 v159, 0x4000, v158
	s_mov_b32 s86, s90
	s_mov_b32 s87, s91
	s_mov_b32 s88, s94
	s_mov_b32 s89, s95
	s_add_u32 s92, s96, 0x9e00000
	s_addc_u32 s93, s97, 0
	s_add_u32 s100, s96, 0x4600000
	s_addc_u32 s101, s97, 0
	global_load_dwordx4 v[164:167], v148, s[86:87]
	global_load_dwordx4 v[168:171], v149, s[86:87]
	global_load_dwordx4 v[172:175], v148, s[86:87] offset:512
	global_load_dwordx4 v[176:179], v149, s[86:87] offset:512
	s_add_u32 s86, s86, 0x10000
	s_addc_u32 s87, s87, 0
	global_load_dwordx4 v[180:183], v148, s[86:87]
	global_load_dwordx4 v[184:187], v149, s[86:87]
	global_load_dwordx4 v[188:191], v148, s[86:87] offset:512
	global_load_dwordx4 v[192:195], v149, s[86:87] offset:512
	s_add_u32 s86, s86, 0x10000
	s_addc_u32 s87, s87, 0
	global_load_dwordx4 v[196:199], v148, s[86:87]
	global_load_dwordx4 v[200:203], v149, s[86:87]
	global_load_dwordx4 v[212:215], v148, s[86:87] offset:512
	v_mov_b32_e32 v160, v120
	v_mov_b32_e32 v161, v121
	v_mov_b32_e32 v162, v122
	v_mov_b32_e32 v163, v123
	v_mov_b32_dpp v120, v124 row_ror:8 row_mask:0xf bank_mask:0x3
	v_mov_b32_dpp v121, v125 row_ror:8 row_mask:0xf bank_mask:0x3
	v_mov_b32_dpp v122, v126 row_ror:8 row_mask:0xf bank_mask:0x3
	v_mov_b32_dpp v123, v127 row_ror:8 row_mask:0xf bank_mask:0x3
	v_mov_b32_dpp v124, v160 row_ror:8 row_mask:0xf bank_mask:0xc
	v_mov_b32_dpp v125, v161 row_ror:8 row_mask:0xf bank_mask:0xc
	v_mov_b32_dpp v126, v162 row_ror:8 row_mask:0xf bank_mask:0xc
	v_mov_b32_dpp v127, v163 row_ror:8 row_mask:0xf bank_mask:0xc
	s_waitcnt vmcnt(10)
	v_fma_f32 v124, v124, 0.5, v164
	v_fma_f32 v125, v125, 0.5, v165
	v_fma_f32 v126, v126, 0.5, v166
	v_fma_f32 v127, v127, 0.5, v167
	global_store_dwordx4 v148, v[124:127], s[88:89]
	v_cvt_pk_bf16_f32 v164, v124, v125
	v_cvt_pk_bf16_f32 v165, v126, v127
	global_store_dwordx2 v158, v[164:165], s[92:93]
	v_mul_f32_e32 v205, v124, v124
	v_fmac_f32_e32 v205, v125, v125
	v_fmac_f32_e32 v205, v126, v126
	v_fmac_f32_e32 v205, v127, v127
	global_load_dwordx4 v[164:167], v149, s[86:87] offset:512
	s_waitcnt vmcnt(12)
	v_fma_f32 v120, v120, 0.5, v168
	v_fma_f32 v121, v121, 0.5, v169
	v_fma_f32 v122, v122, 0.5, v170
	v_fma_f32 v123, v123, 0.5, v171
	global_store_dwordx4 v149, v[120:123], s[88:89]
	v_cvt_pk_bf16_f32 v168, v120, v121
	v_cvt_pk_bf16_f32 v169, v122, v123
	global_store_dwordx2 v159, v[168:169], s[92:93]
	v_mul_f32_e32 v210, v120, v120
	v_fmac_f32_e32 v210, v121, v121
	v_fmac_f32_e32 v210, v122, v122
	v_fmac_f32_e32 v210, v123, v123
	s_add_u32 s86, s86, 0x10000
	s_addc_u32 s87, s87, 0
	global_load_dwordx4 v[168:171], v148, s[86:87]
	v_mov_b32_e32 v160, v112
	v_mov_b32_e32 v161, v113
	v_mov_b32_e32 v162, v114
	v_mov_b32_e32 v163, v115
	v_mov_b32_dpp v112, v116 row_ror:8 row_mask:0xf bank_mask:0x3
	v_mov_b32_dpp v113, v117 row_ror:8 row_mask:0xf bank_mask:0x3
	v_mov_b32_dpp v114, v118 row_ror:8 row_mask:0xf bank_mask:0x3
	v_mov_b32_dpp v115, v119 row_ror:8 row_mask:0xf bank_mask:0x3
	v_mov_b32_dpp v116, v160 row_ror:8 row_mask:0xf bank_mask:0xc
	v_mov_b32_dpp v117, v161 row_ror:8 row_mask:0xf bank_mask:0xc
	v_mov_b32_dpp v118, v162 row_ror:8 row_mask:0xf bank_mask:0xc
	v_mov_b32_dpp v119, v163 row_ror:8 row_mask:0xf bank_mask:0xc
	s_waitcnt vmcnt(14)
	v_fma_f32 v116, v116, 0.5, v172
	v_fma_f32 v117, v117, 0.5, v173
	v_fma_f32 v118, v118, 0.5, v174
	v_fma_f32 v119, v119, 0.5, v175
	global_store_dwordx4 v148, v[116:119], s[88:89] offset:512
	v_cvt_pk_bf16_f32 v172, v116, v117
	v_cvt_pk_bf16_f32 v173, v118, v119
	global_store_dwordx2 v158, v[172:173], s[92:93] offset:256
	v_fmac_f32_e32 v205, v116, v116
	v_fmac_f32_e32 v205, v117, v117
	v_fmac_f32_e32 v205, v118, v118
	v_fmac_f32_e32 v205, v119, v119
	global_load_dwordx4 v[172:175], v149, s[86:87]
	s_waitcnt vmcnt(16)
	v_fma_f32 v112, v112, 0.5, v176
	v_fma_f32 v113, v113, 0.5, v177
	v_fma_f32 v114, v114, 0.5, v178
	v_fma_f32 v115, v115, 0.5, v179
	global_store_dwordx4 v149, v[112:115], s[88:89] offset:512
	v_cvt_pk_bf16_f32 v176, v112, v113
	v_cvt_pk_bf16_f32 v177, v114, v115
	global_store_dwordx2 v159, v[176:177], s[92:93] offset:256
	v_fmac_f32_e32 v210, v112, v112
	v_fmac_f32_e32 v210, v113, v113
	v_fmac_f32_e32 v210, v114, v114
	v_fmac_f32_e32 v210, v115, v115
	global_load_dwordx4 v[176:179], v148, s[86:87] offset:512
	s_nop 1
	v_add_f32_dpp v205, v205, v205 row_ror:8 row_mask:0xf bank_mask:0xf
	v_add_f32_dpp v210, v210, v210 row_ror:8 row_mask:0xf bank_mask:0xf
	s_nop 0
	ds_bpermute_b32 v147, v144, v205
	ds_bpermute_b32 v132, v144, v210
	s_waitcnt lgkmcnt(0)
	v_add_f32_e32 v205, v205, v147
	v_add_f32_e32 v210, v210, v132
	s_nop 0
	ds_bpermute_b32 v147, v145, v205
	ds_bpermute_b32 v132, v145, v210
	s_waitcnt lgkmcnt(0)
	v_add_f32_e32 v205, v205, v147
	v_add_f32_e32 v210, v210, v132
	v_cmp_gt_u32_e32 vcc, 8, v211
	s_nop 1
	v_cndmask_b32_e32 v205, v210, v205, vcc
	v_cmp_eq_u32_e32 vcc, 0, v146
	s_and_saveexec_b64 s[98:99], vcc
	global_store_dword v204, v205, s[100:101]
	s_mov_b64 exec, s[98:99]
	s_add_u32 s88, s88, 0x10000
	s_addc_u32 s89, s89, 0
	s_add_u32 s92, s92, 0x8000
	s_addc_u32 s93, s93, 0
	s_add_u32 s100, s100, 0x400
	s_addc_u32 s101, s101, 0
	v_mov_b32_e32 v160, v104
	v_mov_b32_e32 v161, v105
	v_mov_b32_e32 v162, v106
	v_mov_b32_e32 v163, v107
	v_mov_b32_dpp v104, v108 row_ror:8 row_mask:0xf bank_mask:0x3
	v_mov_b32_dpp v105, v109 row_ror:8 row_mask:0xf bank_mask:0x3
	v_mov_b32_dpp v106, v110 row_ror:8 row_mask:0xf bank_mask:0x3
	v_mov_b32_dpp v107, v111 row_ror:8 row_mask:0xf bank_mask:0x3
	v_mov_b32_dpp v108, v160 row_ror:8 row_mask:0xf bank_mask:0xc
	v_mov_b32_dpp v109, v161 row_ror:8 row_mask:0xf bank_mask:0xc
	v_mov_b32_dpp v110, v162 row_ror:8 row_mask:0xf bank_mask:0xc
	v_mov_b32_dpp v111, v163 row_ror:8 row_mask:0xf bank_mask:0xc
	s_waitcnt vmcnt(19)
	v_fma_f32 v108, v108, 0.5, v180
	v_fma_f32 v109, v109, 0.5, v181
	v_fma_f32 v110, v110, 0.5, v182
	v_fma_f32 v111, v111, 0.5, v183
	global_store_dwordx4 v148, v[108:111], s[88:89]
	v_cvt_pk_bf16_f32 v180, v108, v109
	v_cvt_pk_bf16_f32 v181, v110, v111
	global_store_dwordx2 v158, v[180:181], s[92:93]
	v_mul_f32_e32 v205, v108, v108
	v_fmac_f32_e32 v205, v109, v109
	v_fmac_f32_e32 v205, v110, v110
	v_fmac_f32_e32 v205, v111, v111
	global_load_dwordx4 v[180:183], v149, s[86:87] offset:512
	s_waitcnt vmcnt(21)
	v_fma_f32 v104, v104, 0.5, v184
	v_fma_f32 v105, v105, 0.5, v185
	v_fma_f32 v106, v106, 0.5, v186
	v_fma_f32 v107, v107, 0.5, v187
	global_store_dwordx4 v149, v[104:107], s[88:89]
	v_cvt_pk_bf16_f32 v184, v104, v105
	v_cvt_pk_bf16_f32 v185, v106, v107
	global_store_dwordx2 v159, v[184:185], s[92:93]
	v_mul_f32_e32 v210, v104, v104
	v_fmac_f32_e32 v210, v105, v105
	v_fmac_f32_e32 v210, v106, v106
	v_fmac_f32_e32 v210, v107, v107
	s_add_u32 s86, s86, 0x50000
	s_addc_u32 s87, s87, 0
	global_load_dwordx4 v[184:187], v148, s[86:87]
	v_mov_b32_e32 v160, v96
	v_mov_b32_e32 v161, v97
	v_mov_b32_e32 v162, v98
	v_mov_b32_e32 v163, v99
	v_mov_b32_dpp v96, v100 row_ror:8 row_mask:0xf bank_mask:0x3
	v_mov_b32_dpp v97, v101 row_ror:8 row_mask:0xf bank_mask:0x3
	v_mov_b32_dpp v98, v102 row_ror:8 row_mask:0xf bank_mask:0x3
	v_mov_b32_dpp v99, v103 row_ror:8 row_mask:0xf bank_mask:0x3
	v_mov_b32_dpp v100, v160 row_ror:8 row_mask:0xf bank_mask:0xc
	v_mov_b32_dpp v101, v161 row_ror:8 row_mask:0xf bank_mask:0xc
	v_mov_b32_dpp v102, v162 row_ror:8 row_mask:0xf bank_mask:0xc
	v_mov_b32_dpp v103, v163 row_ror:8 row_mask:0xf bank_mask:0xc
	s_waitcnt vmcnt(23)
	v_fma_f32 v100, v100, 0.5, v188
	v_fma_f32 v101, v101, 0.5, v189
	v_fma_f32 v102, v102, 0.5, v190
	v_fma_f32 v103, v103, 0.5, v191
	global_store_dwordx4 v148, v[100:103], s[88:89] offset:512
	v_cvt_pk_bf16_f32 v188, v100, v101
	v_cvt_pk_bf16_f32 v189, v102, v103
	global_store_dwordx2 v158, v[188:189], s[92:93] offset:256
	v_fmac_f32_e32 v205, v100, v100
	v_fmac_f32_e32 v205, v101, v101
	v_fmac_f32_e32 v205, v102, v102
	v_fmac_f32_e32 v205, v103, v103
	global_load_dwordx4 v[188:191], v149, s[86:87]
	s_waitcnt vmcnt(25)
	v_fma_f32 v96, v96, 0.5, v192
	v_fma_f32 v97, v97, 0.5, v193
	v_fma_f32 v98, v98, 0.5, v194
	v_fma_f32 v99, v99, 0.5, v195
	global_store_dwordx4 v149, v[96:99], s[88:89] offset:512
	v_cvt_pk_bf16_f32 v192, v96, v97
	v_cvt_pk_bf16_f32 v193, v98, v99
	global_store_dwordx2 v159, v[192:193], s[92:93] offset:256
	v_fmac_f32_e32 v210, v96, v96
	v_fmac_f32_e32 v210, v97, v97
	v_fmac_f32_e32 v210, v98, v98
	v_fmac_f32_e32 v210, v99, v99
	global_load_dwordx4 v[192:195], v148, s[86:87] offset:512
	s_nop 1
	v_add_f32_dpp v205, v205, v205 row_ror:8 row_mask:0xf bank_mask:0xf
	v_add_f32_dpp v210, v210, v210 row_ror:8 row_mask:0xf bank_mask:0xf
	s_nop 0
	ds_bpermute_b32 v147, v144, v205
	ds_bpermute_b32 v132, v144, v210
	s_waitcnt lgkmcnt(0)
	v_add_f32_e32 v205, v205, v147
	v_add_f32_e32 v210, v210, v132
	s_nop 0
	ds_bpermute_b32 v147, v145, v205
	ds_bpermute_b32 v132, v145, v210
	s_waitcnt lgkmcnt(0)
	v_add_f32_e32 v205, v205, v147
	v_add_f32_e32 v210, v210, v132
	v_cmp_gt_u32_e32 vcc, 8, v211
	s_nop 1
	v_cndmask_b32_e32 v205, v210, v205, vcc
	v_cmp_eq_u32_e32 vcc, 0, v146
	s_and_saveexec_b64 s[98:99], vcc
	global_store_dword v204, v205, s[100:101]
	s_mov_b64 exec, s[98:99]
	s_add_u32 s88, s88, 0x10000
	s_addc_u32 s89, s89, 0
	s_add_u32 s92, s92, 0x8000
	s_addc_u32 s93, s93, 0
	s_add_u32 s100, s100, 0x400
	s_addc_u32 s101, s101, 0
	v_mov_b32_e32 v160, v88
	v_mov_b32_e32 v161, v89
	v_mov_b32_e32 v162, v90
	v_mov_b32_e32 v163, v91
	v_mov_b32_dpp v88, v92 row_ror:8 row_mask:0xf bank_mask:0x3
	v_mov_b32_dpp v89, v93 row_ror:8 row_mask:0xf bank_mask:0x3
	v_mov_b32_dpp v90, v94 row_ror:8 row_mask:0xf bank_mask:0x3
	v_mov_b32_dpp v91, v95 row_ror:8 row_mask:0xf bank_mask:0x3
	v_mov_b32_dpp v92, v160 row_ror:8 row_mask:0xf bank_mask:0xc
	v_mov_b32_dpp v93, v161 row_ror:8 row_mask:0xf bank_mask:0xc
	v_mov_b32_dpp v94, v162 row_ror:8 row_mask:0xf bank_mask:0xc
	v_mov_b32_dpp v95, v163 row_ror:8 row_mask:0xf bank_mask:0xc
	s_waitcnt vmcnt(28)
	v_fma_f32 v92, v92, 0.5, v196
	v_fma_f32 v93, v93, 0.5, v197
	v_fma_f32 v94, v94, 0.5, v198
	v_fma_f32 v95, v95, 0.5, v199
	global_store_dwordx4 v148, v[92:95], s[88:89]
	v_cvt_pk_bf16_f32 v196, v92, v93
	v_cvt_pk_bf16_f32 v197, v94, v95
	global_store_dwordx2 v158, v[196:197], s[92:93]
	v_mul_f32_e32 v205, v92, v92
	v_fmac_f32_e32 v205, v93, v93
	v_fmac_f32_e32 v205, v94, v94
	v_fmac_f32_e32 v205, v95, v95
	global_load_dwordx4 v[196:199], v149, s[86:87] offset:512
	s_waitcnt vmcnt(30)
	v_fma_f32 v88, v88, 0.5, v200
	v_fma_f32 v89, v89, 0.5, v201
	v_fma_f32 v90, v90, 0.5, v202
	v_fma_f32 v91, v91, 0.5, v203
	global_store_dwordx4 v149, v[88:91], s[88:89]
	v_cvt_pk_bf16_f32 v200, v88, v89
	v_cvt_pk_bf16_f32 v201, v90, v91
	global_store_dwordx2 v159, v[200:201], s[92:93]
	v_mul_f32_e32 v210, v88, v88
	v_fmac_f32_e32 v210, v89, v89
	v_fmac_f32_e32 v210, v90, v90
	v_fmac_f32_e32 v210, v91, v91
	s_add_u32 s86, s86, 0x10000
	s_addc_u32 s87, s87, 0
	global_load_dwordx4 v[200:203], v148, s[86:87]
	v_mov_b32_e32 v160, v80
	v_mov_b32_e32 v161, v81
	v_mov_b32_e32 v162, v82
	v_mov_b32_e32 v163, v83
	v_mov_b32_dpp v80, v84 row_ror:8 row_mask:0xf bank_mask:0x3
	v_mov_b32_dpp v81, v85 row_ror:8 row_mask:0xf bank_mask:0x3
	v_mov_b32_dpp v82, v86 row_ror:8 row_mask:0xf bank_mask:0x3
	v_mov_b32_dpp v83, v87 row_ror:8 row_mask:0xf bank_mask:0x3
	v_mov_b32_dpp v84, v160 row_ror:8 row_mask:0xf bank_mask:0xc
	v_mov_b32_dpp v85, v161 row_ror:8 row_mask:0xf bank_mask:0xc
	v_mov_b32_dpp v86, v162 row_ror:8 row_mask:0xf bank_mask:0xc
	v_mov_b32_dpp v87, v163 row_ror:8 row_mask:0xf bank_mask:0xc
	s_waitcnt vmcnt(32)
	v_fma_f32 v84, v84, 0.5, v212
	v_fma_f32 v85, v85, 0.5, v213
	v_fma_f32 v86, v86, 0.5, v214
	v_fma_f32 v87, v87, 0.5, v215
	global_store_dwordx4 v148, v[84:87], s[88:89] offset:512
	v_cvt_pk_bf16_f32 v212, v84, v85
	v_cvt_pk_bf16_f32 v213, v86, v87
	global_store_dwordx2 v158, v[212:213], s[92:93] offset:256
	v_fmac_f32_e32 v205, v84, v84
	v_fmac_f32_e32 v205, v85, v85
	v_fmac_f32_e32 v205, v86, v86
	v_fmac_f32_e32 v205, v87, v87
	global_load_dwordx4 v[212:215], v149, s[86:87]
	s_waitcnt vmcnt(32)
	v_fma_f32 v80, v80, 0.5, v164
	v_fma_f32 v81, v81, 0.5, v165
	v_fma_f32 v82, v82, 0.5, v166
	v_fma_f32 v83, v83, 0.5, v167
	global_store_dwordx4 v149, v[80:83], s[88:89] offset:512
	v_cvt_pk_bf16_f32 v164, v80, v81
	v_cvt_pk_bf16_f32 v165, v82, v83
	global_store_dwordx2 v159, v[164:165], s[92:93] offset:256
	v_fmac_f32_e32 v210, v80, v80
	v_fmac_f32_e32 v210, v81, v81
	v_fmac_f32_e32 v210, v82, v82
	v_fmac_f32_e32 v210, v83, v83
	global_load_dwordx4 v[164:167], v148, s[86:87] offset:512
	s_nop 1
	v_add_f32_dpp v205, v205, v205 row_ror:8 row_mask:0xf bank_mask:0xf
	v_add_f32_dpp v210, v210, v210 row_ror:8 row_mask:0xf bank_mask:0xf
	s_nop 0
	ds_bpermute_b32 v147, v144, v205
	ds_bpermute_b32 v132, v144, v210
	s_waitcnt lgkmcnt(0)
	v_add_f32_e32 v205, v205, v147
	v_add_f32_e32 v210, v210, v132
	s_nop 0
	ds_bpermute_b32 v147, v145, v205
	ds_bpermute_b32 v132, v145, v210
	s_waitcnt lgkmcnt(0)
	v_add_f32_e32 v205, v205, v147
	v_add_f32_e32 v210, v210, v132
	v_cmp_gt_u32_e32 vcc, 8, v211
	s_nop 1
	v_cndmask_b32_e32 v205, v210, v205, vcc
	v_cmp_eq_u32_e32 vcc, 0, v146
	s_and_saveexec_b64 s[98:99], vcc
	global_store_dword v204, v205, s[100:101]
	s_mov_b64 exec, s[98:99]
	s_add_u32 s88, s88, 0x10000
	s_addc_u32 s89, s89, 0
	s_add_u32 s92, s92, 0x8000
	s_addc_u32 s93, s93, 0
	s_add_u32 s100, s100, 0x400
	s_addc_u32 s101, s101, 0
	v_mov_b32_e32 v160, v72
	v_mov_b32_e32 v161, v73
	v_mov_b32_e32 v162, v74
	v_mov_b32_e32 v163, v75
	v_mov_b32_dpp v72, v76 row_ror:8 row_mask:0xf bank_mask:0x3
	v_mov_b32_dpp v73, v77 row_ror:8 row_mask:0xf bank_mask:0x3
	v_mov_b32_dpp v74, v78 row_ror:8 row_mask:0xf bank_mask:0x3
	v_mov_b32_dpp v75, v79 row_ror:8 row_mask:0xf bank_mask:0x3
	v_mov_b32_dpp v76, v160 row_ror:8 row_mask:0xf bank_mask:0xc
	v_mov_b32_dpp v77, v161 row_ror:8 row_mask:0xf bank_mask:0xc
	v_mov_b32_dpp v78, v162 row_ror:8 row_mask:0xf bank_mask:0xc
	v_mov_b32_dpp v79, v163 row_ror:8 row_mask:0xf bank_mask:0xc
	s_waitcnt vmcnt(33)
	v_fma_f32 v76, v76, 0.5, v168
	v_fma_f32 v77, v77, 0.5, v169
	v_fma_f32 v78, v78, 0.5, v170
	v_fma_f32 v79, v79, 0.5, v171
	global_store_dwordx4 v148, v[76:79], s[88:89]
	v_cvt_pk_bf16_f32 v168, v76, v77
	v_cvt_pk_bf16_f32 v169, v78, v79
	global_store_dwordx2 v158, v[168:169], s[92:93]
	v_mul_f32_e32 v205, v76, v76
	v_fmac_f32_e32 v205, v77, v77
	v_fmac_f32_e32 v205, v78, v78
	v_fmac_f32_e32 v205, v79, v79
	global_load_dwordx4 v[168:171], v149, s[86:87] offset:512
	s_waitcnt vmcnt(33)
	v_fma_f32 v72, v72, 0.5, v172
	v_fma_f32 v73, v73, 0.5, v173
	v_fma_f32 v74, v74, 0.5, v174
	v_fma_f32 v75, v75, 0.5, v175
	global_store_dwordx4 v149, v[72:75], s[88:89]
	v_cvt_pk_bf16_f32 v172, v72, v73
	v_cvt_pk_bf16_f32 v173, v74, v75
	global_store_dwordx2 v159, v[172:173], s[92:93]
	v_mul_f32_e32 v210, v72, v72
	v_fmac_f32_e32 v210, v73, v73
	v_fmac_f32_e32 v210, v74, v74
	v_fmac_f32_e32 v210, v75, v75
	s_add_u32 s86, s86, 0x10000
	s_addc_u32 s87, s87, 0
	global_load_dwordx4 v[172:175], v148, s[86:87]
	v_mov_b32_e32 v160, v64
	v_mov_b32_e32 v161, v65
	v_mov_b32_e32 v162, v66
	v_mov_b32_e32 v163, v67
	v_mov_b32_dpp v64, v68 row_ror:8 row_mask:0xf bank_mask:0x3
	v_mov_b32_dpp v65, v69 row_ror:8 row_mask:0xf bank_mask:0x3
	v_mov_b32_dpp v66, v70 row_ror:8 row_mask:0xf bank_mask:0x3
	v_mov_b32_dpp v67, v71 row_ror:8 row_mask:0xf bank_mask:0x3
	v_mov_b32_dpp v68, v160 row_ror:8 row_mask:0xf bank_mask:0xc
	v_mov_b32_dpp v69, v161 row_ror:8 row_mask:0xf bank_mask:0xc
	v_mov_b32_dpp v70, v162 row_ror:8 row_mask:0xf bank_mask:0xc
	v_mov_b32_dpp v71, v163 row_ror:8 row_mask:0xf bank_mask:0xc
	s_waitcnt vmcnt(33)
	v_fma_f32 v68, v68, 0.5, v176
	v_fma_f32 v69, v69, 0.5, v177
	v_fma_f32 v70, v70, 0.5, v178
	v_fma_f32 v71, v71, 0.5, v179
	global_store_dwordx4 v148, v[68:71], s[88:89] offset:512
	v_cvt_pk_bf16_f32 v176, v68, v69
	v_cvt_pk_bf16_f32 v177, v70, v71
	global_store_dwordx2 v158, v[176:177], s[92:93] offset:256
	v_fmac_f32_e32 v205, v68, v68
	v_fmac_f32_e32 v205, v69, v69
	v_fmac_f32_e32 v205, v70, v70
	v_fmac_f32_e32 v205, v71, v71
	global_load_dwordx4 v[176:179], v149, s[86:87]
	s_waitcnt vmcnt(32)
	v_fma_f32 v64, v64, 0.5, v180
	v_fma_f32 v65, v65, 0.5, v181
	v_fma_f32 v66, v66, 0.5, v182
	v_fma_f32 v67, v67, 0.5, v183
	global_store_dwordx4 v149, v[64:67], s[88:89] offset:512
	v_cvt_pk_bf16_f32 v180, v64, v65
	v_cvt_pk_bf16_f32 v181, v66, v67
	global_store_dwordx2 v159, v[180:181], s[92:93] offset:256
	v_fmac_f32_e32 v210, v64, v64
	v_fmac_f32_e32 v210, v65, v65
	v_fmac_f32_e32 v210, v66, v66
	v_fmac_f32_e32 v210, v67, v67
	global_load_dwordx4 v[180:183], v148, s[86:87] offset:512
	s_nop 1
	v_add_f32_dpp v205, v205, v205 row_ror:8 row_mask:0xf bank_mask:0xf
	v_add_f32_dpp v210, v210, v210 row_ror:8 row_mask:0xf bank_mask:0xf
	s_nop 0
	ds_bpermute_b32 v147, v144, v205
	ds_bpermute_b32 v132, v144, v210
	s_waitcnt lgkmcnt(0)
	v_add_f32_e32 v205, v205, v147
	v_add_f32_e32 v210, v210, v132
	s_nop 0
	ds_bpermute_b32 v147, v145, v205
	ds_bpermute_b32 v132, v145, v210
	s_waitcnt lgkmcnt(0)
	v_add_f32_e32 v205, v205, v147
	v_add_f32_e32 v210, v210, v132
	v_cmp_gt_u32_e32 vcc, 8, v211
	s_nop 1
	v_cndmask_b32_e32 v205, v210, v205, vcc
	v_cmp_eq_u32_e32 vcc, 0, v146
	s_and_saveexec_b64 s[98:99], vcc
	global_store_dword v204, v205, s[100:101]
	s_mov_b64 exec, s[98:99]
	s_add_u32 s88, s88, 0x50000
	s_addc_u32 s89, s89, 0
	s_add_u32 s92, s92, 0x28000
	s_addc_u32 s93, s93, 0
	s_add_u32 s100, s100, 0x1400
	s_addc_u32 s101, s101, 0
	v_mov_b32_e32 v160, v56
	v_mov_b32_e32 v161, v57
	v_mov_b32_e32 v162, v58
	v_mov_b32_e32 v163, v59
	v_mov_b32_dpp v56, v60 row_ror:8 row_mask:0xf bank_mask:0x3
	v_mov_b32_dpp v57, v61 row_ror:8 row_mask:0xf bank_mask:0x3
	v_mov_b32_dpp v58, v62 row_ror:8 row_mask:0xf bank_mask:0x3
	v_mov_b32_dpp v59, v63 row_ror:8 row_mask:0xf bank_mask:0x3
	v_mov_b32_dpp v60, v160 row_ror:8 row_mask:0xf bank_mask:0xc
	v_mov_b32_dpp v61, v161 row_ror:8 row_mask:0xf bank_mask:0xc
	v_mov_b32_dpp v62, v162 row_ror:8 row_mask:0xf bank_mask:0xc
	v_mov_b32_dpp v63, v163 row_ror:8 row_mask:0xf bank_mask:0xc
	s_waitcnt vmcnt(33)
	v_fma_f32 v60, v60, 0.5, v184
	v_fma_f32 v61, v61, 0.5, v185
	v_fma_f32 v62, v62, 0.5, v186
	v_fma_f32 v63, v63, 0.5, v187
	global_store_dwordx4 v148, v[60:63], s[88:89]
	v_cvt_pk_bf16_f32 v184, v60, v61
	v_cvt_pk_bf16_f32 v185, v62, v63
	global_store_dwordx2 v158, v[184:185], s[92:93]
	v_mul_f32_e32 v205, v60, v60
	v_fmac_f32_e32 v205, v61, v61
	v_fmac_f32_e32 v205, v62, v62
	v_fmac_f32_e32 v205, v63, v63
	global_load_dwordx4 v[184:187], v149, s[86:87] offset:512
	s_waitcnt vmcnt(33)
	v_fma_f32 v56, v56, 0.5, v188
	v_fma_f32 v57, v57, 0.5, v189
	v_fma_f32 v58, v58, 0.5, v190
	v_fma_f32 v59, v59, 0.5, v191
	global_store_dwordx4 v149, v[56:59], s[88:89]
	v_cvt_pk_bf16_f32 v188, v56, v57
	v_cvt_pk_bf16_f32 v189, v58, v59
	global_store_dwordx2 v159, v[188:189], s[92:93]
	v_mul_f32_e32 v210, v56, v56
	v_fmac_f32_e32 v210, v57, v57
	v_fmac_f32_e32 v210, v58, v58
	v_fmac_f32_e32 v210, v59, v59
	s_add_u32 s86, s86, 0x10000
	s_addc_u32 s87, s87, 0
	global_load_dwordx4 v[188:191], v148, s[86:87]
	v_mov_b32_e32 v160, v48
	v_mov_b32_e32 v161, v49
	v_mov_b32_e32 v162, v50
	v_mov_b32_e32 v163, v51
	v_mov_b32_dpp v48, v52 row_ror:8 row_mask:0xf bank_mask:0x3
	v_mov_b32_dpp v49, v53 row_ror:8 row_mask:0xf bank_mask:0x3
	v_mov_b32_dpp v50, v54 row_ror:8 row_mask:0xf bank_mask:0x3
	v_mov_b32_dpp v51, v55 row_ror:8 row_mask:0xf bank_mask:0x3
	v_mov_b32_dpp v52, v160 row_ror:8 row_mask:0xf bank_mask:0xc
	v_mov_b32_dpp v53, v161 row_ror:8 row_mask:0xf bank_mask:0xc
	v_mov_b32_dpp v54, v162 row_ror:8 row_mask:0xf bank_mask:0xc
	v_mov_b32_dpp v55, v163 row_ror:8 row_mask:0xf bank_mask:0xc
	s_waitcnt vmcnt(33)
	v_fma_f32 v52, v52, 0.5, v192
	v_fma_f32 v53, v53, 0.5, v193
	v_fma_f32 v54, v54, 0.5, v194
	v_fma_f32 v55, v55, 0.5, v195
	global_store_dwordx4 v148, v[52:55], s[88:89] offset:512
	v_cvt_pk_bf16_f32 v192, v52, v53
	v_cvt_pk_bf16_f32 v193, v54, v55
	global_store_dwordx2 v158, v[192:193], s[92:93] offset:256
	v_fmac_f32_e32 v205, v52, v52
	v_fmac_f32_e32 v205, v53, v53
	v_fmac_f32_e32 v205, v54, v54
	v_fmac_f32_e32 v205, v55, v55
	global_load_dwordx4 v[192:195], v149, s[86:87]
	s_waitcnt vmcnt(32)
	v_fma_f32 v48, v48, 0.5, v196
	v_fma_f32 v49, v49, 0.5, v197
	v_fma_f32 v50, v50, 0.5, v198
	v_fma_f32 v51, v51, 0.5, v199
	global_store_dwordx4 v149, v[48:51], s[88:89] offset:512
	v_cvt_pk_bf16_f32 v196, v48, v49
	v_cvt_pk_bf16_f32 v197, v50, v51
	global_store_dwordx2 v159, v[196:197], s[92:93] offset:256
	v_fmac_f32_e32 v210, v48, v48
	v_fmac_f32_e32 v210, v49, v49
	v_fmac_f32_e32 v210, v50, v50
	v_fmac_f32_e32 v210, v51, v51
	global_load_dwordx4 v[196:199], v148, s[86:87] offset:512
	s_nop 1
	v_add_f32_dpp v205, v205, v205 row_ror:8 row_mask:0xf bank_mask:0xf
	v_add_f32_dpp v210, v210, v210 row_ror:8 row_mask:0xf bank_mask:0xf
	s_nop 0
	ds_bpermute_b32 v147, v144, v205
	ds_bpermute_b32 v132, v144, v210
	s_waitcnt lgkmcnt(0)
	v_add_f32_e32 v205, v205, v147
	v_add_f32_e32 v210, v210, v132
	s_nop 0
	ds_bpermute_b32 v147, v145, v205
	ds_bpermute_b32 v132, v145, v210
	s_waitcnt lgkmcnt(0)
	v_add_f32_e32 v205, v205, v147
	v_add_f32_e32 v210, v210, v132
	v_cmp_gt_u32_e32 vcc, 8, v211
	s_nop 1
	v_cndmask_b32_e32 v205, v210, v205, vcc
	v_cmp_eq_u32_e32 vcc, 0, v146
	s_and_saveexec_b64 s[98:99], vcc
	global_store_dword v204, v205, s[100:101]
	s_mov_b64 exec, s[98:99]
	s_add_u32 s88, s88, 0x10000
	s_addc_u32 s89, s89, 0
	s_add_u32 s92, s92, 0x8000
	s_addc_u32 s93, s93, 0
	s_add_u32 s100, s100, 0x400
	s_addc_u32 s101, s101, 0
	v_mov_b32_e32 v160, v40
	v_mov_b32_e32 v161, v41
	v_mov_b32_e32 v162, v42
	v_mov_b32_e32 v163, v43
	v_mov_b32_dpp v40, v44 row_ror:8 row_mask:0xf bank_mask:0x3
	v_mov_b32_dpp v41, v45 row_ror:8 row_mask:0xf bank_mask:0x3
	v_mov_b32_dpp v42, v46 row_ror:8 row_mask:0xf bank_mask:0x3
	v_mov_b32_dpp v43, v47 row_ror:8 row_mask:0xf bank_mask:0x3
	v_mov_b32_dpp v44, v160 row_ror:8 row_mask:0xf bank_mask:0xc
	v_mov_b32_dpp v45, v161 row_ror:8 row_mask:0xf bank_mask:0xc
	v_mov_b32_dpp v46, v162 row_ror:8 row_mask:0xf bank_mask:0xc
	v_mov_b32_dpp v47, v163 row_ror:8 row_mask:0xf bank_mask:0xc
	s_waitcnt vmcnt(33)
	v_fma_f32 v44, v44, 0.5, v200
	v_fma_f32 v45, v45, 0.5, v201
	v_fma_f32 v46, v46, 0.5, v202
	v_fma_f32 v47, v47, 0.5, v203
	global_store_dwordx4 v148, v[44:47], s[88:89]
	v_cvt_pk_bf16_f32 v200, v44, v45
	v_cvt_pk_bf16_f32 v201, v46, v47
	global_store_dwordx2 v158, v[200:201], s[92:93]
	v_mul_f32_e32 v205, v44, v44
	v_fmac_f32_e32 v205, v45, v45
	v_fmac_f32_e32 v205, v46, v46
	v_fmac_f32_e32 v205, v47, v47
	global_load_dwordx4 v[200:203], v149, s[86:87] offset:512
	s_waitcnt vmcnt(33)
	v_fma_f32 v40, v40, 0.5, v212
	v_fma_f32 v41, v41, 0.5, v213
	v_fma_f32 v42, v42, 0.5, v214
	v_fma_f32 v43, v43, 0.5, v215
	global_store_dwordx4 v149, v[40:43], s[88:89]
	v_cvt_pk_bf16_f32 v212, v40, v41
	v_cvt_pk_bf16_f32 v213, v42, v43
	global_store_dwordx2 v159, v[212:213], s[92:93]
	v_mul_f32_e32 v210, v40, v40
	v_fmac_f32_e32 v210, v41, v41
	v_fmac_f32_e32 v210, v42, v42
	v_fmac_f32_e32 v210, v43, v43
	v_mov_b32_e32 v160, v32
	v_mov_b32_e32 v161, v33
	v_mov_b32_e32 v162, v34
	v_mov_b32_e32 v163, v35
	v_mov_b32_dpp v32, v36 row_ror:8 row_mask:0xf bank_mask:0x3
	v_mov_b32_dpp v33, v37 row_ror:8 row_mask:0xf bank_mask:0x3
	v_mov_b32_dpp v34, v38 row_ror:8 row_mask:0xf bank_mask:0x3
	v_mov_b32_dpp v35, v39 row_ror:8 row_mask:0xf bank_mask:0x3
	v_mov_b32_dpp v36, v160 row_ror:8 row_mask:0xf bank_mask:0xc
	v_mov_b32_dpp v37, v161 row_ror:8 row_mask:0xf bank_mask:0xc
	v_mov_b32_dpp v38, v162 row_ror:8 row_mask:0xf bank_mask:0xc
	v_mov_b32_dpp v39, v163 row_ror:8 row_mask:0xf bank_mask:0xc
	s_waitcnt vmcnt(32)
	v_fma_f32 v36, v36, 0.5, v164
	v_fma_f32 v37, v37, 0.5, v165
	v_fma_f32 v38, v38, 0.5, v166
	v_fma_f32 v39, v39, 0.5, v167
	global_store_dwordx4 v148, v[36:39], s[88:89] offset:512
	v_cvt_pk_bf16_f32 v164, v36, v37
	v_cvt_pk_bf16_f32 v165, v38, v39
	global_store_dwordx2 v158, v[164:165], s[92:93] offset:256
	v_fmac_f32_e32 v205, v36, v36
	v_fmac_f32_e32 v205, v37, v37
	v_fmac_f32_e32 v205, v38, v38
	v_fmac_f32_e32 v205, v39, v39
	s_waitcnt vmcnt(30)
	v_fma_f32 v32, v32, 0.5, v168
	v_fma_f32 v33, v33, 0.5, v169
	v_fma_f32 v34, v34, 0.5, v170
	v_fma_f32 v35, v35, 0.5, v171
	global_store_dwordx4 v149, v[32:35], s[88:89] offset:512
	v_cvt_pk_bf16_f32 v168, v32, v33
	v_cvt_pk_bf16_f32 v169, v34, v35
	global_store_dwordx2 v159, v[168:169], s[92:93] offset:256
	v_fmac_f32_e32 v210, v32, v32
	v_fmac_f32_e32 v210, v33, v33
	v_fmac_f32_e32 v210, v34, v34
	v_fmac_f32_e32 v210, v35, v35
	s_nop 1
	v_add_f32_dpp v205, v205, v205 row_ror:8 row_mask:0xf bank_mask:0xf
	v_add_f32_dpp v210, v210, v210 row_ror:8 row_mask:0xf bank_mask:0xf
	s_nop 0
	ds_bpermute_b32 v147, v144, v205
	ds_bpermute_b32 v132, v144, v210
	s_waitcnt lgkmcnt(0)
	v_add_f32_e32 v205, v205, v147
	v_add_f32_e32 v210, v210, v132
	s_nop 0
	ds_bpermute_b32 v147, v145, v205
	ds_bpermute_b32 v132, v145, v210
	s_waitcnt lgkmcnt(0)
	v_add_f32_e32 v205, v205, v147
	v_add_f32_e32 v210, v210, v132
	v_cmp_gt_u32_e32 vcc, 8, v211
	s_nop 1
	v_cndmask_b32_e32 v205, v210, v205, vcc
	v_cmp_eq_u32_e32 vcc, 0, v146
	s_and_saveexec_b64 s[98:99], vcc
	global_store_dword v204, v205, s[100:101]
	s_mov_b64 exec, s[98:99]
	s_add_u32 s88, s88, 0x10000
	s_addc_u32 s89, s89, 0
	s_add_u32 s92, s92, 0x8000
	s_addc_u32 s93, s93, 0
	s_add_u32 s100, s100, 0x400
	s_addc_u32 s101, s101, 0
	v_mov_b32_e32 v160, v24
	v_mov_b32_e32 v161, v25
	v_mov_b32_e32 v162, v26
	v_mov_b32_e32 v163, v27
	v_mov_b32_dpp v24, v28 row_ror:8 row_mask:0xf bank_mask:0x3
	v_mov_b32_dpp v25, v29 row_ror:8 row_mask:0xf bank_mask:0x3
	v_mov_b32_dpp v26, v30 row_ror:8 row_mask:0xf bank_mask:0x3
	v_mov_b32_dpp v27, v31 row_ror:8 row_mask:0xf bank_mask:0x3
	v_mov_b32_dpp v28, v160 row_ror:8 row_mask:0xf bank_mask:0xc
	v_mov_b32_dpp v29, v161 row_ror:8 row_mask:0xf bank_mask:0xc
	v_mov_b32_dpp v30, v162 row_ror:8 row_mask:0xf bank_mask:0xc
	v_mov_b32_dpp v31, v163 row_ror:8 row_mask:0xf bank_mask:0xc
	s_waitcnt vmcnt(30)
	v_fma_f32 v28, v28, 0.5, v172
	v_fma_f32 v29, v29, 0.5, v173
	v_fma_f32 v30, v30, 0.5, v174
	v_fma_f32 v31, v31, 0.5, v175
	global_store_dwordx4 v148, v[28:31], s[88:89]
	v_cvt_pk_bf16_f32 v172, v28, v29
	v_cvt_pk_bf16_f32 v173, v30, v31
	global_store_dwordx2 v158, v[172:173], s[92:93]
	v_mul_f32_e32 v205, v28, v28
	v_fmac_f32_e32 v205, v29, v29
	v_fmac_f32_e32 v205, v30, v30
	v_fmac_f32_e32 v205, v31, v31
	s_waitcnt vmcnt(29)
	v_fma_f32 v24, v24, 0.5, v176
	v_fma_f32 v25, v25, 0.5, v177
	v_fma_f32 v26, v26, 0.5, v178
	v_fma_f32 v27, v27, 0.5, v179
	global_store_dwordx4 v149, v[24:27], s[88:89]
	v_cvt_pk_bf16_f32 v176, v24, v25
	v_cvt_pk_bf16_f32 v177, v26, v27
	global_store_dwordx2 v159, v[176:177], s[92:93]
	v_mul_f32_e32 v210, v24, v24
	v_fmac_f32_e32 v210, v25, v25
	v_fmac_f32_e32 v210, v26, v26
	v_fmac_f32_e32 v210, v27, v27
	v_mov_b32_e32 v160, v16
	v_mov_b32_e32 v161, v17
	v_mov_b32_e32 v162, v18
	v_mov_b32_e32 v163, v19
	v_mov_b32_dpp v16, v20 row_ror:8 row_mask:0xf bank_mask:0x3
	v_mov_b32_dpp v17, v21 row_ror:8 row_mask:0xf bank_mask:0x3
	v_mov_b32_dpp v18, v22 row_ror:8 row_mask:0xf bank_mask:0x3
	v_mov_b32_dpp v19, v23 row_ror:8 row_mask:0xf bank_mask:0x3
	v_mov_b32_dpp v20, v160 row_ror:8 row_mask:0xf bank_mask:0xc
	v_mov_b32_dpp v21, v161 row_ror:8 row_mask:0xf bank_mask:0xc
	v_mov_b32_dpp v22, v162 row_ror:8 row_mask:0xf bank_mask:0xc
	v_mov_b32_dpp v23, v163 row_ror:8 row_mask:0xf bank_mask:0xc
	s_waitcnt vmcnt(28)
	v_fma_f32 v20, v20, 0.5, v180
	v_fma_f32 v21, v21, 0.5, v181
	v_fma_f32 v22, v22, 0.5, v182
	v_fma_f32 v23, v23, 0.5, v183
	global_store_dwordx4 v148, v[20:23], s[88:89] offset:512
	v_cvt_pk_bf16_f32 v180, v20, v21
	v_cvt_pk_bf16_f32 v181, v22, v23
	global_store_dwordx2 v158, v[180:181], s[92:93] offset:256
	v_fmac_f32_e32 v205, v20, v20
	v_fmac_f32_e32 v205, v21, v21
	v_fmac_f32_e32 v205, v22, v22
	v_fmac_f32_e32 v205, v23, v23
	s_waitcnt vmcnt(26)
	v_fma_f32 v16, v16, 0.5, v184
	v_fma_f32 v17, v17, 0.5, v185
	v_fma_f32 v18, v18, 0.5, v186
	v_fma_f32 v19, v19, 0.5, v187
	global_store_dwordx4 v149, v[16:19], s[88:89] offset:512
	v_cvt_pk_bf16_f32 v184, v16, v17
	v_cvt_pk_bf16_f32 v185, v18, v19
	global_store_dwordx2 v159, v[184:185], s[92:93] offset:256
	v_fmac_f32_e32 v210, v16, v16
	v_fmac_f32_e32 v210, v17, v17
	v_fmac_f32_e32 v210, v18, v18
	v_fmac_f32_e32 v210, v19, v19
	s_nop 1
	v_add_f32_dpp v205, v205, v205 row_ror:8 row_mask:0xf bank_mask:0xf
	v_add_f32_dpp v210, v210, v210 row_ror:8 row_mask:0xf bank_mask:0xf
	s_nop 0
	ds_bpermute_b32 v147, v144, v205
	ds_bpermute_b32 v132, v144, v210
	s_waitcnt lgkmcnt(0)
	v_add_f32_e32 v205, v205, v147
	v_add_f32_e32 v210, v210, v132
	s_nop 0
	ds_bpermute_b32 v147, v145, v205
	ds_bpermute_b32 v132, v145, v210
	s_waitcnt lgkmcnt(0)
	v_add_f32_e32 v205, v205, v147
	v_add_f32_e32 v210, v210, v132
	v_cmp_gt_u32_e32 vcc, 8, v211
	s_nop 1
	v_cndmask_b32_e32 v205, v210, v205, vcc
	v_cmp_eq_u32_e32 vcc, 0, v146
	s_and_saveexec_b64 s[98:99], vcc
	global_store_dword v204, v205, s[100:101]
	s_mov_b64 exec, s[98:99]
	s_add_u32 s88, s88, 0x10000
	s_addc_u32 s89, s89, 0
	s_add_u32 s92, s92, 0x8000
	s_addc_u32 s93, s93, 0
	s_add_u32 s100, s100, 0x400
	s_addc_u32 s101, s101, 0
	v_mov_b32_e32 v160, v8
	v_mov_b32_e32 v161, v9
	v_mov_b32_e32 v162, v10
	v_mov_b32_e32 v163, v11
	v_mov_b32_dpp v8, v12 row_ror:8 row_mask:0xf bank_mask:0x3
	v_mov_b32_dpp v9, v13 row_ror:8 row_mask:0xf bank_mask:0x3
	v_mov_b32_dpp v10, v14 row_ror:8 row_mask:0xf bank_mask:0x3
	v_mov_b32_dpp v11, v15 row_ror:8 row_mask:0xf bank_mask:0x3
	v_mov_b32_dpp v12, v160 row_ror:8 row_mask:0xf bank_mask:0xc
	v_mov_b32_dpp v13, v161 row_ror:8 row_mask:0xf bank_mask:0xc
	v_mov_b32_dpp v14, v162 row_ror:8 row_mask:0xf bank_mask:0xc
	v_mov_b32_dpp v15, v163 row_ror:8 row_mask:0xf bank_mask:0xc
	s_waitcnt vmcnt(26)
	v_fma_f32 v12, v12, 0.5, v188
	v_fma_f32 v13, v13, 0.5, v189
	v_fma_f32 v14, v14, 0.5, v190
	v_fma_f32 v15, v15, 0.5, v191
	global_store_dwordx4 v148, v[12:15], s[88:89]
	v_cvt_pk_bf16_f32 v188, v12, v13
	v_cvt_pk_bf16_f32 v189, v14, v15
	global_store_dwordx2 v158, v[188:189], s[92:93]
	v_mul_f32_e32 v205, v12, v12
	v_fmac_f32_e32 v205, v13, v13
	v_fmac_f32_e32 v205, v14, v14
	v_fmac_f32_e32 v205, v15, v15
	s_waitcnt vmcnt(25)
	v_fma_f32 v8, v8, 0.5, v192
	v_fma_f32 v9, v9, 0.5, v193
	v_fma_f32 v10, v10, 0.5, v194
	v_fma_f32 v11, v11, 0.5, v195
	global_store_dwordx4 v149, v[8:11], s[88:89]
	v_cvt_pk_bf16_f32 v192, v8, v9
	v_cvt_pk_bf16_f32 v193, v10, v11
	global_store_dwordx2 v159, v[192:193], s[92:93]
	v_mul_f32_e32 v210, v8, v8
	v_fmac_f32_e32 v210, v9, v9
	v_fmac_f32_e32 v210, v10, v10
	v_fmac_f32_e32 v210, v11, v11
	v_mov_b32_e32 v160, v0
	v_mov_b32_e32 v161, v1
	v_mov_b32_e32 v162, v2
	v_mov_b32_e32 v163, v3
	v_mov_b32_dpp v0, v4 row_ror:8 row_mask:0xf bank_mask:0x3
	v_mov_b32_dpp v1, v5 row_ror:8 row_mask:0xf bank_mask:0x3
	v_mov_b32_dpp v2, v6 row_ror:8 row_mask:0xf bank_mask:0x3
	v_mov_b32_dpp v3, v7 row_ror:8 row_mask:0xf bank_mask:0x3
	v_mov_b32_dpp v4, v160 row_ror:8 row_mask:0xf bank_mask:0xc
	v_mov_b32_dpp v5, v161 row_ror:8 row_mask:0xf bank_mask:0xc
	v_mov_b32_dpp v6, v162 row_ror:8 row_mask:0xf bank_mask:0xc
	v_mov_b32_dpp v7, v163 row_ror:8 row_mask:0xf bank_mask:0xc
	s_waitcnt vmcnt(24)
	v_fma_f32 v4, v4, 0.5, v196
	v_fma_f32 v5, v5, 0.5, v197
	v_fma_f32 v6, v6, 0.5, v198
	v_fma_f32 v7, v7, 0.5, v199
	global_store_dwordx4 v148, v[4:7], s[88:89] offset:512
	v_cvt_pk_bf16_f32 v196, v4, v5
	v_cvt_pk_bf16_f32 v197, v6, v7
	global_store_dwordx2 v158, v[196:197], s[92:93] offset:256
	v_fmac_f32_e32 v205, v4, v4
	v_fmac_f32_e32 v205, v5, v5
	v_fmac_f32_e32 v205, v6, v6
	v_fmac_f32_e32 v205, v7, v7
	s_waitcnt vmcnt(22)
	v_fma_f32 v0, v0, 0.5, v200
	v_fma_f32 v1, v1, 0.5, v201
	v_fma_f32 v2, v2, 0.5, v202
	v_fma_f32 v3, v3, 0.5, v203
	global_store_dwordx4 v149, v[0:3], s[88:89] offset:512
	v_cvt_pk_bf16_f32 v200, v0, v1
	v_cvt_pk_bf16_f32 v201, v2, v3
	global_store_dwordx2 v159, v[200:201], s[92:93] offset:256
	v_fmac_f32_e32 v210, v0, v0
	v_fmac_f32_e32 v210, v1, v1
	v_fmac_f32_e32 v210, v2, v2
	v_fmac_f32_e32 v210, v3, v3
	s_nop 1
	v_add_f32_dpp v205, v205, v205 row_ror:8 row_mask:0xf bank_mask:0xf
	v_add_f32_dpp v210, v210, v210 row_ror:8 row_mask:0xf bank_mask:0xf
	s_nop 0
	ds_bpermute_b32 v147, v144, v205
	ds_bpermute_b32 v132, v144, v210
	s_waitcnt lgkmcnt(0)
	v_add_f32_e32 v205, v205, v147
	v_add_f32_e32 v210, v210, v132
	s_nop 0
	ds_bpermute_b32 v147, v145, v205
	ds_bpermute_b32 v132, v145, v210
	s_waitcnt lgkmcnt(0)
	v_add_f32_e32 v205, v205, v147
	v_add_f32_e32 v210, v210, v132
	v_cmp_gt_u32_e32 vcc, 8, v211
	s_nop 1
	v_cndmask_b32_e32 v205, v210, v205, vcc
	v_cmp_eq_u32_e32 vcc, 0, v146
	s_and_saveexec_b64 s[98:99], vcc
	global_store_dword v204, v205, s[100:101]
	s_mov_b64 exec, s[98:99]
	s_and_b64 vcc, exec, s[10:11]
	s_mov_b64 s[10:11], -1
	s_cbranch_vccnz .LBB0_259
	s_andn2_b64 vcc, exec, s[26:27]
	s_cbranch_vccnz .LBB0_258
	s_barrier
	s_branch .LBB0_258

.LBB0_1010:
	v_lshrrev_b32_e32 v136, 6, v206
	v_and_b32_e32 v147, 63, v206
	v_lshrrev_b32_e32 v146, 2, v136
	v_and_b32_e32 v136, 3, v136
	v_lshlrev_b32_e32 v146, 6, v146
	v_lshrrev_b32_e32 v150, 4, v147
	v_and_b32_e32 v217, 15, v147
	v_xor_b32_e32 v148, 16, v147
	v_xor_b32_e32 v149, 32, v147
	v_lshlrev_b32_e32 v148, 2, v148
	v_lshlrev_b32_e32 v149, 2, v149
	s_lshl_b32 vcc_lo, s24, 8
	v_add_u32_e32 v146, vcc_lo, v146
	s_lshl_b32 vcc_lo, s20, 2
	v_add_u32_e32 v220, vcc_lo, v136
	v_add_u32_e32 v151, v146, v217
	v_lshlrev_b32_e32 v151, 6, v151
	v_lshl_add_u32 v220, v220, 2, v151
	v_lshlrev_b32_e32 v147, 5, v136
	v_lshrrev_b32_e32 v151, 3, v217
	v_lshl_add_u32 v151, v151, 2, v150
	v_lshl_add_u32 v147, v151, 2, v147
	s_lshl_b32 vcc_lo, s20, 8
	v_add_u32_e32 v147, vcc_lo, v147
	v_and_b32_e32 v151, 7, v217
	v_add_u32_e32 v146, v146, v151
	v_lshlrev_b32_e32 v152, 12, v146
	v_lshl_add_u32 v152, v147, 2, v152
	v_add_u32_e32 v153, 0x8000, v152
	v_lshlrev_b32_e32 v210, 11, v146
	v_lshl_add_u32 v210, v147, 1, v210
	v_add_u32_e32 v211, 0x4000, v210
	s_mov_b32 s86, s94
	s_mov_b32 s87, s95
	s_mov_b32 s88, s94
	s_mov_b32 s89, s95
	s_add_u32 s92, s96, 0x9e00000
	s_addc_u32 s93, s97, 0
	s_add_u32 s100, s96, 0x4b00000
	s_addc_u32 s101, s97, 0
	global_load_dwordx4 v[164:167], v152, s[86:87]
	global_load_dwordx4 v[168:171], v153, s[86:87]
	global_load_dwordx4 v[172:175], v152, s[86:87] offset:512
	global_load_dwordx4 v[176:179], v153, s[86:87] offset:512
	s_add_u32 s86, s86, 0x10000
	s_addc_u32 s87, s87, 0
	global_load_dwordx4 v[180:183], v152, s[86:87]
	global_load_dwordx4 v[184:187], v153, s[86:87]
	global_load_dwordx4 v[188:191], v152, s[86:87] offset:512
	global_load_dwordx4 v[192:195], v153, s[86:87] offset:512
	s_add_u32 s86, s86, 0x10000
	s_addc_u32 s87, s87, 0
	global_load_dwordx4 v[196:199], v152, s[86:87]
	global_load_dwordx4 v[200:203], v153, s[86:87]
	global_load_dwordx4 v[212:215], v152, s[86:87] offset:512
	v_mov_b32_e32 v160, v120
	v_mov_b32_e32 v161, v121
	v_mov_b32_e32 v162, v122
	v_mov_b32_e32 v163, v123
	v_mov_b32_dpp v120, v124 row_ror:8 row_mask:0xf bank_mask:0x3
	v_mov_b32_dpp v121, v125 row_ror:8 row_mask:0xf bank_mask:0x3
	v_mov_b32_dpp v122, v126 row_ror:8 row_mask:0xf bank_mask:0x3
	v_mov_b32_dpp v123, v127 row_ror:8 row_mask:0xf bank_mask:0x3
	v_mov_b32_dpp v124, v160 row_ror:8 row_mask:0xf bank_mask:0xc
	v_mov_b32_dpp v125, v161 row_ror:8 row_mask:0xf bank_mask:0xc
	v_mov_b32_dpp v126, v162 row_ror:8 row_mask:0xf bank_mask:0xc
	v_mov_b32_dpp v127, v163 row_ror:8 row_mask:0xf bank_mask:0xc
	s_waitcnt vmcnt(10)
	v_add_f32_e32 v124, v124, v164
	v_add_f32_e32 v125, v125, v165
	v_add_f32_e32 v126, v126, v166
	v_add_f32_e32 v127, v127, v167
	global_store_dwordx4 v152, v[124:127], s[88:89]
	v_cvt_pk_bf16_f32 v164, v124, v125
	v_cvt_pk_bf16_f32 v165, v126, v127
	global_store_dwordx2 v210, v[164:165], s[92:93]
	v_mul_f32_e32 v221, v124, v124
	v_fmac_f32_e32 v221, v125, v125
	v_fmac_f32_e32 v221, v126, v126
	v_fmac_f32_e32 v221, v127, v127
	global_load_dwordx4 v[164:167], v153, s[86:87] offset:512
	s_waitcnt vmcnt(12)
	v_add_f32_e32 v120, v120, v168
	v_add_f32_e32 v121, v121, v169
	v_add_f32_e32 v122, v122, v170
	v_add_f32_e32 v123, v123, v171
	global_store_dwordx4 v153, v[120:123], s[88:89]
	v_cvt_pk_bf16_f32 v168, v120, v121
	v_cvt_pk_bf16_f32 v169, v122, v123
	global_store_dwordx2 v211, v[168:169], s[92:93]
	v_mul_f32_e32 v216, v120, v120
	v_fmac_f32_e32 v216, v121, v121
	v_fmac_f32_e32 v216, v122, v122
	v_fmac_f32_e32 v216, v123, v123
	s_add_u32 s86, s86, 0x10000
	s_addc_u32 s87, s87, 0
	global_load_dwordx4 v[168:171], v152, s[86:87]
	v_mov_b32_e32 v160, v112
	v_mov_b32_e32 v161, v113
	v_mov_b32_e32 v162, v114
	v_mov_b32_e32 v163, v115
	v_mov_b32_dpp v112, v116 row_ror:8 row_mask:0xf bank_mask:0x3
	v_mov_b32_dpp v113, v117 row_ror:8 row_mask:0xf bank_mask:0x3
	v_mov_b32_dpp v114, v118 row_ror:8 row_mask:0xf bank_mask:0x3
	v_mov_b32_dpp v115, v119 row_ror:8 row_mask:0xf bank_mask:0x3
	v_mov_b32_dpp v116, v160 row_ror:8 row_mask:0xf bank_mask:0xc
	v_mov_b32_dpp v117, v161 row_ror:8 row_mask:0xf bank_mask:0xc
	v_mov_b32_dpp v118, v162 row_ror:8 row_mask:0xf bank_mask:0xc
	v_mov_b32_dpp v119, v163 row_ror:8 row_mask:0xf bank_mask:0xc
	s_waitcnt vmcnt(14)
	v_add_f32_e32 v116, v116, v172
	v_add_f32_e32 v117, v117, v173
	v_add_f32_e32 v118, v118, v174
	v_add_f32_e32 v119, v119, v175
	global_store_dwordx4 v152, v[116:119], s[88:89] offset:512
	v_cvt_pk_bf16_f32 v172, v116, v117
	v_cvt_pk_bf16_f32 v173, v118, v119
	global_store_dwordx2 v210, v[172:173], s[92:93] offset:256
	v_fmac_f32_e32 v221, v116, v116
	v_fmac_f32_e32 v221, v117, v117
	v_fmac_f32_e32 v221, v118, v118
	v_fmac_f32_e32 v221, v119, v119
	global_load_dwordx4 v[172:175], v153, s[86:87]
	s_waitcnt vmcnt(16)
	v_add_f32_e32 v112, v112, v176
	v_add_f32_e32 v113, v113, v177
	v_add_f32_e32 v114, v114, v178
	v_add_f32_e32 v115, v115, v179
	global_store_dwordx4 v153, v[112:115], s[88:89] offset:512
	v_cvt_pk_bf16_f32 v176, v112, v113
	v_cvt_pk_bf16_f32 v177, v114, v115
	global_store_dwordx2 v211, v[176:177], s[92:93] offset:256
	v_fmac_f32_e32 v216, v112, v112
	v_fmac_f32_e32 v216, v113, v113
	v_fmac_f32_e32 v216, v114, v114
	v_fmac_f32_e32 v216, v115, v115
	global_load_dwordx4 v[176:179], v152, s[86:87] offset:512
	s_nop 1
	v_add_f32_dpp v221, v221, v221 row_ror:8 row_mask:0xf bank_mask:0xf
	v_add_f32_dpp v216, v216, v216 row_ror:8 row_mask:0xf bank_mask:0xf
	s_nop 0
	ds_bpermute_b32 v151, v148, v221
	ds_bpermute_b32 v136, v148, v216
	s_waitcnt lgkmcnt(0)
	v_add_f32_e32 v221, v221, v151
	v_add_f32_e32 v216, v216, v136
	s_nop 0
	ds_bpermute_b32 v151, v149, v221
	ds_bpermute_b32 v136, v149, v216
	s_waitcnt lgkmcnt(0)
	v_add_f32_e32 v221, v221, v151
	v_add_f32_e32 v216, v216, v136
	v_cmp_gt_u32_e32 vcc, 8, v217
	s_nop 1
	v_cndmask_b32_e32 v221, v216, v221, vcc
	v_cmp_eq_u32_e32 vcc, 0, v150
	s_and_saveexec_b64 s[98:99], vcc
	global_store_dword v220, v221, s[100:101]
	s_mov_b64 exec, s[98:99]
	s_add_u32 s88, s88, 0x10000
	s_addc_u32 s89, s89, 0
	s_add_u32 s92, s92, 0x8000
	s_addc_u32 s93, s93, 0
	s_add_u32 s100, s100, 0x400
	s_addc_u32 s101, s101, 0
	v_mov_b32_e32 v160, v104
	v_mov_b32_e32 v161, v105
	v_mov_b32_e32 v162, v106
	v_mov_b32_e32 v163, v107
	v_mov_b32_dpp v104, v108 row_ror:8 row_mask:0xf bank_mask:0x3
	v_mov_b32_dpp v105, v109 row_ror:8 row_mask:0xf bank_mask:0x3
	v_mov_b32_dpp v106, v110 row_ror:8 row_mask:0xf bank_mask:0x3
	v_mov_b32_dpp v107, v111 row_ror:8 row_mask:0xf bank_mask:0x3
	v_mov_b32_dpp v108, v160 row_ror:8 row_mask:0xf bank_mask:0xc
	v_mov_b32_dpp v109, v161 row_ror:8 row_mask:0xf bank_mask:0xc
	v_mov_b32_dpp v110, v162 row_ror:8 row_mask:0xf bank_mask:0xc
	v_mov_b32_dpp v111, v163 row_ror:8 row_mask:0xf bank_mask:0xc
	s_waitcnt vmcnt(19)
	v_add_f32_e32 v108, v108, v180
	v_add_f32_e32 v109, v109, v181
	v_add_f32_e32 v110, v110, v182
	v_add_f32_e32 v111, v111, v183
	global_store_dwordx4 v152, v[108:111], s[88:89]
	v_cvt_pk_bf16_f32 v180, v108, v109
	v_cvt_pk_bf16_f32 v181, v110, v111
	global_store_dwordx2 v210, v[180:181], s[92:93]
	v_mul_f32_e32 v221, v108, v108
	v_fmac_f32_e32 v221, v109, v109
	v_fmac_f32_e32 v221, v110, v110
	v_fmac_f32_e32 v221, v111, v111
	global_load_dwordx4 v[180:183], v153, s[86:87] offset:512
	s_waitcnt vmcnt(21)
	v_add_f32_e32 v104, v104, v184
	v_add_f32_e32 v105, v105, v185
	v_add_f32_e32 v106, v106, v186
	v_add_f32_e32 v107, v107, v187
	global_store_dwordx4 v153, v[104:107], s[88:89]
	v_cvt_pk_bf16_f32 v184, v104, v105
	v_cvt_pk_bf16_f32 v185, v106, v107
	global_store_dwordx2 v211, v[184:185], s[92:93]
	v_mul_f32_e32 v216, v104, v104
	v_fmac_f32_e32 v216, v105, v105
	v_fmac_f32_e32 v216, v106, v106
	v_fmac_f32_e32 v216, v107, v107
	s_add_u32 s86, s86, 0x50000
	s_addc_u32 s87, s87, 0
	global_load_dwordx4 v[184:187], v152, s[86:87]
	v_mov_b32_e32 v160, v96
	v_mov_b32_e32 v161, v97
	v_mov_b32_e32 v162, v98
	v_mov_b32_e32 v163, v99
	v_mov_b32_dpp v96, v100 row_ror:8 row_mask:0xf bank_mask:0x3
	v_mov_b32_dpp v97, v101 row_ror:8 row_mask:0xf bank_mask:0x3
	v_mov_b32_dpp v98, v102 row_ror:8 row_mask:0xf bank_mask:0x3
	v_mov_b32_dpp v99, v103 row_ror:8 row_mask:0xf bank_mask:0x3
	v_mov_b32_dpp v100, v160 row_ror:8 row_mask:0xf bank_mask:0xc
	v_mov_b32_dpp v101, v161 row_ror:8 row_mask:0xf bank_mask:0xc
	v_mov_b32_dpp v102, v162 row_ror:8 row_mask:0xf bank_mask:0xc
	v_mov_b32_dpp v103, v163 row_ror:8 row_mask:0xf bank_mask:0xc
	s_waitcnt vmcnt(23)
	v_add_f32_e32 v100, v100, v188
	v_add_f32_e32 v101, v101, v189
	v_add_f32_e32 v102, v102, v190
	v_add_f32_e32 v103, v103, v191
	global_store_dwordx4 v152, v[100:103], s[88:89] offset:512
	v_cvt_pk_bf16_f32 v188, v100, v101
	v_cvt_pk_bf16_f32 v189, v102, v103
	global_store_dwordx2 v210, v[188:189], s[92:93] offset:256
	v_fmac_f32_e32 v221, v100, v100
	v_fmac_f32_e32 v221, v101, v101
	v_fmac_f32_e32 v221, v102, v102
	v_fmac_f32_e32 v221, v103, v103
	global_load_dwordx4 v[188:191], v153, s[86:87]
	s_waitcnt vmcnt(25)
	v_add_f32_e32 v96, v96, v192
	v_add_f32_e32 v97, v97, v193
	v_add_f32_e32 v98, v98, v194
	v_add_f32_e32 v99, v99, v195
	global_store_dwordx4 v153, v[96:99], s[88:89] offset:512
	v_cvt_pk_bf16_f32 v192, v96, v97
	v_cvt_pk_bf16_f32 v193, v98, v99
	global_store_dwordx2 v211, v[192:193], s[92:93] offset:256
	v_fmac_f32_e32 v216, v96, v96
	v_fmac_f32_e32 v216, v97, v97
	v_fmac_f32_e32 v216, v98, v98
	v_fmac_f32_e32 v216, v99, v99
	global_load_dwordx4 v[192:195], v152, s[86:87] offset:512
	s_nop 1
	v_add_f32_dpp v221, v221, v221 row_ror:8 row_mask:0xf bank_mask:0xf
	v_add_f32_dpp v216, v216, v216 row_ror:8 row_mask:0xf bank_mask:0xf
	s_nop 0
	ds_bpermute_b32 v151, v148, v221
	ds_bpermute_b32 v136, v148, v216
	s_waitcnt lgkmcnt(0)
	v_add_f32_e32 v221, v221, v151
	v_add_f32_e32 v216, v216, v136
	s_nop 0
	ds_bpermute_b32 v151, v149, v221
	ds_bpermute_b32 v136, v149, v216
	s_waitcnt lgkmcnt(0)
	v_add_f32_e32 v221, v221, v151
	v_add_f32_e32 v216, v216, v136
	v_cmp_gt_u32_e32 vcc, 8, v217
	s_nop 1
	v_cndmask_b32_e32 v221, v216, v221, vcc
	v_cmp_eq_u32_e32 vcc, 0, v150
	s_and_saveexec_b64 s[98:99], vcc
	global_store_dword v220, v221, s[100:101]
	s_mov_b64 exec, s[98:99]
	s_add_u32 s88, s88, 0x10000
	s_addc_u32 s89, s89, 0
	s_add_u32 s92, s92, 0x8000
	s_addc_u32 s93, s93, 0
	s_add_u32 s100, s100, 0x400
	s_addc_u32 s101, s101, 0
	v_mov_b32_e32 v160, v88
	v_mov_b32_e32 v161, v89
	v_mov_b32_e32 v162, v90
	v_mov_b32_e32 v163, v91
	v_mov_b32_dpp v88, v92 row_ror:8 row_mask:0xf bank_mask:0x3
	v_mov_b32_dpp v89, v93 row_ror:8 row_mask:0xf bank_mask:0x3
	v_mov_b32_dpp v90, v94 row_ror:8 row_mask:0xf bank_mask:0x3
	v_mov_b32_dpp v91, v95 row_ror:8 row_mask:0xf bank_mask:0x3
	v_mov_b32_dpp v92, v160 row_ror:8 row_mask:0xf bank_mask:0xc
	v_mov_b32_dpp v93, v161 row_ror:8 row_mask:0xf bank_mask:0xc
	v_mov_b32_dpp v94, v162 row_ror:8 row_mask:0xf bank_mask:0xc
	v_mov_b32_dpp v95, v163 row_ror:8 row_mask:0xf bank_mask:0xc
	s_waitcnt vmcnt(28)
	v_add_f32_e32 v92, v92, v196
	v_add_f32_e32 v93, v93, v197
	v_add_f32_e32 v94, v94, v198
	v_add_f32_e32 v95, v95, v199
	global_store_dwordx4 v152, v[92:95], s[88:89]
	v_cvt_pk_bf16_f32 v196, v92, v93
	v_cvt_pk_bf16_f32 v197, v94, v95
	global_store_dwordx2 v210, v[196:197], s[92:93]
	v_mul_f32_e32 v221, v92, v92
	v_fmac_f32_e32 v221, v93, v93
	v_fmac_f32_e32 v221, v94, v94
	v_fmac_f32_e32 v221, v95, v95
	global_load_dwordx4 v[196:199], v153, s[86:87] offset:512
	s_waitcnt vmcnt(30)
	v_add_f32_e32 v88, v88, v200
	v_add_f32_e32 v89, v89, v201
	v_add_f32_e32 v90, v90, v202
	v_add_f32_e32 v91, v91, v203
	global_store_dwordx4 v153, v[88:91], s[88:89]
	v_cvt_pk_bf16_f32 v200, v88, v89
	v_cvt_pk_bf16_f32 v201, v90, v91
	global_store_dwordx2 v211, v[200:201], s[92:93]
	v_mul_f32_e32 v216, v88, v88
	v_fmac_f32_e32 v216, v89, v89
	v_fmac_f32_e32 v216, v90, v90
	v_fmac_f32_e32 v216, v91, v91
	s_add_u32 s86, s86, 0x10000
	s_addc_u32 s87, s87, 0
	global_load_dwordx4 v[200:203], v152, s[86:87]
	v_mov_b32_e32 v160, v80
	v_mov_b32_e32 v161, v81
	v_mov_b32_e32 v162, v82
	v_mov_b32_e32 v163, v83
	v_mov_b32_dpp v80, v84 row_ror:8 row_mask:0xf bank_mask:0x3
	v_mov_b32_dpp v81, v85 row_ror:8 row_mask:0xf bank_mask:0x3
	v_mov_b32_dpp v82, v86 row_ror:8 row_mask:0xf bank_mask:0x3
	v_mov_b32_dpp v83, v87 row_ror:8 row_mask:0xf bank_mask:0x3
	v_mov_b32_dpp v84, v160 row_ror:8 row_mask:0xf bank_mask:0xc
	v_mov_b32_dpp v85, v161 row_ror:8 row_mask:0xf bank_mask:0xc
	v_mov_b32_dpp v86, v162 row_ror:8 row_mask:0xf bank_mask:0xc
	v_mov_b32_dpp v87, v163 row_ror:8 row_mask:0xf bank_mask:0xc
	s_waitcnt vmcnt(32)
	v_add_f32_e32 v84, v84, v212
	v_add_f32_e32 v85, v85, v213
	v_add_f32_e32 v86, v86, v214
	v_add_f32_e32 v87, v87, v215
	global_store_dwordx4 v152, v[84:87], s[88:89] offset:512
	v_cvt_pk_bf16_f32 v212, v84, v85
	v_cvt_pk_bf16_f32 v213, v86, v87
	global_store_dwordx2 v210, v[212:213], s[92:93] offset:256
	v_fmac_f32_e32 v221, v84, v84
	v_fmac_f32_e32 v221, v85, v85
	v_fmac_f32_e32 v221, v86, v86
	v_fmac_f32_e32 v221, v87, v87
	global_load_dwordx4 v[212:215], v153, s[86:87]
	s_waitcnt vmcnt(32)
	v_add_f32_e32 v80, v80, v164
	v_add_f32_e32 v81, v81, v165
	v_add_f32_e32 v82, v82, v166
	v_add_f32_e32 v83, v83, v167
	global_store_dwordx4 v153, v[80:83], s[88:89] offset:512
	v_cvt_pk_bf16_f32 v164, v80, v81
	v_cvt_pk_bf16_f32 v165, v82, v83
	global_store_dwordx2 v211, v[164:165], s[92:93] offset:256
	v_fmac_f32_e32 v216, v80, v80
	v_fmac_f32_e32 v216, v81, v81
	v_fmac_f32_e32 v216, v82, v82
	v_fmac_f32_e32 v216, v83, v83
	global_load_dwordx4 v[164:167], v152, s[86:87] offset:512
	s_nop 1
	v_add_f32_dpp v221, v221, v221 row_ror:8 row_mask:0xf bank_mask:0xf
	v_add_f32_dpp v216, v216, v216 row_ror:8 row_mask:0xf bank_mask:0xf
	s_nop 0
	ds_bpermute_b32 v151, v148, v221
	ds_bpermute_b32 v136, v148, v216
	s_waitcnt lgkmcnt(0)
	v_add_f32_e32 v221, v221, v151
	v_add_f32_e32 v216, v216, v136
	s_nop 0
	ds_bpermute_b32 v151, v149, v221
	ds_bpermute_b32 v136, v149, v216
	s_waitcnt lgkmcnt(0)
	v_add_f32_e32 v221, v221, v151
	v_add_f32_e32 v216, v216, v136
	v_cmp_gt_u32_e32 vcc, 8, v217
	s_nop 1
	v_cndmask_b32_e32 v221, v216, v221, vcc
	v_cmp_eq_u32_e32 vcc, 0, v150
	s_and_saveexec_b64 s[98:99], vcc
	global_store_dword v220, v221, s[100:101]
	s_mov_b64 exec, s[98:99]
	s_add_u32 s88, s88, 0x10000
	s_addc_u32 s89, s89, 0
	s_add_u32 s92, s92, 0x8000
	s_addc_u32 s93, s93, 0
	s_add_u32 s100, s100, 0x400
	s_addc_u32 s101, s101, 0
	v_mov_b32_e32 v160, v72
	v_mov_b32_e32 v161, v73
	v_mov_b32_e32 v162, v74
	v_mov_b32_e32 v163, v75
	v_mov_b32_dpp v72, v76 row_ror:8 row_mask:0xf bank_mask:0x3
	v_mov_b32_dpp v73, v77 row_ror:8 row_mask:0xf bank_mask:0x3
	v_mov_b32_dpp v74, v78 row_ror:8 row_mask:0xf bank_mask:0x3
	v_mov_b32_dpp v75, v79 row_ror:8 row_mask:0xf bank_mask:0x3
	v_mov_b32_dpp v76, v160 row_ror:8 row_mask:0xf bank_mask:0xc
	v_mov_b32_dpp v77, v161 row_ror:8 row_mask:0xf bank_mask:0xc
	v_mov_b32_dpp v78, v162 row_ror:8 row_mask:0xf bank_mask:0xc
	v_mov_b32_dpp v79, v163 row_ror:8 row_mask:0xf bank_mask:0xc
	s_waitcnt vmcnt(33)
	v_add_f32_e32 v76, v76, v168
	v_add_f32_e32 v77, v77, v169
	v_add_f32_e32 v78, v78, v170
	v_add_f32_e32 v79, v79, v171
	global_store_dwordx4 v152, v[76:79], s[88:89]
	v_cvt_pk_bf16_f32 v168, v76, v77
	v_cvt_pk_bf16_f32 v169, v78, v79
	global_store_dwordx2 v210, v[168:169], s[92:93]
	v_mul_f32_e32 v221, v76, v76
	v_fmac_f32_e32 v221, v77, v77
	v_fmac_f32_e32 v221, v78, v78
	v_fmac_f32_e32 v221, v79, v79
	global_load_dwordx4 v[168:171], v153, s[86:87] offset:512
	s_waitcnt vmcnt(33)
	v_add_f32_e32 v72, v72, v172
	v_add_f32_e32 v73, v73, v173
	v_add_f32_e32 v74, v74, v174
	v_add_f32_e32 v75, v75, v175
	global_store_dwordx4 v153, v[72:75], s[88:89]
	v_cvt_pk_bf16_f32 v172, v72, v73
	v_cvt_pk_bf16_f32 v173, v74, v75
	global_store_dwordx2 v211, v[172:173], s[92:93]
	v_mul_f32_e32 v216, v72, v72
	v_fmac_f32_e32 v216, v73, v73
	v_fmac_f32_e32 v216, v74, v74
	v_fmac_f32_e32 v216, v75, v75
	s_add_u32 s86, s86, 0x10000
	s_addc_u32 s87, s87, 0
	global_load_dwordx4 v[172:175], v152, s[86:87]
	v_mov_b32_e32 v160, v64
	v_mov_b32_e32 v161, v65
	v_mov_b32_e32 v162, v66
	v_mov_b32_e32 v163, v67
	v_mov_b32_dpp v64, v68 row_ror:8 row_mask:0xf bank_mask:0x3
	v_mov_b32_dpp v65, v69 row_ror:8 row_mask:0xf bank_mask:0x3
	v_mov_b32_dpp v66, v70 row_ror:8 row_mask:0xf bank_mask:0x3
	v_mov_b32_dpp v67, v71 row_ror:8 row_mask:0xf bank_mask:0x3
	v_mov_b32_dpp v68, v160 row_ror:8 row_mask:0xf bank_mask:0xc
	v_mov_b32_dpp v69, v161 row_ror:8 row_mask:0xf bank_mask:0xc
	v_mov_b32_dpp v70, v162 row_ror:8 row_mask:0xf bank_mask:0xc
	v_mov_b32_dpp v71, v163 row_ror:8 row_mask:0xf bank_mask:0xc
	s_waitcnt vmcnt(33)
	v_add_f32_e32 v68, v68, v176
	v_add_f32_e32 v69, v69, v177
	v_add_f32_e32 v70, v70, v178
	v_add_f32_e32 v71, v71, v179
	global_store_dwordx4 v152, v[68:71], s[88:89] offset:512
	v_cvt_pk_bf16_f32 v176, v68, v69
	v_cvt_pk_bf16_f32 v177, v70, v71
	global_store_dwordx2 v210, v[176:177], s[92:93] offset:256
	v_fmac_f32_e32 v221, v68, v68
	v_fmac_f32_e32 v221, v69, v69
	v_fmac_f32_e32 v221, v70, v70
	v_fmac_f32_e32 v221, v71, v71
	global_load_dwordx4 v[176:179], v153, s[86:87]
	s_waitcnt vmcnt(32)
	v_add_f32_e32 v64, v64, v180
	v_add_f32_e32 v65, v65, v181
	v_add_f32_e32 v66, v66, v182
	v_add_f32_e32 v67, v67, v183
	global_store_dwordx4 v153, v[64:67], s[88:89] offset:512
	v_cvt_pk_bf16_f32 v180, v64, v65
	v_cvt_pk_bf16_f32 v181, v66, v67
	global_store_dwordx2 v211, v[180:181], s[92:93] offset:256
	v_fmac_f32_e32 v216, v64, v64
	v_fmac_f32_e32 v216, v65, v65
	v_fmac_f32_e32 v216, v66, v66
	v_fmac_f32_e32 v216, v67, v67
	global_load_dwordx4 v[180:183], v152, s[86:87] offset:512
	s_nop 1
	v_add_f32_dpp v221, v221, v221 row_ror:8 row_mask:0xf bank_mask:0xf
	v_add_f32_dpp v216, v216, v216 row_ror:8 row_mask:0xf bank_mask:0xf
	s_nop 0
	ds_bpermute_b32 v151, v148, v221
	ds_bpermute_b32 v136, v148, v216
	s_waitcnt lgkmcnt(0)
	v_add_f32_e32 v221, v221, v151
	v_add_f32_e32 v216, v216, v136
	s_nop 0
	ds_bpermute_b32 v151, v149, v221
	ds_bpermute_b32 v136, v149, v216
	s_waitcnt lgkmcnt(0)
	v_add_f32_e32 v221, v221, v151
	v_add_f32_e32 v216, v216, v136
	v_cmp_gt_u32_e32 vcc, 8, v217
	s_nop 1
	v_cndmask_b32_e32 v221, v216, v221, vcc
	v_cmp_eq_u32_e32 vcc, 0, v150
	s_and_saveexec_b64 s[98:99], vcc
	global_store_dword v220, v221, s[100:101]
	s_mov_b64 exec, s[98:99]
	s_add_u32 s88, s88, 0x50000
	s_addc_u32 s89, s89, 0
	s_add_u32 s92, s92, 0x28000
	s_addc_u32 s93, s93, 0
	s_add_u32 s100, s100, 0x1400
	s_addc_u32 s101, s101, 0
	v_mov_b32_e32 v160, v56
	v_mov_b32_e32 v161, v57
	v_mov_b32_e32 v162, v58
	v_mov_b32_e32 v163, v59
	v_mov_b32_dpp v56, v60 row_ror:8 row_mask:0xf bank_mask:0x3
	v_mov_b32_dpp v57, v61 row_ror:8 row_mask:0xf bank_mask:0x3
	v_mov_b32_dpp v58, v62 row_ror:8 row_mask:0xf bank_mask:0x3
	v_mov_b32_dpp v59, v63 row_ror:8 row_mask:0xf bank_mask:0x3
	v_mov_b32_dpp v60, v160 row_ror:8 row_mask:0xf bank_mask:0xc
	v_mov_b32_dpp v61, v161 row_ror:8 row_mask:0xf bank_mask:0xc
	v_mov_b32_dpp v62, v162 row_ror:8 row_mask:0xf bank_mask:0xc
	v_mov_b32_dpp v63, v163 row_ror:8 row_mask:0xf bank_mask:0xc
	s_waitcnt vmcnt(33)
	v_add_f32_e32 v60, v60, v184
	v_add_f32_e32 v61, v61, v185
	v_add_f32_e32 v62, v62, v186
	v_add_f32_e32 v63, v63, v187
	global_store_dwordx4 v152, v[60:63], s[88:89]
	v_cvt_pk_bf16_f32 v184, v60, v61
	v_cvt_pk_bf16_f32 v185, v62, v63
	global_store_dwordx2 v210, v[184:185], s[92:93]
	v_mul_f32_e32 v221, v60, v60
	v_fmac_f32_e32 v221, v61, v61
	v_fmac_f32_e32 v221, v62, v62
	v_fmac_f32_e32 v221, v63, v63
	global_load_dwordx4 v[184:187], v153, s[86:87] offset:512
	s_waitcnt vmcnt(33)
	v_add_f32_e32 v56, v56, v188
	v_add_f32_e32 v57, v57, v189
	v_add_f32_e32 v58, v58, v190
	v_add_f32_e32 v59, v59, v191
	global_store_dwordx4 v153, v[56:59], s[88:89]
	v_cvt_pk_bf16_f32 v188, v56, v57
	v_cvt_pk_bf16_f32 v189, v58, v59
	global_store_dwordx2 v211, v[188:189], s[92:93]
	v_mul_f32_e32 v216, v56, v56
	v_fmac_f32_e32 v216, v57, v57
	v_fmac_f32_e32 v216, v58, v58
	v_fmac_f32_e32 v216, v59, v59
	s_add_u32 s86, s86, 0x10000
	s_addc_u32 s87, s87, 0
	global_load_dwordx4 v[188:191], v152, s[86:87]
	v_mov_b32_e32 v160, v48
	v_mov_b32_e32 v161, v49
	v_mov_b32_e32 v162, v50
	v_mov_b32_e32 v163, v51
	v_mov_b32_dpp v48, v52 row_ror:8 row_mask:0xf bank_mask:0x3
	v_mov_b32_dpp v49, v53 row_ror:8 row_mask:0xf bank_mask:0x3
	v_mov_b32_dpp v50, v54 row_ror:8 row_mask:0xf bank_mask:0x3
	v_mov_b32_dpp v51, v55 row_ror:8 row_mask:0xf bank_mask:0x3
	v_mov_b32_dpp v52, v160 row_ror:8 row_mask:0xf bank_mask:0xc
	v_mov_b32_dpp v53, v161 row_ror:8 row_mask:0xf bank_mask:0xc
	v_mov_b32_dpp v54, v162 row_ror:8 row_mask:0xf bank_mask:0xc
	v_mov_b32_dpp v55, v163 row_ror:8 row_mask:0xf bank_mask:0xc
	s_waitcnt vmcnt(33)
	v_add_f32_e32 v52, v52, v192
	v_add_f32_e32 v53, v53, v193
	v_add_f32_e32 v54, v54, v194
	v_add_f32_e32 v55, v55, v195
	global_store_dwordx4 v152, v[52:55], s[88:89] offset:512
	v_cvt_pk_bf16_f32 v192, v52, v53
	v_cvt_pk_bf16_f32 v193, v54, v55
	global_store_dwordx2 v210, v[192:193], s[92:93] offset:256
	v_fmac_f32_e32 v221, v52, v52
	v_fmac_f32_e32 v221, v53, v53
	v_fmac_f32_e32 v221, v54, v54
	v_fmac_f32_e32 v221, v55, v55
	global_load_dwordx4 v[192:195], v153, s[86:87]
	s_waitcnt vmcnt(32)
	v_add_f32_e32 v48, v48, v196
	v_add_f32_e32 v49, v49, v197
	v_add_f32_e32 v50, v50, v198
	v_add_f32_e32 v51, v51, v199
	global_store_dwordx4 v153, v[48:51], s[88:89] offset:512
	v_cvt_pk_bf16_f32 v196, v48, v49
	v_cvt_pk_bf16_f32 v197, v50, v51
	global_store_dwordx2 v211, v[196:197], s[92:93] offset:256
	v_fmac_f32_e32 v216, v48, v48
	v_fmac_f32_e32 v216, v49, v49
	v_fmac_f32_e32 v216, v50, v50
	v_fmac_f32_e32 v216, v51, v51
	global_load_dwordx4 v[196:199], v152, s[86:87] offset:512
	s_nop 1
	v_add_f32_dpp v221, v221, v221 row_ror:8 row_mask:0xf bank_mask:0xf
	v_add_f32_dpp v216, v216, v216 row_ror:8 row_mask:0xf bank_mask:0xf
	s_nop 0
	ds_bpermute_b32 v151, v148, v221
	ds_bpermute_b32 v136, v148, v216
	s_waitcnt lgkmcnt(0)
	v_add_f32_e32 v221, v221, v151
	v_add_f32_e32 v216, v216, v136
	s_nop 0
	ds_bpermute_b32 v151, v149, v221
	ds_bpermute_b32 v136, v149, v216
	s_waitcnt lgkmcnt(0)
	v_add_f32_e32 v221, v221, v151
	v_add_f32_e32 v216, v216, v136
	v_cmp_gt_u32_e32 vcc, 8, v217
	s_nop 1
	v_cndmask_b32_e32 v221, v216, v221, vcc
	v_cmp_eq_u32_e32 vcc, 0, v150
	s_and_saveexec_b64 s[98:99], vcc
	global_store_dword v220, v221, s[100:101]
	s_mov_b64 exec, s[98:99]
	s_add_u32 s88, s88, 0x10000
	s_addc_u32 s89, s89, 0
	s_add_u32 s92, s92, 0x8000
	s_addc_u32 s93, s93, 0
	s_add_u32 s100, s100, 0x400
	s_addc_u32 s101, s101, 0
	v_mov_b32_e32 v160, v40
	v_mov_b32_e32 v161, v41
	v_mov_b32_e32 v162, v42
	v_mov_b32_e32 v163, v43
	v_mov_b32_dpp v40, v44 row_ror:8 row_mask:0xf bank_mask:0x3
	v_mov_b32_dpp v41, v45 row_ror:8 row_mask:0xf bank_mask:0x3
	v_mov_b32_dpp v42, v46 row_ror:8 row_mask:0xf bank_mask:0x3
	v_mov_b32_dpp v43, v47 row_ror:8 row_mask:0xf bank_mask:0x3
	v_mov_b32_dpp v44, v160 row_ror:8 row_mask:0xf bank_mask:0xc
	v_mov_b32_dpp v45, v161 row_ror:8 row_mask:0xf bank_mask:0xc
	v_mov_b32_dpp v46, v162 row_ror:8 row_mask:0xf bank_mask:0xc
	v_mov_b32_dpp v47, v163 row_ror:8 row_mask:0xf bank_mask:0xc
	s_waitcnt vmcnt(33)
	v_add_f32_e32 v44, v44, v200
	v_add_f32_e32 v45, v45, v201
	v_add_f32_e32 v46, v46, v202
	v_add_f32_e32 v47, v47, v203
	global_store_dwordx4 v152, v[44:47], s[88:89]
	v_cvt_pk_bf16_f32 v200, v44, v45
	v_cvt_pk_bf16_f32 v201, v46, v47
	global_store_dwordx2 v210, v[200:201], s[92:93]
	v_mul_f32_e32 v221, v44, v44
	v_fmac_f32_e32 v221, v45, v45
	v_fmac_f32_e32 v221, v46, v46
	v_fmac_f32_e32 v221, v47, v47
	global_load_dwordx4 v[200:203], v153, s[86:87] offset:512
	s_waitcnt vmcnt(33)
	v_add_f32_e32 v40, v40, v212
	v_add_f32_e32 v41, v41, v213
	v_add_f32_e32 v42, v42, v214
	v_add_f32_e32 v43, v43, v215
	global_store_dwordx4 v153, v[40:43], s[88:89]
	v_cvt_pk_bf16_f32 v212, v40, v41
	v_cvt_pk_bf16_f32 v213, v42, v43
	global_store_dwordx2 v211, v[212:213], s[92:93]
	v_mul_f32_e32 v216, v40, v40
	v_fmac_f32_e32 v216, v41, v41
	v_fmac_f32_e32 v216, v42, v42
	v_fmac_f32_e32 v216, v43, v43
	v_mov_b32_e32 v160, v32
	v_mov_b32_e32 v161, v33
	v_mov_b32_e32 v162, v34
	v_mov_b32_e32 v163, v35
	v_mov_b32_dpp v32, v36 row_ror:8 row_mask:0xf bank_mask:0x3
	v_mov_b32_dpp v33, v37 row_ror:8 row_mask:0xf bank_mask:0x3
	v_mov_b32_dpp v34, v38 row_ror:8 row_mask:0xf bank_mask:0x3
	v_mov_b32_dpp v35, v39 row_ror:8 row_mask:0xf bank_mask:0x3
	v_mov_b32_dpp v36, v160 row_ror:8 row_mask:0xf bank_mask:0xc
	v_mov_b32_dpp v37, v161 row_ror:8 row_mask:0xf bank_mask:0xc
	v_mov_b32_dpp v38, v162 row_ror:8 row_mask:0xf bank_mask:0xc
	v_mov_b32_dpp v39, v163 row_ror:8 row_mask:0xf bank_mask:0xc
	s_waitcnt vmcnt(32)
	v_add_f32_e32 v36, v36, v164
	v_add_f32_e32 v37, v37, v165
	v_add_f32_e32 v38, v38, v166
	v_add_f32_e32 v39, v39, v167
	global_store_dwordx4 v152, v[36:39], s[88:89] offset:512
	v_cvt_pk_bf16_f32 v164, v36, v37
	v_cvt_pk_bf16_f32 v165, v38, v39
	global_store_dwordx2 v210, v[164:165], s[92:93] offset:256
	v_fmac_f32_e32 v221, v36, v36
	v_fmac_f32_e32 v221, v37, v37
	v_fmac_f32_e32 v221, v38, v38
	v_fmac_f32_e32 v221, v39, v39
	s_waitcnt vmcnt(30)
	v_add_f32_e32 v32, v32, v168
	v_add_f32_e32 v33, v33, v169
	v_add_f32_e32 v34, v34, v170
	v_add_f32_e32 v35, v35, v171
	global_store_dwordx4 v153, v[32:35], s[88:89] offset:512
	v_cvt_pk_bf16_f32 v168, v32, v33
	v_cvt_pk_bf16_f32 v169, v34, v35
	global_store_dwordx2 v211, v[168:169], s[92:93] offset:256
	v_fmac_f32_e32 v216, v32, v32
	v_fmac_f32_e32 v216, v33, v33
	v_fmac_f32_e32 v216, v34, v34
	v_fmac_f32_e32 v216, v35, v35
	s_nop 1
	v_add_f32_dpp v221, v221, v221 row_ror:8 row_mask:0xf bank_mask:0xf
	v_add_f32_dpp v216, v216, v216 row_ror:8 row_mask:0xf bank_mask:0xf
	s_nop 0
	ds_bpermute_b32 v151, v148, v221
	ds_bpermute_b32 v136, v148, v216
	s_waitcnt lgkmcnt(0)
	v_add_f32_e32 v221, v221, v151
	v_add_f32_e32 v216, v216, v136
	s_nop 0
	ds_bpermute_b32 v151, v149, v221
	ds_bpermute_b32 v136, v149, v216
	s_waitcnt lgkmcnt(0)
	v_add_f32_e32 v221, v221, v151
	v_add_f32_e32 v216, v216, v136
	v_cmp_gt_u32_e32 vcc, 8, v217
	s_nop 1
	v_cndmask_b32_e32 v221, v216, v221, vcc
	v_cmp_eq_u32_e32 vcc, 0, v150
	s_and_saveexec_b64 s[98:99], vcc
	global_store_dword v220, v221, s[100:101]
	s_mov_b64 exec, s[98:99]
	s_add_u32 s88, s88, 0x10000
	s_addc_u32 s89, s89, 0
	s_add_u32 s92, s92, 0x8000
	s_addc_u32 s93, s93, 0
	s_add_u32 s100, s100, 0x400
	s_addc_u32 s101, s101, 0
	v_mov_b32_e32 v160, v24
	v_mov_b32_e32 v161, v25
	v_mov_b32_e32 v162, v26
	v_mov_b32_e32 v163, v27
	v_mov_b32_dpp v24, v28 row_ror:8 row_mask:0xf bank_mask:0x3
	v_mov_b32_dpp v25, v29 row_ror:8 row_mask:0xf bank_mask:0x3
	v_mov_b32_dpp v26, v30 row_ror:8 row_mask:0xf bank_mask:0x3
	v_mov_b32_dpp v27, v31 row_ror:8 row_mask:0xf bank_mask:0x3
	v_mov_b32_dpp v28, v160 row_ror:8 row_mask:0xf bank_mask:0xc
	v_mov_b32_dpp v29, v161 row_ror:8 row_mask:0xf bank_mask:0xc
	v_mov_b32_dpp v30, v162 row_ror:8 row_mask:0xf bank_mask:0xc
	v_mov_b32_dpp v31, v163 row_ror:8 row_mask:0xf bank_mask:0xc
	s_waitcnt vmcnt(30)
	v_add_f32_e32 v28, v28, v172
	v_add_f32_e32 v29, v29, v173
	v_add_f32_e32 v30, v30, v174
	v_add_f32_e32 v31, v31, v175
	global_store_dwordx4 v152, v[28:31], s[88:89]
	v_cvt_pk_bf16_f32 v172, v28, v29
	v_cvt_pk_bf16_f32 v173, v30, v31
	global_store_dwordx2 v210, v[172:173], s[92:93]
	v_mul_f32_e32 v221, v28, v28
	v_fmac_f32_e32 v221, v29, v29
	v_fmac_f32_e32 v221, v30, v30
	v_fmac_f32_e32 v221, v31, v31
	s_waitcnt vmcnt(29)
	v_add_f32_e32 v24, v24, v176
	v_add_f32_e32 v25, v25, v177
	v_add_f32_e32 v26, v26, v178
	v_add_f32_e32 v27, v27, v179
	global_store_dwordx4 v153, v[24:27], s[88:89]
	v_cvt_pk_bf16_f32 v176, v24, v25
	v_cvt_pk_bf16_f32 v177, v26, v27
	global_store_dwordx2 v211, v[176:177], s[92:93]
	v_mul_f32_e32 v216, v24, v24
	v_fmac_f32_e32 v216, v25, v25
	v_fmac_f32_e32 v216, v26, v26
	v_fmac_f32_e32 v216, v27, v27
	v_mov_b32_e32 v160, v16
	v_mov_b32_e32 v161, v17
	v_mov_b32_e32 v162, v18
	v_mov_b32_e32 v163, v19
	v_mov_b32_dpp v16, v20 row_ror:8 row_mask:0xf bank_mask:0x3
	v_mov_b32_dpp v17, v21 row_ror:8 row_mask:0xf bank_mask:0x3
	v_mov_b32_dpp v18, v22 row_ror:8 row_mask:0xf bank_mask:0x3
	v_mov_b32_dpp v19, v23 row_ror:8 row_mask:0xf bank_mask:0x3
	v_mov_b32_dpp v20, v160 row_ror:8 row_mask:0xf bank_mask:0xc
	v_mov_b32_dpp v21, v161 row_ror:8 row_mask:0xf bank_mask:0xc
	v_mov_b32_dpp v22, v162 row_ror:8 row_mask:0xf bank_mask:0xc
	v_mov_b32_dpp v23, v163 row_ror:8 row_mask:0xf bank_mask:0xc
	s_waitcnt vmcnt(28)
	v_add_f32_e32 v20, v20, v180
	v_add_f32_e32 v21, v21, v181
	v_add_f32_e32 v22, v22, v182
	v_add_f32_e32 v23, v23, v183
	global_store_dwordx4 v152, v[20:23], s[88:89] offset:512
	v_cvt_pk_bf16_f32 v180, v20, v21
	v_cvt_pk_bf16_f32 v181, v22, v23
	global_store_dwordx2 v210, v[180:181], s[92:93] offset:256
	v_fmac_f32_e32 v221, v20, v20
	v_fmac_f32_e32 v221, v21, v21
	v_fmac_f32_e32 v221, v22, v22
	v_fmac_f32_e32 v221, v23, v23
	s_waitcnt vmcnt(26)
	v_add_f32_e32 v16, v16, v184
	v_add_f32_e32 v17, v17, v185
	v_add_f32_e32 v18, v18, v186
	v_add_f32_e32 v19, v19, v187
	global_store_dwordx4 v153, v[16:19], s[88:89] offset:512
	v_cvt_pk_bf16_f32 v184, v16, v17
	v_cvt_pk_bf16_f32 v185, v18, v19
	global_store_dwordx2 v211, v[184:185], s[92:93] offset:256
	v_fmac_f32_e32 v216, v16, v16
	v_fmac_f32_e32 v216, v17, v17
	v_fmac_f32_e32 v216, v18, v18
	v_fmac_f32_e32 v216, v19, v19
	s_nop 1
	v_add_f32_dpp v221, v221, v221 row_ror:8 row_mask:0xf bank_mask:0xf
	v_add_f32_dpp v216, v216, v216 row_ror:8 row_mask:0xf bank_mask:0xf
	s_nop 0
	ds_bpermute_b32 v151, v148, v221
	ds_bpermute_b32 v136, v148, v216
	s_waitcnt lgkmcnt(0)
	v_add_f32_e32 v221, v221, v151
	v_add_f32_e32 v216, v216, v136
	s_nop 0
	ds_bpermute_b32 v151, v149, v221
	ds_bpermute_b32 v136, v149, v216
	s_waitcnt lgkmcnt(0)
	v_add_f32_e32 v221, v221, v151
	v_add_f32_e32 v216, v216, v136
	v_cmp_gt_u32_e32 vcc, 8, v217
	s_nop 1
	v_cndmask_b32_e32 v221, v216, v221, vcc
	v_cmp_eq_u32_e32 vcc, 0, v150
	s_and_saveexec_b64 s[98:99], vcc
	global_store_dword v220, v221, s[100:101]
	s_mov_b64 exec, s[98:99]
	s_add_u32 s88, s88, 0x10000
	s_addc_u32 s89, s89, 0
	s_add_u32 s92, s92, 0x8000
	s_addc_u32 s93, s93, 0
	s_add_u32 s100, s100, 0x400
	s_addc_u32 s101, s101, 0
	v_mov_b32_e32 v160, v8
	v_mov_b32_e32 v161, v9
	v_mov_b32_e32 v162, v10
	v_mov_b32_e32 v163, v11
	v_mov_b32_dpp v8, v12 row_ror:8 row_mask:0xf bank_mask:0x3
	v_mov_b32_dpp v9, v13 row_ror:8 row_mask:0xf bank_mask:0x3
	v_mov_b32_dpp v10, v14 row_ror:8 row_mask:0xf bank_mask:0x3
	v_mov_b32_dpp v11, v15 row_ror:8 row_mask:0xf bank_mask:0x3
	v_mov_b32_dpp v12, v160 row_ror:8 row_mask:0xf bank_mask:0xc
	v_mov_b32_dpp v13, v161 row_ror:8 row_mask:0xf bank_mask:0xc
	v_mov_b32_dpp v14, v162 row_ror:8 row_mask:0xf bank_mask:0xc
	v_mov_b32_dpp v15, v163 row_ror:8 row_mask:0xf bank_mask:0xc
	s_waitcnt vmcnt(26)
	v_add_f32_e32 v12, v12, v188
	v_add_f32_e32 v13, v13, v189
	v_add_f32_e32 v14, v14, v190
	v_add_f32_e32 v15, v15, v191
	global_store_dwordx4 v152, v[12:15], s[88:89]
	v_cvt_pk_bf16_f32 v188, v12, v13
	v_cvt_pk_bf16_f32 v189, v14, v15
	global_store_dwordx2 v210, v[188:189], s[92:93]
	v_mul_f32_e32 v221, v12, v12
	v_fmac_f32_e32 v221, v13, v13
	v_fmac_f32_e32 v221, v14, v14
	v_fmac_f32_e32 v221, v15, v15
	s_waitcnt vmcnt(25)
	v_add_f32_e32 v8, v8, v192
	v_add_f32_e32 v9, v9, v193
	v_add_f32_e32 v10, v10, v194
	v_add_f32_e32 v11, v11, v195
	global_store_dwordx4 v153, v[8:11], s[88:89]
	v_cvt_pk_bf16_f32 v192, v8, v9
	v_cvt_pk_bf16_f32 v193, v10, v11
	global_store_dwordx2 v211, v[192:193], s[92:93]
	v_mul_f32_e32 v216, v8, v8
	v_fmac_f32_e32 v216, v9, v9
	v_fmac_f32_e32 v216, v10, v10
	v_fmac_f32_e32 v216, v11, v11
	v_mov_b32_e32 v160, v0
	v_mov_b32_e32 v161, v1
	v_mov_b32_e32 v162, v2
	v_mov_b32_e32 v163, v3
	v_mov_b32_dpp v0, v4 row_ror:8 row_mask:0xf bank_mask:0x3
	v_mov_b32_dpp v1, v5 row_ror:8 row_mask:0xf bank_mask:0x3
	v_mov_b32_dpp v2, v6 row_ror:8 row_mask:0xf bank_mask:0x3
	v_mov_b32_dpp v3, v7 row_ror:8 row_mask:0xf bank_mask:0x3
	v_mov_b32_dpp v4, v160 row_ror:8 row_mask:0xf bank_mask:0xc
	v_mov_b32_dpp v5, v161 row_ror:8 row_mask:0xf bank_mask:0xc
	v_mov_b32_dpp v6, v162 row_ror:8 row_mask:0xf bank_mask:0xc
	v_mov_b32_dpp v7, v163 row_ror:8 row_mask:0xf bank_mask:0xc
	s_waitcnt vmcnt(24)
	v_add_f32_e32 v4, v4, v196
	v_add_f32_e32 v5, v5, v197
	v_add_f32_e32 v6, v6, v198
	v_add_f32_e32 v7, v7, v199
	global_store_dwordx4 v152, v[4:7], s[88:89] offset:512
	v_cvt_pk_bf16_f32 v196, v4, v5
	v_cvt_pk_bf16_f32 v197, v6, v7
	global_store_dwordx2 v210, v[196:197], s[92:93] offset:256
	v_fmac_f32_e32 v221, v4, v4
	v_fmac_f32_e32 v221, v5, v5
	v_fmac_f32_e32 v221, v6, v6
	v_fmac_f32_e32 v221, v7, v7
	s_waitcnt vmcnt(22)
	v_add_f32_e32 v0, v0, v200
	v_add_f32_e32 v1, v1, v201
	v_add_f32_e32 v2, v2, v202
	v_add_f32_e32 v3, v3, v203
	global_store_dwordx4 v153, v[0:3], s[88:89] offset:512
	v_cvt_pk_bf16_f32 v200, v0, v1
	v_cvt_pk_bf16_f32 v201, v2, v3
	global_store_dwordx2 v211, v[200:201], s[92:93] offset:256
	v_fmac_f32_e32 v216, v0, v0
	v_fmac_f32_e32 v216, v1, v1
	v_fmac_f32_e32 v216, v2, v2
	v_fmac_f32_e32 v216, v3, v3
	s_nop 1
	v_add_f32_dpp v221, v221, v221 row_ror:8 row_mask:0xf bank_mask:0xf
	v_add_f32_dpp v216, v216, v216 row_ror:8 row_mask:0xf bank_mask:0xf
	s_nop 0
	ds_bpermute_b32 v151, v148, v221
	ds_bpermute_b32 v136, v148, v216
	s_waitcnt lgkmcnt(0)
	v_add_f32_e32 v221, v221, v151
	v_add_f32_e32 v216, v216, v136
	s_nop 0
	ds_bpermute_b32 v151, v149, v221
	ds_bpermute_b32 v136, v149, v216
	s_waitcnt lgkmcnt(0)
	v_add_f32_e32 v221, v221, v151
	v_add_f32_e32 v216, v216, v136
	v_cmp_gt_u32_e32 vcc, 8, v217
	s_nop 1
	v_cndmask_b32_e32 v221, v216, v221, vcc
	v_cmp_eq_u32_e32 vcc, 0, v150
	s_and_saveexec_b64 s[98:99], vcc
	global_store_dword v220, v221, s[100:101]
	s_mov_b64 exec, s[98:99]
	s_and_b64 vcc, exec, s[12:13]
	s_mov_b64 s[12:13], -1
	s_cbranch_vccnz .LBB0_997
	s_andn2_b64 vcc, exec, s[26:27]
	s_cbranch_vccnz .LBB0_996
	s_barrier
	s_branch .LBB0_996

.LBB0_1286:
	v_lshrrev_b32_e32 v132, 6, v206
	v_and_b32_e32 v143, 63, v206
	v_lshrrev_b32_e32 v142, 2, v132
	v_and_b32_e32 v132, 3, v132
	v_lshlrev_b32_e32 v142, 6, v142
	v_lshrrev_b32_e32 v146, 4, v143
	v_and_b32_e32 v213, 15, v143
	v_xor_b32_e32 v144, 16, v143
	v_xor_b32_e32 v145, 32, v143
	v_lshlrev_b32_e32 v144, 2, v144
	v_lshlrev_b32_e32 v145, 2, v145
	s_lshl_b32 vcc_lo, s24, 8
	v_add_u32_e32 v142, vcc_lo, v142
	s_lshl_b32 vcc_lo, s20, 2
	v_add_u32_e32 v216, vcc_lo, v132
	v_add_u32_e32 v147, v142, v213
	v_lshlrev_b32_e32 v147, 6, v147
	v_lshl_add_u32 v216, v216, 2, v147
	v_lshlrev_b32_e32 v143, 5, v132
	v_lshrrev_b32_e32 v147, 3, v213
	v_lshl_add_u32 v147, v147, 2, v146
	v_lshl_add_u32 v143, v147, 2, v143
	s_lshl_b32 vcc_lo, s20, 8
	v_add_u32_e32 v143, vcc_lo, v143
	v_and_b32_e32 v147, 7, v213
	v_add_u32_e32 v142, v142, v147
	v_lshlrev_b32_e32 v148, 12, v142
	v_lshl_add_u32 v148, v143, 2, v148
	v_add_u32_e32 v149, 0x8000, v148
	v_lshlrev_b32_e32 v210, 11, v142
	v_lshl_add_u32 v210, v143, 1, v210
	v_add_u32_e32 v211, 0x4000, v210
	s_mov_b32 s86, s94
	s_mov_b32 s87, s95
	s_mov_b32 s88, s94
	s_mov_b32 s89, s95
	s_add_u32 s92, s96, 0x9e00000
	s_addc_u32 s93, s97, 0
	s_add_u32 s100, s96, 0x5000000
	s_addc_u32 s101, s97, 0
	global_load_dwordx4 v[160:163], v148, s[86:87]
	global_load_dwordx4 v[164:167], v149, s[86:87]
	global_load_dwordx4 v[168:171], v148, s[86:87] offset:512
	global_load_dwordx4 v[172:175], v149, s[86:87] offset:512
	s_add_u32 s86, s86, 0x10000
	s_addc_u32 s87, s87, 0
	global_load_dwordx4 v[176:179], v148, s[86:87]
	global_load_dwordx4 v[180:183], v149, s[86:87]
	global_load_dwordx4 v[184:187], v148, s[86:87] offset:512
	global_load_dwordx4 v[188:191], v149, s[86:87] offset:512
	s_add_u32 s86, s86, 0x10000
	s_addc_u32 s87, s87, 0
	global_load_dwordx4 v[192:195], v148, s[86:87]
	global_load_dwordx4 v[196:199], v149, s[86:87]
	global_load_dwordx4 v[200:203], v148, s[86:87] offset:512
	v_mov_b32_e32 v156, v120
	v_mov_b32_e32 v157, v121
	v_mov_b32_e32 v158, v122
	v_mov_b32_e32 v159, v123
	v_mov_b32_dpp v120, v124 row_ror:8 row_mask:0xf bank_mask:0x3
	v_mov_b32_dpp v121, v125 row_ror:8 row_mask:0xf bank_mask:0x3
	v_mov_b32_dpp v122, v126 row_ror:8 row_mask:0xf bank_mask:0x3
	v_mov_b32_dpp v123, v127 row_ror:8 row_mask:0xf bank_mask:0x3
	v_mov_b32_dpp v124, v156 row_ror:8 row_mask:0xf bank_mask:0xc
	v_mov_b32_dpp v125, v157 row_ror:8 row_mask:0xf bank_mask:0xc
	v_mov_b32_dpp v126, v158 row_ror:8 row_mask:0xf bank_mask:0xc
	v_mov_b32_dpp v127, v159 row_ror:8 row_mask:0xf bank_mask:0xc
	s_waitcnt vmcnt(10)
	v_add_f32_e32 v124, v124, v160
	v_add_f32_e32 v125, v125, v161
	v_add_f32_e32 v126, v126, v162
	v_add_f32_e32 v127, v127, v163
	global_store_dwordx4 v148, v[124:127], s[88:89]
	v_cvt_pk_bf16_f32 v160, v124, v125
	v_cvt_pk_bf16_f32 v161, v126, v127
	global_store_dwordx2 v210, v[160:161], s[92:93]
	v_mul_f32_e32 v217, v124, v124
	v_fmac_f32_e32 v217, v125, v125
	v_fmac_f32_e32 v217, v126, v126
	v_fmac_f32_e32 v217, v127, v127
	global_load_dwordx4 v[160:163], v149, s[86:87] offset:512
	s_waitcnt vmcnt(12)
	v_add_f32_e32 v120, v120, v164
	v_add_f32_e32 v121, v121, v165
	v_add_f32_e32 v122, v122, v166
	v_add_f32_e32 v123, v123, v167
	global_store_dwordx4 v149, v[120:123], s[88:89]
	v_cvt_pk_bf16_f32 v164, v120, v121
	v_cvt_pk_bf16_f32 v165, v122, v123
	global_store_dwordx2 v211, v[164:165], s[92:93]
	v_mul_f32_e32 v212, v120, v120
	v_fmac_f32_e32 v212, v121, v121
	v_fmac_f32_e32 v212, v122, v122
	v_fmac_f32_e32 v212, v123, v123
	s_add_u32 s86, s86, 0x10000
	s_addc_u32 s87, s87, 0
	global_load_dwordx4 v[164:167], v148, s[86:87]
	v_mov_b32_e32 v156, v112
	v_mov_b32_e32 v157, v113
	v_mov_b32_e32 v158, v114
	v_mov_b32_e32 v159, v115
	v_mov_b32_dpp v112, v116 row_ror:8 row_mask:0xf bank_mask:0x3
	v_mov_b32_dpp v113, v117 row_ror:8 row_mask:0xf bank_mask:0x3
	v_mov_b32_dpp v114, v118 row_ror:8 row_mask:0xf bank_mask:0x3
	v_mov_b32_dpp v115, v119 row_ror:8 row_mask:0xf bank_mask:0x3
	v_mov_b32_dpp v116, v156 row_ror:8 row_mask:0xf bank_mask:0xc
	v_mov_b32_dpp v117, v157 row_ror:8 row_mask:0xf bank_mask:0xc
	v_mov_b32_dpp v118, v158 row_ror:8 row_mask:0xf bank_mask:0xc
	v_mov_b32_dpp v119, v159 row_ror:8 row_mask:0xf bank_mask:0xc
	s_waitcnt vmcnt(14)
	v_add_f32_e32 v116, v116, v168
	v_add_f32_e32 v117, v117, v169
	v_add_f32_e32 v118, v118, v170
	v_add_f32_e32 v119, v119, v171
	global_store_dwordx4 v148, v[116:119], s[88:89] offset:512
	v_cvt_pk_bf16_f32 v168, v116, v117
	v_cvt_pk_bf16_f32 v169, v118, v119
	global_store_dwordx2 v210, v[168:169], s[92:93] offset:256
	v_fmac_f32_e32 v217, v116, v116
	v_fmac_f32_e32 v217, v117, v117
	v_fmac_f32_e32 v217, v118, v118
	v_fmac_f32_e32 v217, v119, v119
	global_load_dwordx4 v[168:171], v149, s[86:87]
	s_waitcnt vmcnt(16)
	v_add_f32_e32 v112, v112, v172
	v_add_f32_e32 v113, v113, v173
	v_add_f32_e32 v114, v114, v174
	v_add_f32_e32 v115, v115, v175
	global_store_dwordx4 v149, v[112:115], s[88:89] offset:512
	v_cvt_pk_bf16_f32 v172, v112, v113
	v_cvt_pk_bf16_f32 v173, v114, v115
	global_store_dwordx2 v211, v[172:173], s[92:93] offset:256
	v_fmac_f32_e32 v212, v112, v112
	v_fmac_f32_e32 v212, v113, v113
	v_fmac_f32_e32 v212, v114, v114
	v_fmac_f32_e32 v212, v115, v115
	global_load_dwordx4 v[172:175], v148, s[86:87] offset:512
	s_nop 1
	v_add_f32_dpp v217, v217, v217 row_ror:8 row_mask:0xf bank_mask:0xf
	v_add_f32_dpp v212, v212, v212 row_ror:8 row_mask:0xf bank_mask:0xf
	s_nop 0
	ds_bpermute_b32 v147, v144, v217
	ds_bpermute_b32 v132, v144, v212
	s_waitcnt lgkmcnt(0)
	v_add_f32_e32 v217, v217, v147
	v_add_f32_e32 v212, v212, v132
	s_nop 0
	ds_bpermute_b32 v147, v145, v217
	ds_bpermute_b32 v132, v145, v212
	s_waitcnt lgkmcnt(0)
	v_add_f32_e32 v217, v217, v147
	v_add_f32_e32 v212, v212, v132
	v_cmp_gt_u32_e32 vcc, 8, v213
	s_nop 1
	v_cndmask_b32_e32 v217, v212, v217, vcc
	v_cmp_eq_u32_e32 vcc, 0, v146
	s_and_saveexec_b64 s[98:99], vcc
	global_store_dword v216, v217, s[100:101]
	s_mov_b64 exec, s[98:99]
	s_add_u32 s88, s88, 0x10000
	s_addc_u32 s89, s89, 0
	s_add_u32 s92, s92, 0x8000
	s_addc_u32 s93, s93, 0
	s_add_u32 s100, s100, 0x400
	s_addc_u32 s101, s101, 0
	v_mov_b32_e32 v156, v104
	v_mov_b32_e32 v157, v105
	v_mov_b32_e32 v158, v106
	v_mov_b32_e32 v159, v107
	v_mov_b32_dpp v104, v108 row_ror:8 row_mask:0xf bank_mask:0x3
	v_mov_b32_dpp v105, v109 row_ror:8 row_mask:0xf bank_mask:0x3
	v_mov_b32_dpp v106, v110 row_ror:8 row_mask:0xf bank_mask:0x3
	v_mov_b32_dpp v107, v111 row_ror:8 row_mask:0xf bank_mask:0x3
	v_mov_b32_dpp v108, v156 row_ror:8 row_mask:0xf bank_mask:0xc
	v_mov_b32_dpp v109, v157 row_ror:8 row_mask:0xf bank_mask:0xc
	v_mov_b32_dpp v110, v158 row_ror:8 row_mask:0xf bank_mask:0xc
	v_mov_b32_dpp v111, v159 row_ror:8 row_mask:0xf bank_mask:0xc
	s_waitcnt vmcnt(19)
	v_add_f32_e32 v108, v108, v176
	v_add_f32_e32 v109, v109, v177
	v_add_f32_e32 v110, v110, v178
	v_add_f32_e32 v111, v111, v179
	global_store_dwordx4 v148, v[108:111], s[88:89]
	v_cvt_pk_bf16_f32 v176, v108, v109
	v_cvt_pk_bf16_f32 v177, v110, v111
	global_store_dwordx2 v210, v[176:177], s[92:93]
	v_mul_f32_e32 v217, v108, v108
	v_fmac_f32_e32 v217, v109, v109
	v_fmac_f32_e32 v217, v110, v110
	v_fmac_f32_e32 v217, v111, v111
	global_load_dwordx4 v[176:179], v149, s[86:87] offset:512
	s_waitcnt vmcnt(21)
	v_add_f32_e32 v104, v104, v180
	v_add_f32_e32 v105, v105, v181
	v_add_f32_e32 v106, v106, v182
	v_add_f32_e32 v107, v107, v183
	global_store_dwordx4 v149, v[104:107], s[88:89]
	v_cvt_pk_bf16_f32 v180, v104, v105
	v_cvt_pk_bf16_f32 v181, v106, v107
	global_store_dwordx2 v211, v[180:181], s[92:93]
	v_mul_f32_e32 v212, v104, v104
	v_fmac_f32_e32 v212, v105, v105
	v_fmac_f32_e32 v212, v106, v106
	v_fmac_f32_e32 v212, v107, v107
	s_add_u32 s86, s86, 0x50000
	s_addc_u32 s87, s87, 0
	global_load_dwordx4 v[180:183], v148, s[86:87]
	v_mov_b32_e32 v156, v96
	v_mov_b32_e32 v157, v97
	v_mov_b32_e32 v158, v98
	v_mov_b32_e32 v159, v99
	v_mov_b32_dpp v96, v100 row_ror:8 row_mask:0xf bank_mask:0x3
	v_mov_b32_dpp v97, v101 row_ror:8 row_mask:0xf bank_mask:0x3
	v_mov_b32_dpp v98, v102 row_ror:8 row_mask:0xf bank_mask:0x3
	v_mov_b32_dpp v99, v103 row_ror:8 row_mask:0xf bank_mask:0x3
	v_mov_b32_dpp v100, v156 row_ror:8 row_mask:0xf bank_mask:0xc
	v_mov_b32_dpp v101, v157 row_ror:8 row_mask:0xf bank_mask:0xc
	v_mov_b32_dpp v102, v158 row_ror:8 row_mask:0xf bank_mask:0xc
	v_mov_b32_dpp v103, v159 row_ror:8 row_mask:0xf bank_mask:0xc
	s_waitcnt vmcnt(23)
	v_add_f32_e32 v100, v100, v184
	v_add_f32_e32 v101, v101, v185
	v_add_f32_e32 v102, v102, v186
	v_add_f32_e32 v103, v103, v187
	global_store_dwordx4 v148, v[100:103], s[88:89] offset:512
	v_cvt_pk_bf16_f32 v184, v100, v101
	v_cvt_pk_bf16_f32 v185, v102, v103
	global_store_dwordx2 v210, v[184:185], s[92:93] offset:256
	v_fmac_f32_e32 v217, v100, v100
	v_fmac_f32_e32 v217, v101, v101
	v_fmac_f32_e32 v217, v102, v102
	v_fmac_f32_e32 v217, v103, v103
	global_load_dwordx4 v[184:187], v149, s[86:87]
	s_waitcnt vmcnt(25)
	v_add_f32_e32 v96, v96, v188
	v_add_f32_e32 v97, v97, v189
	v_add_f32_e32 v98, v98, v190
	v_add_f32_e32 v99, v99, v191
	global_store_dwordx4 v149, v[96:99], s[88:89] offset:512
	v_cvt_pk_bf16_f32 v188, v96, v97
	v_cvt_pk_bf16_f32 v189, v98, v99
	global_store_dwordx2 v211, v[188:189], s[92:93] offset:256
	v_fmac_f32_e32 v212, v96, v96
	v_fmac_f32_e32 v212, v97, v97
	v_fmac_f32_e32 v212, v98, v98
	v_fmac_f32_e32 v212, v99, v99
	global_load_dwordx4 v[188:191], v148, s[86:87] offset:512
	s_nop 1
	v_add_f32_dpp v217, v217, v217 row_ror:8 row_mask:0xf bank_mask:0xf
	v_add_f32_dpp v212, v212, v212 row_ror:8 row_mask:0xf bank_mask:0xf
	s_nop 0
	ds_bpermute_b32 v147, v144, v217
	ds_bpermute_b32 v132, v144, v212
	s_waitcnt lgkmcnt(0)
	v_add_f32_e32 v217, v217, v147
	v_add_f32_e32 v212, v212, v132
	s_nop 0
	ds_bpermute_b32 v147, v145, v217
	ds_bpermute_b32 v132, v145, v212
	s_waitcnt lgkmcnt(0)
	v_add_f32_e32 v217, v217, v147
	v_add_f32_e32 v212, v212, v132
	v_cmp_gt_u32_e32 vcc, 8, v213
	s_nop 1
	v_cndmask_b32_e32 v217, v212, v217, vcc
	v_cmp_eq_u32_e32 vcc, 0, v146
	s_and_saveexec_b64 s[98:99], vcc
	global_store_dword v216, v217, s[100:101]
	s_mov_b64 exec, s[98:99]
	s_add_u32 s88, s88, 0x10000
	s_addc_u32 s89, s89, 0
	s_add_u32 s92, s92, 0x8000
	s_addc_u32 s93, s93, 0
	s_add_u32 s100, s100, 0x400
	s_addc_u32 s101, s101, 0
	v_mov_b32_e32 v156, v88
	v_mov_b32_e32 v157, v89
	v_mov_b32_e32 v158, v90
	v_mov_b32_e32 v159, v91
	v_mov_b32_dpp v88, v92 row_ror:8 row_mask:0xf bank_mask:0x3
	v_mov_b32_dpp v89, v93 row_ror:8 row_mask:0xf bank_mask:0x3
	v_mov_b32_dpp v90, v94 row_ror:8 row_mask:0xf bank_mask:0x3
	v_mov_b32_dpp v91, v95 row_ror:8 row_mask:0xf bank_mask:0x3
	v_mov_b32_dpp v92, v156 row_ror:8 row_mask:0xf bank_mask:0xc
	v_mov_b32_dpp v93, v157 row_ror:8 row_mask:0xf bank_mask:0xc
	v_mov_b32_dpp v94, v158 row_ror:8 row_mask:0xf bank_mask:0xc
	v_mov_b32_dpp v95, v159 row_ror:8 row_mask:0xf bank_mask:0xc
	s_waitcnt vmcnt(28)
	v_add_f32_e32 v92, v92, v192
	v_add_f32_e32 v93, v93, v193
	v_add_f32_e32 v94, v94, v194
	v_add_f32_e32 v95, v95, v195
	global_store_dwordx4 v148, v[92:95], s[88:89]
	v_cvt_pk_bf16_f32 v192, v92, v93
	v_cvt_pk_bf16_f32 v193, v94, v95
	global_store_dwordx2 v210, v[192:193], s[92:93]
	v_mul_f32_e32 v217, v92, v92
	v_fmac_f32_e32 v217, v93, v93
	v_fmac_f32_e32 v217, v94, v94
	v_fmac_f32_e32 v217, v95, v95
	global_load_dwordx4 v[192:195], v149, s[86:87] offset:512
	s_waitcnt vmcnt(30)
	v_add_f32_e32 v88, v88, v196
	v_add_f32_e32 v89, v89, v197
	v_add_f32_e32 v90, v90, v198
	v_add_f32_e32 v91, v91, v199
	global_store_dwordx4 v149, v[88:91], s[88:89]
	v_cvt_pk_bf16_f32 v196, v88, v89
	v_cvt_pk_bf16_f32 v197, v90, v91
	global_store_dwordx2 v211, v[196:197], s[92:93]
	v_mul_f32_e32 v212, v88, v88
	v_fmac_f32_e32 v212, v89, v89
	v_fmac_f32_e32 v212, v90, v90
	v_fmac_f32_e32 v212, v91, v91
	s_add_u32 s86, s86, 0x10000
	s_addc_u32 s87, s87, 0
	global_load_dwordx4 v[196:199], v148, s[86:87]
	v_mov_b32_e32 v156, v80
	v_mov_b32_e32 v157, v81
	v_mov_b32_e32 v158, v82
	v_mov_b32_e32 v159, v83
	v_mov_b32_dpp v80, v84 row_ror:8 row_mask:0xf bank_mask:0x3
	v_mov_b32_dpp v81, v85 row_ror:8 row_mask:0xf bank_mask:0x3
	v_mov_b32_dpp v82, v86 row_ror:8 row_mask:0xf bank_mask:0x3
	v_mov_b32_dpp v83, v87 row_ror:8 row_mask:0xf bank_mask:0x3
	v_mov_b32_dpp v84, v156 row_ror:8 row_mask:0xf bank_mask:0xc
	v_mov_b32_dpp v85, v157 row_ror:8 row_mask:0xf bank_mask:0xc
	v_mov_b32_dpp v86, v158 row_ror:8 row_mask:0xf bank_mask:0xc
	v_mov_b32_dpp v87, v159 row_ror:8 row_mask:0xf bank_mask:0xc
	s_waitcnt vmcnt(32)
	v_add_f32_e32 v84, v84, v200
	v_add_f32_e32 v85, v85, v201
	v_add_f32_e32 v86, v86, v202
	v_add_f32_e32 v87, v87, v203
	global_store_dwordx4 v148, v[84:87], s[88:89] offset:512
	v_cvt_pk_bf16_f32 v200, v84, v85
	v_cvt_pk_bf16_f32 v201, v86, v87
	global_store_dwordx2 v210, v[200:201], s[92:93] offset:256
	v_fmac_f32_e32 v217, v84, v84
	v_fmac_f32_e32 v217, v85, v85
	v_fmac_f32_e32 v217, v86, v86
	v_fmac_f32_e32 v217, v87, v87
	global_load_dwordx4 v[200:203], v149, s[86:87]
	s_waitcnt vmcnt(32)
	v_add_f32_e32 v80, v80, v160
	v_add_f32_e32 v81, v81, v161
	v_add_f32_e32 v82, v82, v162
	v_add_f32_e32 v83, v83, v163
	global_store_dwordx4 v149, v[80:83], s[88:89] offset:512
	v_cvt_pk_bf16_f32 v160, v80, v81
	v_cvt_pk_bf16_f32 v161, v82, v83
	global_store_dwordx2 v211, v[160:161], s[92:93] offset:256
	v_fmac_f32_e32 v212, v80, v80
	v_fmac_f32_e32 v212, v81, v81
	v_fmac_f32_e32 v212, v82, v82
	v_fmac_f32_e32 v212, v83, v83
	global_load_dwordx4 v[160:163], v148, s[86:87] offset:512
	s_nop 1
	v_add_f32_dpp v217, v217, v217 row_ror:8 row_mask:0xf bank_mask:0xf
	v_add_f32_dpp v212, v212, v212 row_ror:8 row_mask:0xf bank_mask:0xf
	s_nop 0
	ds_bpermute_b32 v147, v144, v217
	ds_bpermute_b32 v132, v144, v212
	s_waitcnt lgkmcnt(0)
	v_add_f32_e32 v217, v217, v147
	v_add_f32_e32 v212, v212, v132
	s_nop 0
	ds_bpermute_b32 v147, v145, v217
	ds_bpermute_b32 v132, v145, v212
	s_waitcnt lgkmcnt(0)
	v_add_f32_e32 v217, v217, v147
	v_add_f32_e32 v212, v212, v132
	v_cmp_gt_u32_e32 vcc, 8, v213
	s_nop 1
	v_cndmask_b32_e32 v217, v212, v217, vcc
	v_cmp_eq_u32_e32 vcc, 0, v146
	s_and_saveexec_b64 s[98:99], vcc
	global_store_dword v216, v217, s[100:101]
	s_mov_b64 exec, s[98:99]
	s_add_u32 s88, s88, 0x10000
	s_addc_u32 s89, s89, 0
	s_add_u32 s92, s92, 0x8000
	s_addc_u32 s93, s93, 0
	s_add_u32 s100, s100, 0x400
	s_addc_u32 s101, s101, 0
	v_mov_b32_e32 v156, v72
	v_mov_b32_e32 v157, v73
	v_mov_b32_e32 v158, v74
	v_mov_b32_e32 v159, v75
	v_mov_b32_dpp v72, v76 row_ror:8 row_mask:0xf bank_mask:0x3
	v_mov_b32_dpp v73, v77 row_ror:8 row_mask:0xf bank_mask:0x3
	v_mov_b32_dpp v74, v78 row_ror:8 row_mask:0xf bank_mask:0x3
	v_mov_b32_dpp v75, v79 row_ror:8 row_mask:0xf bank_mask:0x3
	v_mov_b32_dpp v76, v156 row_ror:8 row_mask:0xf bank_mask:0xc
	v_mov_b32_dpp v77, v157 row_ror:8 row_mask:0xf bank_mask:0xc
	v_mov_b32_dpp v78, v158 row_ror:8 row_mask:0xf bank_mask:0xc
	v_mov_b32_dpp v79, v159 row_ror:8 row_mask:0xf bank_mask:0xc
	s_waitcnt vmcnt(33)
	v_add_f32_e32 v76, v76, v164
	v_add_f32_e32 v77, v77, v165
	v_add_f32_e32 v78, v78, v166
	v_add_f32_e32 v79, v79, v167
	global_store_dwordx4 v148, v[76:79], s[88:89]
	v_cvt_pk_bf16_f32 v164, v76, v77
	v_cvt_pk_bf16_f32 v165, v78, v79
	global_store_dwordx2 v210, v[164:165], s[92:93]
	v_mul_f32_e32 v217, v76, v76
	v_fmac_f32_e32 v217, v77, v77
	v_fmac_f32_e32 v217, v78, v78
	v_fmac_f32_e32 v217, v79, v79
	global_load_dwordx4 v[164:167], v149, s[86:87] offset:512
	s_waitcnt vmcnt(33)
	v_add_f32_e32 v72, v72, v168
	v_add_f32_e32 v73, v73, v169
	v_add_f32_e32 v74, v74, v170
	v_add_f32_e32 v75, v75, v171
	global_store_dwordx4 v149, v[72:75], s[88:89]
	v_cvt_pk_bf16_f32 v168, v72, v73
	v_cvt_pk_bf16_f32 v169, v74, v75
	global_store_dwordx2 v211, v[168:169], s[92:93]
	v_mul_f32_e32 v212, v72, v72
	v_fmac_f32_e32 v212, v73, v73
	v_fmac_f32_e32 v212, v74, v74
	v_fmac_f32_e32 v212, v75, v75
	s_add_u32 s86, s86, 0x10000
	s_addc_u32 s87, s87, 0
	global_load_dwordx4 v[168:171], v148, s[86:87]
	v_mov_b32_e32 v156, v64
	v_mov_b32_e32 v157, v65
	v_mov_b32_e32 v158, v66
	v_mov_b32_e32 v159, v67
	v_mov_b32_dpp v64, v68 row_ror:8 row_mask:0xf bank_mask:0x3
	v_mov_b32_dpp v65, v69 row_ror:8 row_mask:0xf bank_mask:0x3
	v_mov_b32_dpp v66, v70 row_ror:8 row_mask:0xf bank_mask:0x3
	v_mov_b32_dpp v67, v71 row_ror:8 row_mask:0xf bank_mask:0x3
	v_mov_b32_dpp v68, v156 row_ror:8 row_mask:0xf bank_mask:0xc
	v_mov_b32_dpp v69, v157 row_ror:8 row_mask:0xf bank_mask:0xc
	v_mov_b32_dpp v70, v158 row_ror:8 row_mask:0xf bank_mask:0xc
	v_mov_b32_dpp v71, v159 row_ror:8 row_mask:0xf bank_mask:0xc
	s_waitcnt vmcnt(33)
	v_add_f32_e32 v68, v68, v172
	v_add_f32_e32 v69, v69, v173
	v_add_f32_e32 v70, v70, v174
	v_add_f32_e32 v71, v71, v175
	global_store_dwordx4 v148, v[68:71], s[88:89] offset:512
	v_cvt_pk_bf16_f32 v172, v68, v69
	v_cvt_pk_bf16_f32 v173, v70, v71
	global_store_dwordx2 v210, v[172:173], s[92:93] offset:256
	v_fmac_f32_e32 v217, v68, v68
	v_fmac_f32_e32 v217, v69, v69
	v_fmac_f32_e32 v217, v70, v70
	v_fmac_f32_e32 v217, v71, v71
	global_load_dwordx4 v[172:175], v149, s[86:87]
	s_waitcnt vmcnt(32)
	v_add_f32_e32 v64, v64, v176
	v_add_f32_e32 v65, v65, v177
	v_add_f32_e32 v66, v66, v178
	v_add_f32_e32 v67, v67, v179
	global_store_dwordx4 v149, v[64:67], s[88:89] offset:512
	v_cvt_pk_bf16_f32 v176, v64, v65
	v_cvt_pk_bf16_f32 v177, v66, v67
	global_store_dwordx2 v211, v[176:177], s[92:93] offset:256
	v_fmac_f32_e32 v212, v64, v64
	v_fmac_f32_e32 v212, v65, v65
	v_fmac_f32_e32 v212, v66, v66
	v_fmac_f32_e32 v212, v67, v67
	global_load_dwordx4 v[176:179], v148, s[86:87] offset:512
	s_nop 1
	v_add_f32_dpp v217, v217, v217 row_ror:8 row_mask:0xf bank_mask:0xf
	v_add_f32_dpp v212, v212, v212 row_ror:8 row_mask:0xf bank_mask:0xf
	s_nop 0
	ds_bpermute_b32 v147, v144, v217
	ds_bpermute_b32 v132, v144, v212
	s_waitcnt lgkmcnt(0)
	v_add_f32_e32 v217, v217, v147
	v_add_f32_e32 v212, v212, v132
	s_nop 0
	ds_bpermute_b32 v147, v145, v217
	ds_bpermute_b32 v132, v145, v212
	s_waitcnt lgkmcnt(0)
	v_add_f32_e32 v217, v217, v147
	v_add_f32_e32 v212, v212, v132
	v_cmp_gt_u32_e32 vcc, 8, v213
	s_nop 1
	v_cndmask_b32_e32 v217, v212, v217, vcc
	v_cmp_eq_u32_e32 vcc, 0, v146
	s_and_saveexec_b64 s[98:99], vcc
	global_store_dword v216, v217, s[100:101]
	s_mov_b64 exec, s[98:99]
	s_add_u32 s88, s88, 0x50000
	s_addc_u32 s89, s89, 0
	s_add_u32 s92, s92, 0x28000
	s_addc_u32 s93, s93, 0
	s_add_u32 s100, s100, 0x1400
	s_addc_u32 s101, s101, 0
	v_mov_b32_e32 v156, v56
	v_mov_b32_e32 v157, v57
	v_mov_b32_e32 v158, v58
	v_mov_b32_e32 v159, v59
	v_mov_b32_dpp v56, v60 row_ror:8 row_mask:0xf bank_mask:0x3
	v_mov_b32_dpp v57, v61 row_ror:8 row_mask:0xf bank_mask:0x3
	v_mov_b32_dpp v58, v62 row_ror:8 row_mask:0xf bank_mask:0x3
	v_mov_b32_dpp v59, v63 row_ror:8 row_mask:0xf bank_mask:0x3
	v_mov_b32_dpp v60, v156 row_ror:8 row_mask:0xf bank_mask:0xc
	v_mov_b32_dpp v61, v157 row_ror:8 row_mask:0xf bank_mask:0xc
	v_mov_b32_dpp v62, v158 row_ror:8 row_mask:0xf bank_mask:0xc
	v_mov_b32_dpp v63, v159 row_ror:8 row_mask:0xf bank_mask:0xc
	s_waitcnt vmcnt(33)
	v_add_f32_e32 v60, v60, v180
	v_add_f32_e32 v61, v61, v181
	v_add_f32_e32 v62, v62, v182
	v_add_f32_e32 v63, v63, v183
	global_store_dwordx4 v148, v[60:63], s[88:89]
	v_cvt_pk_bf16_f32 v180, v60, v61
	v_cvt_pk_bf16_f32 v181, v62, v63
	global_store_dwordx2 v210, v[180:181], s[92:93]
	v_mul_f32_e32 v217, v60, v60
	v_fmac_f32_e32 v217, v61, v61
	v_fmac_f32_e32 v217, v62, v62
	v_fmac_f32_e32 v217, v63, v63
	global_load_dwordx4 v[180:183], v149, s[86:87] offset:512
	s_waitcnt vmcnt(33)
	v_add_f32_e32 v56, v56, v184
	v_add_f32_e32 v57, v57, v185
	v_add_f32_e32 v58, v58, v186
	v_add_f32_e32 v59, v59, v187
	global_store_dwordx4 v149, v[56:59], s[88:89]
	v_cvt_pk_bf16_f32 v184, v56, v57
	v_cvt_pk_bf16_f32 v185, v58, v59
	global_store_dwordx2 v211, v[184:185], s[92:93]
	v_mul_f32_e32 v212, v56, v56
	v_fmac_f32_e32 v212, v57, v57
	v_fmac_f32_e32 v212, v58, v58
	v_fmac_f32_e32 v212, v59, v59
	s_add_u32 s86, s86, 0x10000
	s_addc_u32 s87, s87, 0
	global_load_dwordx4 v[184:187], v148, s[86:87]
	v_mov_b32_e32 v156, v48
	v_mov_b32_e32 v157, v49
	v_mov_b32_e32 v158, v50
	v_mov_b32_e32 v159, v51
	v_mov_b32_dpp v48, v52 row_ror:8 row_mask:0xf bank_mask:0x3
	v_mov_b32_dpp v49, v53 row_ror:8 row_mask:0xf bank_mask:0x3
	v_mov_b32_dpp v50, v54 row_ror:8 row_mask:0xf bank_mask:0x3
	v_mov_b32_dpp v51, v55 row_ror:8 row_mask:0xf bank_mask:0x3
	v_mov_b32_dpp v52, v156 row_ror:8 row_mask:0xf bank_mask:0xc
	v_mov_b32_dpp v53, v157 row_ror:8 row_mask:0xf bank_mask:0xc
	v_mov_b32_dpp v54, v158 row_ror:8 row_mask:0xf bank_mask:0xc
	v_mov_b32_dpp v55, v159 row_ror:8 row_mask:0xf bank_mask:0xc
	s_waitcnt vmcnt(33)
	v_add_f32_e32 v52, v52, v188
	v_add_f32_e32 v53, v53, v189
	v_add_f32_e32 v54, v54, v190
	v_add_f32_e32 v55, v55, v191
	global_store_dwordx4 v148, v[52:55], s[88:89] offset:512
	v_cvt_pk_bf16_f32 v188, v52, v53
	v_cvt_pk_bf16_f32 v189, v54, v55
	global_store_dwordx2 v210, v[188:189], s[92:93] offset:256
	v_fmac_f32_e32 v217, v52, v52
	v_fmac_f32_e32 v217, v53, v53
	v_fmac_f32_e32 v217, v54, v54
	v_fmac_f32_e32 v217, v55, v55
	global_load_dwordx4 v[188:191], v149, s[86:87]
	s_waitcnt vmcnt(32)
	v_add_f32_e32 v48, v48, v192
	v_add_f32_e32 v49, v49, v193
	v_add_f32_e32 v50, v50, v194
	v_add_f32_e32 v51, v51, v195
	global_store_dwordx4 v149, v[48:51], s[88:89] offset:512
	v_cvt_pk_bf16_f32 v192, v48, v49
	v_cvt_pk_bf16_f32 v193, v50, v51
	global_store_dwordx2 v211, v[192:193], s[92:93] offset:256
	v_fmac_f32_e32 v212, v48, v48
	v_fmac_f32_e32 v212, v49, v49
	v_fmac_f32_e32 v212, v50, v50
	v_fmac_f32_e32 v212, v51, v51
	global_load_dwordx4 v[192:195], v148, s[86:87] offset:512
	s_nop 1
	v_add_f32_dpp v217, v217, v217 row_ror:8 row_mask:0xf bank_mask:0xf
	v_add_f32_dpp v212, v212, v212 row_ror:8 row_mask:0xf bank_mask:0xf
	s_nop 0
	ds_bpermute_b32 v147, v144, v217
	ds_bpermute_b32 v132, v144, v212
	s_waitcnt lgkmcnt(0)
	v_add_f32_e32 v217, v217, v147
	v_add_f32_e32 v212, v212, v132
	s_nop 0
	ds_bpermute_b32 v147, v145, v217
	ds_bpermute_b32 v132, v145, v212
	s_waitcnt lgkmcnt(0)
	v_add_f32_e32 v217, v217, v147
	v_add_f32_e32 v212, v212, v132
	v_cmp_gt_u32_e32 vcc, 8, v213
	s_nop 1
	v_cndmask_b32_e32 v217, v212, v217, vcc
	v_cmp_eq_u32_e32 vcc, 0, v146
	s_and_saveexec_b64 s[98:99], vcc
	global_store_dword v216, v217, s[100:101]
	s_mov_b64 exec, s[98:99]
	s_add_u32 s88, s88, 0x10000
	s_addc_u32 s89, s89, 0
	s_add_u32 s92, s92, 0x8000
	s_addc_u32 s93, s93, 0
	s_add_u32 s100, s100, 0x400
	s_addc_u32 s101, s101, 0
	v_mov_b32_e32 v156, v40
	v_mov_b32_e32 v157, v41
	v_mov_b32_e32 v158, v42
	v_mov_b32_e32 v159, v43
	v_mov_b32_dpp v40, v44 row_ror:8 row_mask:0xf bank_mask:0x3
	v_mov_b32_dpp v41, v45 row_ror:8 row_mask:0xf bank_mask:0x3
	v_mov_b32_dpp v42, v46 row_ror:8 row_mask:0xf bank_mask:0x3
	v_mov_b32_dpp v43, v47 row_ror:8 row_mask:0xf bank_mask:0x3
	v_mov_b32_dpp v44, v156 row_ror:8 row_mask:0xf bank_mask:0xc
	v_mov_b32_dpp v45, v157 row_ror:8 row_mask:0xf bank_mask:0xc
	v_mov_b32_dpp v46, v158 row_ror:8 row_mask:0xf bank_mask:0xc
	v_mov_b32_dpp v47, v159 row_ror:8 row_mask:0xf bank_mask:0xc
	s_waitcnt vmcnt(33)
	v_add_f32_e32 v44, v44, v196
	v_add_f32_e32 v45, v45, v197
	v_add_f32_e32 v46, v46, v198
	v_add_f32_e32 v47, v47, v199
	global_store_dwordx4 v148, v[44:47], s[88:89]
	v_cvt_pk_bf16_f32 v196, v44, v45
	v_cvt_pk_bf16_f32 v197, v46, v47
	global_store_dwordx2 v210, v[196:197], s[92:93]
	v_mul_f32_e32 v217, v44, v44
	v_fmac_f32_e32 v217, v45, v45
	v_fmac_f32_e32 v217, v46, v46
	v_fmac_f32_e32 v217, v47, v47
	global_load_dwordx4 v[196:199], v149, s[86:87] offset:512
	s_waitcnt vmcnt(33)
	v_add_f32_e32 v40, v40, v200
	v_add_f32_e32 v41, v41, v201
	v_add_f32_e32 v42, v42, v202
	v_add_f32_e32 v43, v43, v203
	global_store_dwordx4 v149, v[40:43], s[88:89]
	v_cvt_pk_bf16_f32 v200, v40, v41
	v_cvt_pk_bf16_f32 v201, v42, v43
	global_store_dwordx2 v211, v[200:201], s[92:93]
	v_mul_f32_e32 v212, v40, v40
	v_fmac_f32_e32 v212, v41, v41
	v_fmac_f32_e32 v212, v42, v42
	v_fmac_f32_e32 v212, v43, v43
	v_mov_b32_e32 v156, v32
	v_mov_b32_e32 v157, v33
	v_mov_b32_e32 v158, v34
	v_mov_b32_e32 v159, v35
	v_mov_b32_dpp v32, v36 row_ror:8 row_mask:0xf bank_mask:0x3
	v_mov_b32_dpp v33, v37 row_ror:8 row_mask:0xf bank_mask:0x3
	v_mov_b32_dpp v34, v38 row_ror:8 row_mask:0xf bank_mask:0x3
	v_mov_b32_dpp v35, v39 row_ror:8 row_mask:0xf bank_mask:0x3
	v_mov_b32_dpp v36, v156 row_ror:8 row_mask:0xf bank_mask:0xc
	v_mov_b32_dpp v37, v157 row_ror:8 row_mask:0xf bank_mask:0xc
	v_mov_b32_dpp v38, v158 row_ror:8 row_mask:0xf bank_mask:0xc
	v_mov_b32_dpp v39, v159 row_ror:8 row_mask:0xf bank_mask:0xc
	s_waitcnt vmcnt(32)
	v_add_f32_e32 v36, v36, v160
	v_add_f32_e32 v37, v37, v161
	v_add_f32_e32 v38, v38, v162
	v_add_f32_e32 v39, v39, v163
	global_store_dwordx4 v148, v[36:39], s[88:89] offset:512
	v_cvt_pk_bf16_f32 v160, v36, v37
	v_cvt_pk_bf16_f32 v161, v38, v39
	global_store_dwordx2 v210, v[160:161], s[92:93] offset:256
	v_fmac_f32_e32 v217, v36, v36
	v_fmac_f32_e32 v217, v37, v37
	v_fmac_f32_e32 v217, v38, v38
	v_fmac_f32_e32 v217, v39, v39
	s_waitcnt vmcnt(30)
	v_add_f32_e32 v32, v32, v164
	v_add_f32_e32 v33, v33, v165
	v_add_f32_e32 v34, v34, v166
	v_add_f32_e32 v35, v35, v167
	global_store_dwordx4 v149, v[32:35], s[88:89] offset:512
	v_cvt_pk_bf16_f32 v164, v32, v33
	v_cvt_pk_bf16_f32 v165, v34, v35
	global_store_dwordx2 v211, v[164:165], s[92:93] offset:256
	v_fmac_f32_e32 v212, v32, v32
	v_fmac_f32_e32 v212, v33, v33
	v_fmac_f32_e32 v212, v34, v34
	v_fmac_f32_e32 v212, v35, v35
	s_nop 1
	v_add_f32_dpp v217, v217, v217 row_ror:8 row_mask:0xf bank_mask:0xf
	v_add_f32_dpp v212, v212, v212 row_ror:8 row_mask:0xf bank_mask:0xf
	s_nop 0
	ds_bpermute_b32 v147, v144, v217
	ds_bpermute_b32 v132, v144, v212
	s_waitcnt lgkmcnt(0)
	v_add_f32_e32 v217, v217, v147
	v_add_f32_e32 v212, v212, v132
	s_nop 0
	ds_bpermute_b32 v147, v145, v217
	ds_bpermute_b32 v132, v145, v212
	s_waitcnt lgkmcnt(0)
	v_add_f32_e32 v217, v217, v147
	v_add_f32_e32 v212, v212, v132
	v_cmp_gt_u32_e32 vcc, 8, v213
	s_nop 1
	v_cndmask_b32_e32 v217, v212, v217, vcc
	v_cmp_eq_u32_e32 vcc, 0, v146
	s_and_saveexec_b64 s[98:99], vcc
	global_store_dword v216, v217, s[100:101]
	s_mov_b64 exec, s[98:99]
	s_add_u32 s88, s88, 0x10000
	s_addc_u32 s89, s89, 0
	s_add_u32 s92, s92, 0x8000
	s_addc_u32 s93, s93, 0
	s_add_u32 s100, s100, 0x400
	s_addc_u32 s101, s101, 0
	v_mov_b32_e32 v156, v24
	v_mov_b32_e32 v157, v25
	v_mov_b32_e32 v158, v26
	v_mov_b32_e32 v159, v27
	v_mov_b32_dpp v24, v28 row_ror:8 row_mask:0xf bank_mask:0x3
	v_mov_b32_dpp v25, v29 row_ror:8 row_mask:0xf bank_mask:0x3
	v_mov_b32_dpp v26, v30 row_ror:8 row_mask:0xf bank_mask:0x3
	v_mov_b32_dpp v27, v31 row_ror:8 row_mask:0xf bank_mask:0x3
	v_mov_b32_dpp v28, v156 row_ror:8 row_mask:0xf bank_mask:0xc
	v_mov_b32_dpp v29, v157 row_ror:8 row_mask:0xf bank_mask:0xc
	v_mov_b32_dpp v30, v158 row_ror:8 row_mask:0xf bank_mask:0xc
	v_mov_b32_dpp v31, v159 row_ror:8 row_mask:0xf bank_mask:0xc
	s_waitcnt vmcnt(30)
	v_add_f32_e32 v28, v28, v168
	v_add_f32_e32 v29, v29, v169
	v_add_f32_e32 v30, v30, v170
	v_add_f32_e32 v31, v31, v171
	global_store_dwordx4 v148, v[28:31], s[88:89]
	v_cvt_pk_bf16_f32 v168, v28, v29
	v_cvt_pk_bf16_f32 v169, v30, v31
	global_store_dwordx2 v210, v[168:169], s[92:93]
	v_mul_f32_e32 v217, v28, v28
	v_fmac_f32_e32 v217, v29, v29
	v_fmac_f32_e32 v217, v30, v30
	v_fmac_f32_e32 v217, v31, v31
	s_waitcnt vmcnt(29)
	v_add_f32_e32 v24, v24, v172
	v_add_f32_e32 v25, v25, v173
	v_add_f32_e32 v26, v26, v174
	v_add_f32_e32 v27, v27, v175
	global_store_dwordx4 v149, v[24:27], s[88:89]
	v_cvt_pk_bf16_f32 v172, v24, v25
	v_cvt_pk_bf16_f32 v173, v26, v27
	global_store_dwordx2 v211, v[172:173], s[92:93]
	v_mul_f32_e32 v212, v24, v24
	v_fmac_f32_e32 v212, v25, v25
	v_fmac_f32_e32 v212, v26, v26
	v_fmac_f32_e32 v212, v27, v27
	v_mov_b32_e32 v156, v16
	v_mov_b32_e32 v157, v17
	v_mov_b32_e32 v158, v18
	v_mov_b32_e32 v159, v19
	v_mov_b32_dpp v16, v20 row_ror:8 row_mask:0xf bank_mask:0x3
	v_mov_b32_dpp v17, v21 row_ror:8 row_mask:0xf bank_mask:0x3
	v_mov_b32_dpp v18, v22 row_ror:8 row_mask:0xf bank_mask:0x3
	v_mov_b32_dpp v19, v23 row_ror:8 row_mask:0xf bank_mask:0x3
	v_mov_b32_dpp v20, v156 row_ror:8 row_mask:0xf bank_mask:0xc
	v_mov_b32_dpp v21, v157 row_ror:8 row_mask:0xf bank_mask:0xc
	v_mov_b32_dpp v22, v158 row_ror:8 row_mask:0xf bank_mask:0xc
	v_mov_b32_dpp v23, v159 row_ror:8 row_mask:0xf bank_mask:0xc
	s_waitcnt vmcnt(28)
	v_add_f32_e32 v20, v20, v176
	v_add_f32_e32 v21, v21, v177
	v_add_f32_e32 v22, v22, v178
	v_add_f32_e32 v23, v23, v179
	global_store_dwordx4 v148, v[20:23], s[88:89] offset:512
	v_cvt_pk_bf16_f32 v176, v20, v21
	v_cvt_pk_bf16_f32 v177, v22, v23
	global_store_dwordx2 v210, v[176:177], s[92:93] offset:256
	v_fmac_f32_e32 v217, v20, v20
	v_fmac_f32_e32 v217, v21, v21
	v_fmac_f32_e32 v217, v22, v22
	v_fmac_f32_e32 v217, v23, v23
	s_waitcnt vmcnt(26)
	v_add_f32_e32 v16, v16, v180
	v_add_f32_e32 v17, v17, v181
	v_add_f32_e32 v18, v18, v182
	v_add_f32_e32 v19, v19, v183
	global_store_dwordx4 v149, v[16:19], s[88:89] offset:512
	v_cvt_pk_bf16_f32 v180, v16, v17
	v_cvt_pk_bf16_f32 v181, v18, v19
	global_store_dwordx2 v211, v[180:181], s[92:93] offset:256
	v_fmac_f32_e32 v212, v16, v16
	v_fmac_f32_e32 v212, v17, v17
	v_fmac_f32_e32 v212, v18, v18
	v_fmac_f32_e32 v212, v19, v19
	s_nop 1
	v_add_f32_dpp v217, v217, v217 row_ror:8 row_mask:0xf bank_mask:0xf
	v_add_f32_dpp v212, v212, v212 row_ror:8 row_mask:0xf bank_mask:0xf
	s_nop 0
	ds_bpermute_b32 v147, v144, v217
	ds_bpermute_b32 v132, v144, v212
	s_waitcnt lgkmcnt(0)
	v_add_f32_e32 v217, v217, v147
	v_add_f32_e32 v212, v212, v132
	s_nop 0
	ds_bpermute_b32 v147, v145, v217
	ds_bpermute_b32 v132, v145, v212
	s_waitcnt lgkmcnt(0)
	v_add_f32_e32 v217, v217, v147
	v_add_f32_e32 v212, v212, v132
	v_cmp_gt_u32_e32 vcc, 8, v213
	s_nop 1
	v_cndmask_b32_e32 v217, v212, v217, vcc
	v_cmp_eq_u32_e32 vcc, 0, v146
	s_and_saveexec_b64 s[98:99], vcc
	global_store_dword v216, v217, s[100:101]
	s_mov_b64 exec, s[98:99]
	s_add_u32 s88, s88, 0x10000
	s_addc_u32 s89, s89, 0
	s_add_u32 s92, s92, 0x8000
	s_addc_u32 s93, s93, 0
	s_add_u32 s100, s100, 0x400
	s_addc_u32 s101, s101, 0
	v_mov_b32_e32 v156, v8
	v_mov_b32_e32 v157, v9
	v_mov_b32_e32 v158, v10
	v_mov_b32_e32 v159, v11
	v_mov_b32_dpp v8, v12 row_ror:8 row_mask:0xf bank_mask:0x3
	v_mov_b32_dpp v9, v13 row_ror:8 row_mask:0xf bank_mask:0x3
	v_mov_b32_dpp v10, v14 row_ror:8 row_mask:0xf bank_mask:0x3
	v_mov_b32_dpp v11, v15 row_ror:8 row_mask:0xf bank_mask:0x3
	v_mov_b32_dpp v12, v156 row_ror:8 row_mask:0xf bank_mask:0xc
	v_mov_b32_dpp v13, v157 row_ror:8 row_mask:0xf bank_mask:0xc
	v_mov_b32_dpp v14, v158 row_ror:8 row_mask:0xf bank_mask:0xc
	v_mov_b32_dpp v15, v159 row_ror:8 row_mask:0xf bank_mask:0xc
	s_waitcnt vmcnt(26)
	v_add_f32_e32 v12, v12, v184
	v_add_f32_e32 v13, v13, v185
	v_add_f32_e32 v14, v14, v186
	v_add_f32_e32 v15, v15, v187
	global_store_dwordx4 v148, v[12:15], s[88:89]
	v_cvt_pk_bf16_f32 v184, v12, v13
	v_cvt_pk_bf16_f32 v185, v14, v15
	global_store_dwordx2 v210, v[184:185], s[92:93]
	v_mul_f32_e32 v217, v12, v12
	v_fmac_f32_e32 v217, v13, v13
	v_fmac_f32_e32 v217, v14, v14
	v_fmac_f32_e32 v217, v15, v15
	s_waitcnt vmcnt(25)
	v_add_f32_e32 v8, v8, v188
	v_add_f32_e32 v9, v9, v189
	v_add_f32_e32 v10, v10, v190
	v_add_f32_e32 v11, v11, v191
	global_store_dwordx4 v149, v[8:11], s[88:89]
	v_cvt_pk_bf16_f32 v188, v8, v9
	v_cvt_pk_bf16_f32 v189, v10, v11
	global_store_dwordx2 v211, v[188:189], s[92:93]
	v_mul_f32_e32 v212, v8, v8
	v_fmac_f32_e32 v212, v9, v9
	v_fmac_f32_e32 v212, v10, v10
	v_fmac_f32_e32 v212, v11, v11
	v_mov_b32_e32 v156, v0
	v_mov_b32_e32 v157, v1
	v_mov_b32_e32 v158, v2
	v_mov_b32_e32 v159, v3
	v_mov_b32_dpp v0, v4 row_ror:8 row_mask:0xf bank_mask:0x3
	v_mov_b32_dpp v1, v5 row_ror:8 row_mask:0xf bank_mask:0x3
	v_mov_b32_dpp v2, v6 row_ror:8 row_mask:0xf bank_mask:0x3
	v_mov_b32_dpp v3, v7 row_ror:8 row_mask:0xf bank_mask:0x3
	v_mov_b32_dpp v4, v156 row_ror:8 row_mask:0xf bank_mask:0xc
	v_mov_b32_dpp v5, v157 row_ror:8 row_mask:0xf bank_mask:0xc
	v_mov_b32_dpp v6, v158 row_ror:8 row_mask:0xf bank_mask:0xc
	v_mov_b32_dpp v7, v159 row_ror:8 row_mask:0xf bank_mask:0xc
	s_waitcnt vmcnt(24)
	v_add_f32_e32 v4, v4, v192
	v_add_f32_e32 v5, v5, v193
	v_add_f32_e32 v6, v6, v194
	v_add_f32_e32 v7, v7, v195
	global_store_dwordx4 v148, v[4:7], s[88:89] offset:512
	v_cvt_pk_bf16_f32 v192, v4, v5
	v_cvt_pk_bf16_f32 v193, v6, v7
	global_store_dwordx2 v210, v[192:193], s[92:93] offset:256
	v_fmac_f32_e32 v217, v4, v4
	v_fmac_f32_e32 v217, v5, v5
	v_fmac_f32_e32 v217, v6, v6
	v_fmac_f32_e32 v217, v7, v7
	s_waitcnt vmcnt(22)
	v_add_f32_e32 v0, v0, v196
	v_add_f32_e32 v1, v1, v197
	v_add_f32_e32 v2, v2, v198
	v_add_f32_e32 v3, v3, v199
	global_store_dwordx4 v149, v[0:3], s[88:89] offset:512
	v_cvt_pk_bf16_f32 v196, v0, v1
	v_cvt_pk_bf16_f32 v197, v2, v3
	global_store_dwordx2 v211, v[196:197], s[92:93] offset:256
	v_fmac_f32_e32 v212, v0, v0
	v_fmac_f32_e32 v212, v1, v1
	v_fmac_f32_e32 v212, v2, v2
	v_fmac_f32_e32 v212, v3, v3
	s_nop 1
	v_add_f32_dpp v217, v217, v217 row_ror:8 row_mask:0xf bank_mask:0xf
	v_add_f32_dpp v212, v212, v212 row_ror:8 row_mask:0xf bank_mask:0xf
	s_nop 0
	ds_bpermute_b32 v147, v144, v217
	ds_bpermute_b32 v132, v144, v212
	s_waitcnt lgkmcnt(0)
	v_add_f32_e32 v217, v217, v147
	v_add_f32_e32 v212, v212, v132
	s_nop 0
	ds_bpermute_b32 v147, v145, v217
	ds_bpermute_b32 v132, v145, v212
	s_waitcnt lgkmcnt(0)
	v_add_f32_e32 v217, v217, v147
	v_add_f32_e32 v212, v212, v132
	v_cmp_gt_u32_e32 vcc, 8, v213
	s_nop 1
	v_cndmask_b32_e32 v217, v212, v217, vcc
	v_cmp_eq_u32_e32 vcc, 0, v146
	s_and_saveexec_b64 s[98:99], vcc
	global_store_dword v216, v217, s[100:101]
	s_mov_b64 exec, s[98:99]
	s_andn2_b64 vcc, exec, s[12:13]
	s_mov_b64 s[12:13], -1
	s_cbranch_vccnz .LBB0_1275
	s_andn2_b64 vcc, exec, s[26:27]
	s_cbranch_vccnz .LBB0_1274
	s_barrier
	s_branch .LBB0_1274

.LBB0_1492:
	v_lshrrev_b32_e32 v132, 6, v206
	v_and_b32_e32 v143, 63, v206
	v_lshrrev_b32_e32 v142, 2, v132
	v_and_b32_e32 v132, 3, v132
	v_lshlrev_b32_e32 v142, 6, v142
	v_lshrrev_b32_e32 v146, 4, v143
	v_and_b32_e32 v213, 15, v143
	v_xor_b32_e32 v144, 16, v143
	v_xor_b32_e32 v145, 32, v143
	v_lshlrev_b32_e32 v144, 2, v144
	v_lshlrev_b32_e32 v145, 2, v145
	s_lshl_b32 vcc_lo, s12, 8
	v_add_u32_e32 v142, vcc_lo, v142
	s_lshl_b32 vcc_lo, s49, 2
	v_add_u32_e32 v216, vcc_lo, v132
	v_add_u32_e32 v147, v142, v213
	v_lshlrev_b32_e32 v147, 6, v147
	v_lshl_add_u32 v216, v216, 2, v147
	v_lshlrev_b32_e32 v143, 5, v132
	v_lshrrev_b32_e32 v147, 3, v213
	v_lshl_add_u32 v147, v147, 2, v146
	v_lshl_add_u32 v143, v147, 2, v143
	s_lshl_b32 vcc_lo, s49, 8
	v_add_u32_e32 v143, vcc_lo, v143
	v_and_b32_e32 v147, 7, v213
	v_add_u32_e32 v142, v142, v147
	v_lshlrev_b32_e32 v148, 12, v142
	v_lshl_add_u32 v148, v143, 2, v148
	v_add_u32_e32 v149, 0x8000, v148
	v_lshlrev_b32_e32 v210, 11, v142
	v_lshl_add_u32 v210, v143, 1, v210
	v_add_u32_e32 v211, 0x4000, v210
	s_mov_b32 s86, s94
	s_mov_b32 s87, s95
	s_mov_b32 s88, s94
	s_mov_b32 s89, s95
	s_add_u32 s100, s96, 0x5500000
	s_addc_u32 s101, s97, 0
	global_load_dwordx4 v[160:163], v148, s[86:87]
	global_load_dwordx4 v[164:167], v149, s[86:87]
	global_load_dwordx4 v[168:171], v148, s[86:87] offset:512
	global_load_dwordx4 v[172:175], v149, s[86:87] offset:512
	s_add_u32 s86, s86, 0x10000
	s_addc_u32 s87, s87, 0
	global_load_dwordx4 v[176:179], v148, s[86:87]
	global_load_dwordx4 v[180:183], v149, s[86:87]
	global_load_dwordx4 v[184:187], v148, s[86:87] offset:512
	global_load_dwordx4 v[188:191], v149, s[86:87] offset:512
	s_add_u32 s86, s86, 0x10000
	s_addc_u32 s87, s87, 0
	global_load_dwordx4 v[192:195], v148, s[86:87]
	global_load_dwordx4 v[196:199], v149, s[86:87]
	global_load_dwordx4 v[200:203], v148, s[86:87] offset:512
	v_mov_b32_e32 v156, v120
	v_mov_b32_e32 v157, v121
	v_mov_b32_e32 v158, v122
	v_mov_b32_e32 v159, v123
	v_mov_b32_dpp v120, v124 row_ror:8 row_mask:0xf bank_mask:0x3
	v_mov_b32_dpp v121, v125 row_ror:8 row_mask:0xf bank_mask:0x3
	v_mov_b32_dpp v122, v126 row_ror:8 row_mask:0xf bank_mask:0x3
	v_mov_b32_dpp v123, v127 row_ror:8 row_mask:0xf bank_mask:0x3
	v_mov_b32_dpp v124, v156 row_ror:8 row_mask:0xf bank_mask:0xc
	v_mov_b32_dpp v125, v157 row_ror:8 row_mask:0xf bank_mask:0xc
	v_mov_b32_dpp v126, v158 row_ror:8 row_mask:0xf bank_mask:0xc
	v_mov_b32_dpp v127, v159 row_ror:8 row_mask:0xf bank_mask:0xc
	s_waitcnt vmcnt(10)
	v_fma_f32 v124, v124, 0.5, v160
	v_fma_f32 v125, v125, 0.5, v161
	v_fma_f32 v126, v126, 0.5, v162
	v_fma_f32 v127, v127, 0.5, v163
	global_store_dwordx4 v148, v[124:127], s[88:89]
	v_mul_f32_e32 v217, v124, v124
	v_fmac_f32_e32 v217, v125, v125
	v_fmac_f32_e32 v217, v126, v126
	v_fmac_f32_e32 v217, v127, v127
	global_load_dwordx4 v[160:163], v149, s[86:87] offset:512
	s_waitcnt vmcnt(11)
	v_fma_f32 v120, v120, 0.5, v164
	v_fma_f32 v121, v121, 0.5, v165
	v_fma_f32 v122, v122, 0.5, v166
	v_fma_f32 v123, v123, 0.5, v167
	global_store_dwordx4 v149, v[120:123], s[88:89]
	v_mul_f32_e32 v212, v120, v120
	v_fmac_f32_e32 v212, v121, v121
	v_fmac_f32_e32 v212, v122, v122
	v_fmac_f32_e32 v212, v123, v123
	s_add_u32 s86, s86, 0x10000
	s_addc_u32 s87, s87, 0
	global_load_dwordx4 v[164:167], v148, s[86:87]
	v_mov_b32_e32 v156, v112
	v_mov_b32_e32 v157, v113
	v_mov_b32_e32 v158, v114
	v_mov_b32_e32 v159, v115
	v_mov_b32_dpp v112, v116 row_ror:8 row_mask:0xf bank_mask:0x3
	v_mov_b32_dpp v113, v117 row_ror:8 row_mask:0xf bank_mask:0x3
	v_mov_b32_dpp v114, v118 row_ror:8 row_mask:0xf bank_mask:0x3
	v_mov_b32_dpp v115, v119 row_ror:8 row_mask:0xf bank_mask:0x3
	v_mov_b32_dpp v116, v156 row_ror:8 row_mask:0xf bank_mask:0xc
	v_mov_b32_dpp v117, v157 row_ror:8 row_mask:0xf bank_mask:0xc
	v_mov_b32_dpp v118, v158 row_ror:8 row_mask:0xf bank_mask:0xc
	v_mov_b32_dpp v119, v159 row_ror:8 row_mask:0xf bank_mask:0xc
	s_waitcnt vmcnt(12)
	v_fma_f32 v116, v116, 0.5, v168
	v_fma_f32 v117, v117, 0.5, v169
	v_fma_f32 v118, v118, 0.5, v170
	v_fma_f32 v119, v119, 0.5, v171
	global_store_dwordx4 v148, v[116:119], s[88:89] offset:512
	v_fmac_f32_e32 v217, v116, v116
	v_fmac_f32_e32 v217, v117, v117
	v_fmac_f32_e32 v217, v118, v118
	v_fmac_f32_e32 v217, v119, v119
	global_load_dwordx4 v[168:171], v149, s[86:87]
	s_waitcnt vmcnt(13)
	v_fma_f32 v112, v112, 0.5, v172
	v_fma_f32 v113, v113, 0.5, v173
	v_fma_f32 v114, v114, 0.5, v174
	v_fma_f32 v115, v115, 0.5, v175
	global_store_dwordx4 v149, v[112:115], s[88:89] offset:512
	v_fmac_f32_e32 v212, v112, v112
	v_fmac_f32_e32 v212, v113, v113
	v_fmac_f32_e32 v212, v114, v114
	v_fmac_f32_e32 v212, v115, v115
	global_load_dwordx4 v[172:175], v148, s[86:87] offset:512
	s_nop 1
	v_add_f32_dpp v217, v217, v217 row_ror:8 row_mask:0xf bank_mask:0xf
	v_add_f32_dpp v212, v212, v212 row_ror:8 row_mask:0xf bank_mask:0xf
	s_nop 0
	ds_bpermute_b32 v147, v144, v217
	ds_bpermute_b32 v132, v144, v212
	s_waitcnt lgkmcnt(0)
	v_add_f32_e32 v217, v217, v147
	v_add_f32_e32 v212, v212, v132
	s_nop 0
	ds_bpermute_b32 v147, v145, v217
	ds_bpermute_b32 v132, v145, v212
	s_waitcnt lgkmcnt(0)
	v_add_f32_e32 v217, v217, v147
	v_add_f32_e32 v212, v212, v132
	v_cmp_gt_u32_e32 vcc, 8, v213
	s_nop 1
	v_cndmask_b32_e32 v217, v212, v217, vcc
	v_cmp_eq_u32_e32 vcc, 0, v146
	s_and_saveexec_b64 s[98:99], vcc
	global_store_dword v216, v217, s[100:101]
	s_mov_b64 exec, s[98:99]
	s_add_u32 s88, s88, 0x10000
	s_addc_u32 s89, s89, 0
	s_add_u32 s100, s100, 0x400
	s_addc_u32 s101, s101, 0
	v_mov_b32_e32 v156, v104
	v_mov_b32_e32 v157, v105
	v_mov_b32_e32 v158, v106
	v_mov_b32_e32 v159, v107
	v_mov_b32_dpp v104, v108 row_ror:8 row_mask:0xf bank_mask:0x3
	v_mov_b32_dpp v105, v109 row_ror:8 row_mask:0xf bank_mask:0x3
	v_mov_b32_dpp v106, v110 row_ror:8 row_mask:0xf bank_mask:0x3
	v_mov_b32_dpp v107, v111 row_ror:8 row_mask:0xf bank_mask:0x3
	v_mov_b32_dpp v108, v156 row_ror:8 row_mask:0xf bank_mask:0xc
	v_mov_b32_dpp v109, v157 row_ror:8 row_mask:0xf bank_mask:0xc
	v_mov_b32_dpp v110, v158 row_ror:8 row_mask:0xf bank_mask:0xc
	v_mov_b32_dpp v111, v159 row_ror:8 row_mask:0xf bank_mask:0xc
	s_waitcnt vmcnt(15)
	v_fma_f32 v108, v108, 0.5, v176
	v_fma_f32 v109, v109, 0.5, v177
	v_fma_f32 v110, v110, 0.5, v178
	v_fma_f32 v111, v111, 0.5, v179
	global_store_dwordx4 v148, v[108:111], s[88:89]
	v_mul_f32_e32 v217, v108, v108
	v_fmac_f32_e32 v217, v109, v109
	v_fmac_f32_e32 v217, v110, v110
	v_fmac_f32_e32 v217, v111, v111
	global_load_dwordx4 v[176:179], v149, s[86:87] offset:512
	s_waitcnt vmcnt(16)
	v_fma_f32 v104, v104, 0.5, v180
	v_fma_f32 v105, v105, 0.5, v181
	v_fma_f32 v106, v106, 0.5, v182
	v_fma_f32 v107, v107, 0.5, v183
	global_store_dwordx4 v149, v[104:107], s[88:89]
	v_mul_f32_e32 v212, v104, v104
	v_fmac_f32_e32 v212, v105, v105
	v_fmac_f32_e32 v212, v106, v106
	v_fmac_f32_e32 v212, v107, v107
	s_add_u32 s86, s86, 0x50000
	s_addc_u32 s87, s87, 0
	global_load_dwordx4 v[180:183], v148, s[86:87]
	v_mov_b32_e32 v156, v96
	v_mov_b32_e32 v157, v97
	v_mov_b32_e32 v158, v98
	v_mov_b32_e32 v159, v99
	v_mov_b32_dpp v96, v100 row_ror:8 row_mask:0xf bank_mask:0x3
	v_mov_b32_dpp v97, v101 row_ror:8 row_mask:0xf bank_mask:0x3
	v_mov_b32_dpp v98, v102 row_ror:8 row_mask:0xf bank_mask:0x3
	v_mov_b32_dpp v99, v103 row_ror:8 row_mask:0xf bank_mask:0x3
	v_mov_b32_dpp v100, v156 row_ror:8 row_mask:0xf bank_mask:0xc
	v_mov_b32_dpp v101, v157 row_ror:8 row_mask:0xf bank_mask:0xc
	v_mov_b32_dpp v102, v158 row_ror:8 row_mask:0xf bank_mask:0xc
	v_mov_b32_dpp v103, v159 row_ror:8 row_mask:0xf bank_mask:0xc
	s_waitcnt vmcnt(17)
	v_fma_f32 v100, v100, 0.5, v184
	v_fma_f32 v101, v101, 0.5, v185
	v_fma_f32 v102, v102, 0.5, v186
	v_fma_f32 v103, v103, 0.5, v187
	global_store_dwordx4 v148, v[100:103], s[88:89] offset:512
	v_fmac_f32_e32 v217, v100, v100
	v_fmac_f32_e32 v217, v101, v101
	v_fmac_f32_e32 v217, v102, v102
	v_fmac_f32_e32 v217, v103, v103
	global_load_dwordx4 v[184:187], v149, s[86:87]
	s_waitcnt vmcnt(18)
	v_fma_f32 v96, v96, 0.5, v188
	v_fma_f32 v97, v97, 0.5, v189
	v_fma_f32 v98, v98, 0.5, v190
	v_fma_f32 v99, v99, 0.5, v191
	global_store_dwordx4 v149, v[96:99], s[88:89] offset:512
	v_fmac_f32_e32 v212, v96, v96
	v_fmac_f32_e32 v212, v97, v97
	v_fmac_f32_e32 v212, v98, v98
	v_fmac_f32_e32 v212, v99, v99
	global_load_dwordx4 v[188:191], v148, s[86:87] offset:512
	s_nop 1
	v_add_f32_dpp v217, v217, v217 row_ror:8 row_mask:0xf bank_mask:0xf
	v_add_f32_dpp v212, v212, v212 row_ror:8 row_mask:0xf bank_mask:0xf
	s_nop 0
	ds_bpermute_b32 v147, v144, v217
	ds_bpermute_b32 v132, v144, v212
	s_waitcnt lgkmcnt(0)
	v_add_f32_e32 v217, v217, v147
	v_add_f32_e32 v212, v212, v132
	s_nop 0
	ds_bpermute_b32 v147, v145, v217
	ds_bpermute_b32 v132, v145, v212
	s_waitcnt lgkmcnt(0)
	v_add_f32_e32 v217, v217, v147
	v_add_f32_e32 v212, v212, v132
	v_cmp_gt_u32_e32 vcc, 8, v213
	s_nop 1
	v_cndmask_b32_e32 v217, v212, v217, vcc
	v_cmp_eq_u32_e32 vcc, 0, v146
	s_and_saveexec_b64 s[98:99], vcc
	global_store_dword v216, v217, s[100:101]
	s_mov_b64 exec, s[98:99]
	s_add_u32 s88, s88, 0x10000
	s_addc_u32 s89, s89, 0
	s_add_u32 s100, s100, 0x400
	s_addc_u32 s101, s101, 0
	v_mov_b32_e32 v156, v88
	v_mov_b32_e32 v157, v89
	v_mov_b32_e32 v158, v90
	v_mov_b32_e32 v159, v91
	v_mov_b32_dpp v88, v92 row_ror:8 row_mask:0xf bank_mask:0x3
	v_mov_b32_dpp v89, v93 row_ror:8 row_mask:0xf bank_mask:0x3
	v_mov_b32_dpp v90, v94 row_ror:8 row_mask:0xf bank_mask:0x3
	v_mov_b32_dpp v91, v95 row_ror:8 row_mask:0xf bank_mask:0x3
	v_mov_b32_dpp v92, v156 row_ror:8 row_mask:0xf bank_mask:0xc
	v_mov_b32_dpp v93, v157 row_ror:8 row_mask:0xf bank_mask:0xc
	v_mov_b32_dpp v94, v158 row_ror:8 row_mask:0xf bank_mask:0xc
	v_mov_b32_dpp v95, v159 row_ror:8 row_mask:0xf bank_mask:0xc
	s_waitcnt vmcnt(20)
	v_fma_f32 v92, v92, 0.5, v192
	v_fma_f32 v93, v93, 0.5, v193
	v_fma_f32 v94, v94, 0.5, v194
	v_fma_f32 v95, v95, 0.5, v195
	global_store_dwordx4 v148, v[92:95], s[88:89]
	v_mul_f32_e32 v217, v92, v92
	v_fmac_f32_e32 v217, v93, v93
	v_fmac_f32_e32 v217, v94, v94
	v_fmac_f32_e32 v217, v95, v95
	global_load_dwordx4 v[192:195], v149, s[86:87] offset:512
	s_waitcnt vmcnt(21)
	v_fma_f32 v88, v88, 0.5, v196
	v_fma_f32 v89, v89, 0.5, v197
	v_fma_f32 v90, v90, 0.5, v198
	v_fma_f32 v91, v91, 0.5, v199
	global_store_dwordx4 v149, v[88:91], s[88:89]
	v_mul_f32_e32 v212, v88, v88
	v_fmac_f32_e32 v212, v89, v89
	v_fmac_f32_e32 v212, v90, v90
	v_fmac_f32_e32 v212, v91, v91
	s_add_u32 s86, s86, 0x10000
	s_addc_u32 s87, s87, 0
	global_load_dwordx4 v[196:199], v148, s[86:87]
	v_mov_b32_e32 v156, v80
	v_mov_b32_e32 v157, v81
	v_mov_b32_e32 v158, v82
	v_mov_b32_e32 v159, v83
	v_mov_b32_dpp v80, v84 row_ror:8 row_mask:0xf bank_mask:0x3
	v_mov_b32_dpp v81, v85 row_ror:8 row_mask:0xf bank_mask:0x3
	v_mov_b32_dpp v82, v86 row_ror:8 row_mask:0xf bank_mask:0x3
	v_mov_b32_dpp v83, v87 row_ror:8 row_mask:0xf bank_mask:0x3
	v_mov_b32_dpp v84, v156 row_ror:8 row_mask:0xf bank_mask:0xc
	v_mov_b32_dpp v85, v157 row_ror:8 row_mask:0xf bank_mask:0xc
	v_mov_b32_dpp v86, v158 row_ror:8 row_mask:0xf bank_mask:0xc
	v_mov_b32_dpp v87, v159 row_ror:8 row_mask:0xf bank_mask:0xc
	s_waitcnt vmcnt(22)
	v_fma_f32 v84, v84, 0.5, v200
	v_fma_f32 v85, v85, 0.5, v201
	v_fma_f32 v86, v86, 0.5, v202
	v_fma_f32 v87, v87, 0.5, v203
	global_store_dwordx4 v148, v[84:87], s[88:89] offset:512
	v_fmac_f32_e32 v217, v84, v84
	v_fmac_f32_e32 v217, v85, v85
	v_fmac_f32_e32 v217, v86, v86
	v_fmac_f32_e32 v217, v87, v87
	global_load_dwordx4 v[200:203], v149, s[86:87]
	s_waitcnt vmcnt(22)
	v_fma_f32 v80, v80, 0.5, v160
	v_fma_f32 v81, v81, 0.5, v161
	v_fma_f32 v82, v82, 0.5, v162
	v_fma_f32 v83, v83, 0.5, v163
	global_store_dwordx4 v149, v[80:83], s[88:89] offset:512
	v_fmac_f32_e32 v212, v80, v80
	v_fmac_f32_e32 v212, v81, v81
	v_fmac_f32_e32 v212, v82, v82
	v_fmac_f32_e32 v212, v83, v83
	global_load_dwordx4 v[160:163], v148, s[86:87] offset:512
	s_nop 1
	v_add_f32_dpp v217, v217, v217 row_ror:8 row_mask:0xf bank_mask:0xf
	v_add_f32_dpp v212, v212, v212 row_ror:8 row_mask:0xf bank_mask:0xf
	s_nop 0
	ds_bpermute_b32 v147, v144, v217
	ds_bpermute_b32 v132, v144, v212
	s_waitcnt lgkmcnt(0)
	v_add_f32_e32 v217, v217, v147
	v_add_f32_e32 v212, v212, v132
	s_nop 0
	ds_bpermute_b32 v147, v145, v217
	ds_bpermute_b32 v132, v145, v212
	s_waitcnt lgkmcnt(0)
	v_add_f32_e32 v217, v217, v147
	v_add_f32_e32 v212, v212, v132
	v_cmp_gt_u32_e32 vcc, 8, v213
	s_nop 1
	v_cndmask_b32_e32 v217, v212, v217, vcc
	v_cmp_eq_u32_e32 vcc, 0, v146
	s_and_saveexec_b64 s[98:99], vcc
	global_store_dword v216, v217, s[100:101]
	s_mov_b64 exec, s[98:99]
	s_add_u32 s88, s88, 0x10000
	s_addc_u32 s89, s89, 0
	s_add_u32 s100, s100, 0x400
	s_addc_u32 s101, s101, 0
	v_mov_b32_e32 v156, v72
	v_mov_b32_e32 v157, v73
	v_mov_b32_e32 v158, v74
	v_mov_b32_e32 v159, v75
	v_mov_b32_dpp v72, v76 row_ror:8 row_mask:0xf bank_mask:0x3
	v_mov_b32_dpp v73, v77 row_ror:8 row_mask:0xf bank_mask:0x3
	v_mov_b32_dpp v74, v78 row_ror:8 row_mask:0xf bank_mask:0x3
	v_mov_b32_dpp v75, v79 row_ror:8 row_mask:0xf bank_mask:0x3
	v_mov_b32_dpp v76, v156 row_ror:8 row_mask:0xf bank_mask:0xc
	v_mov_b32_dpp v77, v157 row_ror:8 row_mask:0xf bank_mask:0xc
	v_mov_b32_dpp v78, v158 row_ror:8 row_mask:0xf bank_mask:0xc
	v_mov_b32_dpp v79, v159 row_ror:8 row_mask:0xf bank_mask:0xc
	s_waitcnt vmcnt(23)
	v_fma_f32 v76, v76, 0.5, v164
	v_fma_f32 v77, v77, 0.5, v165
	v_fma_f32 v78, v78, 0.5, v166
	v_fma_f32 v79, v79, 0.5, v167
	global_store_dwordx4 v148, v[76:79], s[88:89]
	v_mul_f32_e32 v217, v76, v76
	v_fmac_f32_e32 v217, v77, v77
	v_fmac_f32_e32 v217, v78, v78
	v_fmac_f32_e32 v217, v79, v79
	global_load_dwordx4 v[164:167], v149, s[86:87] offset:512
	s_waitcnt vmcnt(23)
	v_fma_f32 v72, v72, 0.5, v168
	v_fma_f32 v73, v73, 0.5, v169
	v_fma_f32 v74, v74, 0.5, v170
	v_fma_f32 v75, v75, 0.5, v171
	global_store_dwordx4 v149, v[72:75], s[88:89]
	v_mul_f32_e32 v212, v72, v72
	v_fmac_f32_e32 v212, v73, v73
	v_fmac_f32_e32 v212, v74, v74
	v_fmac_f32_e32 v212, v75, v75
	s_add_u32 s86, s86, 0x10000
	s_addc_u32 s87, s87, 0
	global_load_dwordx4 v[168:171], v148, s[86:87]
	v_mov_b32_e32 v156, v64
	v_mov_b32_e32 v157, v65
	v_mov_b32_e32 v158, v66
	v_mov_b32_e32 v159, v67
	v_mov_b32_dpp v64, v68 row_ror:8 row_mask:0xf bank_mask:0x3
	v_mov_b32_dpp v65, v69 row_ror:8 row_mask:0xf bank_mask:0x3
	v_mov_b32_dpp v66, v70 row_ror:8 row_mask:0xf bank_mask:0x3
	v_mov_b32_dpp v67, v71 row_ror:8 row_mask:0xf bank_mask:0x3
	v_mov_b32_dpp v68, v156 row_ror:8 row_mask:0xf bank_mask:0xc
	v_mov_b32_dpp v69, v157 row_ror:8 row_mask:0xf bank_mask:0xc
	v_mov_b32_dpp v70, v158 row_ror:8 row_mask:0xf bank_mask:0xc
	v_mov_b32_dpp v71, v159 row_ror:8 row_mask:0xf bank_mask:0xc
	s_waitcnt vmcnt(23)
	v_fma_f32 v68, v68, 0.5, v172
	v_fma_f32 v69, v69, 0.5, v173
	v_fma_f32 v70, v70, 0.5, v174
	v_fma_f32 v71, v71, 0.5, v175
	global_store_dwordx4 v148, v[68:71], s[88:89] offset:512
	v_fmac_f32_e32 v217, v68, v68
	v_fmac_f32_e32 v217, v69, v69
	v_fmac_f32_e32 v217, v70, v70
	v_fmac_f32_e32 v217, v71, v71
	global_load_dwordx4 v[172:175], v149, s[86:87]
	s_waitcnt vmcnt(22)
	v_fma_f32 v64, v64, 0.5, v176
	v_fma_f32 v65, v65, 0.5, v177
	v_fma_f32 v66, v66, 0.5, v178
	v_fma_f32 v67, v67, 0.5, v179
	global_store_dwordx4 v149, v[64:67], s[88:89] offset:512
	v_fmac_f32_e32 v212, v64, v64
	v_fmac_f32_e32 v212, v65, v65
	v_fmac_f32_e32 v212, v66, v66
	v_fmac_f32_e32 v212, v67, v67
	global_load_dwordx4 v[176:179], v148, s[86:87] offset:512
	s_nop 1
	v_add_f32_dpp v217, v217, v217 row_ror:8 row_mask:0xf bank_mask:0xf
	v_add_f32_dpp v212, v212, v212 row_ror:8 row_mask:0xf bank_mask:0xf
	s_nop 0
	ds_bpermute_b32 v147, v144, v217
	ds_bpermute_b32 v132, v144, v212
	s_waitcnt lgkmcnt(0)
	v_add_f32_e32 v217, v217, v147
	v_add_f32_e32 v212, v212, v132
	s_nop 0
	ds_bpermute_b32 v147, v145, v217
	ds_bpermute_b32 v132, v145, v212
	s_waitcnt lgkmcnt(0)
	v_add_f32_e32 v217, v217, v147
	v_add_f32_e32 v212, v212, v132
	v_cmp_gt_u32_e32 vcc, 8, v213
	s_nop 1
	v_cndmask_b32_e32 v217, v212, v217, vcc
	v_cmp_eq_u32_e32 vcc, 0, v146
	s_and_saveexec_b64 s[98:99], vcc
	global_store_dword v216, v217, s[100:101]
	s_mov_b64 exec, s[98:99]
	s_add_u32 s88, s88, 0x50000
	s_addc_u32 s89, s89, 0
	s_add_u32 s100, s100, 0x1400
	s_addc_u32 s101, s101, 0
	v_mov_b32_e32 v156, v56
	v_mov_b32_e32 v157, v57
	v_mov_b32_e32 v158, v58
	v_mov_b32_e32 v159, v59
	v_mov_b32_dpp v56, v60 row_ror:8 row_mask:0xf bank_mask:0x3
	v_mov_b32_dpp v57, v61 row_ror:8 row_mask:0xf bank_mask:0x3
	v_mov_b32_dpp v58, v62 row_ror:8 row_mask:0xf bank_mask:0x3
	v_mov_b32_dpp v59, v63 row_ror:8 row_mask:0xf bank_mask:0x3
	v_mov_b32_dpp v60, v156 row_ror:8 row_mask:0xf bank_mask:0xc
	v_mov_b32_dpp v61, v157 row_ror:8 row_mask:0xf bank_mask:0xc
	v_mov_b32_dpp v62, v158 row_ror:8 row_mask:0xf bank_mask:0xc
	v_mov_b32_dpp v63, v159 row_ror:8 row_mask:0xf bank_mask:0xc
	s_waitcnt vmcnt(23)
	v_fma_f32 v60, v60, 0.5, v180
	v_fma_f32 v61, v61, 0.5, v181
	v_fma_f32 v62, v62, 0.5, v182
	v_fma_f32 v63, v63, 0.5, v183
	global_store_dwordx4 v148, v[60:63], s[88:89]
	v_mul_f32_e32 v217, v60, v60
	v_fmac_f32_e32 v217, v61, v61
	v_fmac_f32_e32 v217, v62, v62
	v_fmac_f32_e32 v217, v63, v63
	global_load_dwordx4 v[180:183], v149, s[86:87] offset:512
	s_waitcnt vmcnt(23)
	v_fma_f32 v56, v56, 0.5, v184
	v_fma_f32 v57, v57, 0.5, v185
	v_fma_f32 v58, v58, 0.5, v186
	v_fma_f32 v59, v59, 0.5, v187
	global_store_dwordx4 v149, v[56:59], s[88:89]
	v_mul_f32_e32 v212, v56, v56
	v_fmac_f32_e32 v212, v57, v57
	v_fmac_f32_e32 v212, v58, v58
	v_fmac_f32_e32 v212, v59, v59
	s_add_u32 s86, s86, 0x10000
	s_addc_u32 s87, s87, 0
	global_load_dwordx4 v[184:187], v148, s[86:87]
	v_mov_b32_e32 v156, v48
	v_mov_b32_e32 v157, v49
	v_mov_b32_e32 v158, v50
	v_mov_b32_e32 v159, v51
	v_mov_b32_dpp v48, v52 row_ror:8 row_mask:0xf bank_mask:0x3
	v_mov_b32_dpp v49, v53 row_ror:8 row_mask:0xf bank_mask:0x3
	v_mov_b32_dpp v50, v54 row_ror:8 row_mask:0xf bank_mask:0x3
	v_mov_b32_dpp v51, v55 row_ror:8 row_mask:0xf bank_mask:0x3
	v_mov_b32_dpp v52, v156 row_ror:8 row_mask:0xf bank_mask:0xc
	v_mov_b32_dpp v53, v157 row_ror:8 row_mask:0xf bank_mask:0xc
	v_mov_b32_dpp v54, v158 row_ror:8 row_mask:0xf bank_mask:0xc
	v_mov_b32_dpp v55, v159 row_ror:8 row_mask:0xf bank_mask:0xc
	s_waitcnt vmcnt(23)
	v_fma_f32 v52, v52, 0.5, v188
	v_fma_f32 v53, v53, 0.5, v189
	v_fma_f32 v54, v54, 0.5, v190
	v_fma_f32 v55, v55, 0.5, v191
	global_store_dwordx4 v148, v[52:55], s[88:89] offset:512
	v_fmac_f32_e32 v217, v52, v52
	v_fmac_f32_e32 v217, v53, v53
	v_fmac_f32_e32 v217, v54, v54
	v_fmac_f32_e32 v217, v55, v55
	global_load_dwordx4 v[188:191], v149, s[86:87]
	s_waitcnt vmcnt(22)
	v_fma_f32 v48, v48, 0.5, v192
	v_fma_f32 v49, v49, 0.5, v193
	v_fma_f32 v50, v50, 0.5, v194
	v_fma_f32 v51, v51, 0.5, v195
	global_store_dwordx4 v149, v[48:51], s[88:89] offset:512
	v_fmac_f32_e32 v212, v48, v48
	v_fmac_f32_e32 v212, v49, v49
	v_fmac_f32_e32 v212, v50, v50
	v_fmac_f32_e32 v212, v51, v51
	global_load_dwordx4 v[192:195], v148, s[86:87] offset:512
	s_nop 1
	v_add_f32_dpp v217, v217, v217 row_ror:8 row_mask:0xf bank_mask:0xf
	v_add_f32_dpp v212, v212, v212 row_ror:8 row_mask:0xf bank_mask:0xf
	s_nop 0
	ds_bpermute_b32 v147, v144, v217
	ds_bpermute_b32 v132, v144, v212
	s_waitcnt lgkmcnt(0)
	v_add_f32_e32 v217, v217, v147
	v_add_f32_e32 v212, v212, v132
	s_nop 0
	ds_bpermute_b32 v147, v145, v217
	ds_bpermute_b32 v132, v145, v212
	s_waitcnt lgkmcnt(0)
	v_add_f32_e32 v217, v217, v147
	v_add_f32_e32 v212, v212, v132
	v_cmp_gt_u32_e32 vcc, 8, v213
	s_nop 1
	v_cndmask_b32_e32 v217, v212, v217, vcc
	v_cmp_eq_u32_e32 vcc, 0, v146
	s_and_saveexec_b64 s[98:99], vcc
	global_store_dword v216, v217, s[100:101]
	s_mov_b64 exec, s[98:99]
	s_add_u32 s88, s88, 0x10000
	s_addc_u32 s89, s89, 0
	s_add_u32 s100, s100, 0x400
	s_addc_u32 s101, s101, 0
	v_mov_b32_e32 v156, v40
	v_mov_b32_e32 v157, v41
	v_mov_b32_e32 v158, v42
	v_mov_b32_e32 v159, v43
	v_mov_b32_dpp v40, v44 row_ror:8 row_mask:0xf bank_mask:0x3
	v_mov_b32_dpp v41, v45 row_ror:8 row_mask:0xf bank_mask:0x3
	v_mov_b32_dpp v42, v46 row_ror:8 row_mask:0xf bank_mask:0x3
	v_mov_b32_dpp v43, v47 row_ror:8 row_mask:0xf bank_mask:0x3
	v_mov_b32_dpp v44, v156 row_ror:8 row_mask:0xf bank_mask:0xc
	v_mov_b32_dpp v45, v157 row_ror:8 row_mask:0xf bank_mask:0xc
	v_mov_b32_dpp v46, v158 row_ror:8 row_mask:0xf bank_mask:0xc
	v_mov_b32_dpp v47, v159 row_ror:8 row_mask:0xf bank_mask:0xc
	s_waitcnt vmcnt(23)
	v_fma_f32 v44, v44, 0.5, v196
	v_fma_f32 v45, v45, 0.5, v197
	v_fma_f32 v46, v46, 0.5, v198
	v_fma_f32 v47, v47, 0.5, v199
	global_store_dwordx4 v148, v[44:47], s[88:89]
	v_mul_f32_e32 v217, v44, v44
	v_fmac_f32_e32 v217, v45, v45
	v_fmac_f32_e32 v217, v46, v46
	v_fmac_f32_e32 v217, v47, v47
	global_load_dwordx4 v[196:199], v149, s[86:87] offset:512
	s_waitcnt vmcnt(23)
	v_fma_f32 v40, v40, 0.5, v200
	v_fma_f32 v41, v41, 0.5, v201
	v_fma_f32 v42, v42, 0.5, v202
	v_fma_f32 v43, v43, 0.5, v203
	global_store_dwordx4 v149, v[40:43], s[88:89]
	v_mul_f32_e32 v212, v40, v40
	v_fmac_f32_e32 v212, v41, v41
	v_fmac_f32_e32 v212, v42, v42
	v_fmac_f32_e32 v212, v43, v43
	v_mov_b32_e32 v156, v32
	v_mov_b32_e32 v157, v33
	v_mov_b32_e32 v158, v34
	v_mov_b32_e32 v159, v35
	v_mov_b32_dpp v32, v36 row_ror:8 row_mask:0xf bank_mask:0x3
	v_mov_b32_dpp v33, v37 row_ror:8 row_mask:0xf bank_mask:0x3
	v_mov_b32_dpp v34, v38 row_ror:8 row_mask:0xf bank_mask:0x3
	v_mov_b32_dpp v35, v39 row_ror:8 row_mask:0xf bank_mask:0x3
	v_mov_b32_dpp v36, v156 row_ror:8 row_mask:0xf bank_mask:0xc
	v_mov_b32_dpp v37, v157 row_ror:8 row_mask:0xf bank_mask:0xc
	v_mov_b32_dpp v38, v158 row_ror:8 row_mask:0xf bank_mask:0xc
	v_mov_b32_dpp v39, v159 row_ror:8 row_mask:0xf bank_mask:0xc
	s_waitcnt vmcnt(22)
	v_fma_f32 v36, v36, 0.5, v160
	v_fma_f32 v37, v37, 0.5, v161
	v_fma_f32 v38, v38, 0.5, v162
	v_fma_f32 v39, v39, 0.5, v163
	global_store_dwordx4 v148, v[36:39], s[88:89] offset:512
	v_fmac_f32_e32 v217, v36, v36
	v_fmac_f32_e32 v217, v37, v37
	v_fmac_f32_e32 v217, v38, v38
	v_fmac_f32_e32 v217, v39, v39
	s_waitcnt vmcnt(20)
	v_fma_f32 v32, v32, 0.5, v164
	v_fma_f32 v33, v33, 0.5, v165
	v_fma_f32 v34, v34, 0.5, v166
	v_fma_f32 v35, v35, 0.5, v167
	global_store_dwordx4 v149, v[32:35], s[88:89] offset:512
	v_fmac_f32_e32 v212, v32, v32
	v_fmac_f32_e32 v212, v33, v33
	v_fmac_f32_e32 v212, v34, v34
	v_fmac_f32_e32 v212, v35, v35
	s_nop 1
	v_add_f32_dpp v217, v217, v217 row_ror:8 row_mask:0xf bank_mask:0xf
	v_add_f32_dpp v212, v212, v212 row_ror:8 row_mask:0xf bank_mask:0xf
	s_nop 0
	ds_bpermute_b32 v147, v144, v217
	ds_bpermute_b32 v132, v144, v212
	s_waitcnt lgkmcnt(0)
	v_add_f32_e32 v217, v217, v147
	v_add_f32_e32 v212, v212, v132
	s_nop 0
	ds_bpermute_b32 v147, v145, v217
	ds_bpermute_b32 v132, v145, v212
	s_waitcnt lgkmcnt(0)
	v_add_f32_e32 v217, v217, v147
	v_add_f32_e32 v212, v212, v132
	v_cmp_gt_u32_e32 vcc, 8, v213
	s_nop 1
	v_cndmask_b32_e32 v217, v212, v217, vcc
	v_cmp_eq_u32_e32 vcc, 0, v146
	s_and_saveexec_b64 s[98:99], vcc
	global_store_dword v216, v217, s[100:101]
	s_mov_b64 exec, s[98:99]
	s_add_u32 s88, s88, 0x10000
	s_addc_u32 s89, s89, 0
	s_add_u32 s100, s100, 0x400
	s_addc_u32 s101, s101, 0
	v_mov_b32_e32 v156, v24
	v_mov_b32_e32 v157, v25
	v_mov_b32_e32 v158, v26
	v_mov_b32_e32 v159, v27
	v_mov_b32_dpp v24, v28 row_ror:8 row_mask:0xf bank_mask:0x3
	v_mov_b32_dpp v25, v29 row_ror:8 row_mask:0xf bank_mask:0x3
	v_mov_b32_dpp v26, v30 row_ror:8 row_mask:0xf bank_mask:0x3
	v_mov_b32_dpp v27, v31 row_ror:8 row_mask:0xf bank_mask:0x3
	v_mov_b32_dpp v28, v156 row_ror:8 row_mask:0xf bank_mask:0xc
	v_mov_b32_dpp v29, v157 row_ror:8 row_mask:0xf bank_mask:0xc
	v_mov_b32_dpp v30, v158 row_ror:8 row_mask:0xf bank_mask:0xc
	v_mov_b32_dpp v31, v159 row_ror:8 row_mask:0xf bank_mask:0xc
	s_waitcnt vmcnt(20)
	v_fma_f32 v28, v28, 0.5, v168
	v_fma_f32 v29, v29, 0.5, v169
	v_fma_f32 v30, v30, 0.5, v170
	v_fma_f32 v31, v31, 0.5, v171
	global_store_dwordx4 v148, v[28:31], s[88:89]
	v_mul_f32_e32 v217, v28, v28
	v_fmac_f32_e32 v217, v29, v29
	v_fmac_f32_e32 v217, v30, v30
	v_fmac_f32_e32 v217, v31, v31
	s_waitcnt vmcnt(19)
	v_fma_f32 v24, v24, 0.5, v172
	v_fma_f32 v25, v25, 0.5, v173
	v_fma_f32 v26, v26, 0.5, v174
	v_fma_f32 v27, v27, 0.5, v175
	global_store_dwordx4 v149, v[24:27], s[88:89]
	v_mul_f32_e32 v212, v24, v24
	v_fmac_f32_e32 v212, v25, v25
	v_fmac_f32_e32 v212, v26, v26
	v_fmac_f32_e32 v212, v27, v27
	v_mov_b32_e32 v156, v16
	v_mov_b32_e32 v157, v17
	v_mov_b32_e32 v158, v18
	v_mov_b32_e32 v159, v19
	v_mov_b32_dpp v16, v20 row_ror:8 row_mask:0xf bank_mask:0x3
	v_mov_b32_dpp v17, v21 row_ror:8 row_mask:0xf bank_mask:0x3
	v_mov_b32_dpp v18, v22 row_ror:8 row_mask:0xf bank_mask:0x3
	v_mov_b32_dpp v19, v23 row_ror:8 row_mask:0xf bank_mask:0x3
	v_mov_b32_dpp v20, v156 row_ror:8 row_mask:0xf bank_mask:0xc
	v_mov_b32_dpp v21, v157 row_ror:8 row_mask:0xf bank_mask:0xc
	v_mov_b32_dpp v22, v158 row_ror:8 row_mask:0xf bank_mask:0xc
	v_mov_b32_dpp v23, v159 row_ror:8 row_mask:0xf bank_mask:0xc
	s_waitcnt vmcnt(18)
	v_fma_f32 v20, v20, 0.5, v176
	v_fma_f32 v21, v21, 0.5, v177
	v_fma_f32 v22, v22, 0.5, v178
	v_fma_f32 v23, v23, 0.5, v179
	global_store_dwordx4 v148, v[20:23], s[88:89] offset:512
	v_fmac_f32_e32 v217, v20, v20
	v_fmac_f32_e32 v217, v21, v21
	v_fmac_f32_e32 v217, v22, v22
	v_fmac_f32_e32 v217, v23, v23
	s_waitcnt vmcnt(16)
	v_fma_f32 v16, v16, 0.5, v180
	v_fma_f32 v17, v17, 0.5, v181
	v_fma_f32 v18, v18, 0.5, v182
	v_fma_f32 v19, v19, 0.5, v183
	global_store_dwordx4 v149, v[16:19], s[88:89] offset:512
	v_fmac_f32_e32 v212, v16, v16
	v_fmac_f32_e32 v212, v17, v17
	v_fmac_f32_e32 v212, v18, v18
	v_fmac_f32_e32 v212, v19, v19
	s_nop 1
	v_add_f32_dpp v217, v217, v217 row_ror:8 row_mask:0xf bank_mask:0xf
	v_add_f32_dpp v212, v212, v212 row_ror:8 row_mask:0xf bank_mask:0xf
	s_nop 0
	ds_bpermute_b32 v147, v144, v217
	ds_bpermute_b32 v132, v144, v212
	s_waitcnt lgkmcnt(0)
	v_add_f32_e32 v217, v217, v147
	v_add_f32_e32 v212, v212, v132
	s_nop 0
	ds_bpermute_b32 v147, v145, v217
	ds_bpermute_b32 v132, v145, v212
	s_waitcnt lgkmcnt(0)
	v_add_f32_e32 v217, v217, v147
	v_add_f32_e32 v212, v212, v132
	v_cmp_gt_u32_e32 vcc, 8, v213
	s_nop 1
	v_cndmask_b32_e32 v217, v212, v217, vcc
	v_cmp_eq_u32_e32 vcc, 0, v146
	s_and_saveexec_b64 s[98:99], vcc
	global_store_dword v216, v217, s[100:101]
	s_mov_b64 exec, s[98:99]
	s_add_u32 s88, s88, 0x10000
	s_addc_u32 s89, s89, 0
	s_add_u32 s100, s100, 0x400
	s_addc_u32 s101, s101, 0
	v_mov_b32_e32 v156, v8
	v_mov_b32_e32 v157, v9
	v_mov_b32_e32 v158, v10
	v_mov_b32_e32 v159, v11
	v_mov_b32_dpp v8, v12 row_ror:8 row_mask:0xf bank_mask:0x3
	v_mov_b32_dpp v9, v13 row_ror:8 row_mask:0xf bank_mask:0x3
	v_mov_b32_dpp v10, v14 row_ror:8 row_mask:0xf bank_mask:0x3
	v_mov_b32_dpp v11, v15 row_ror:8 row_mask:0xf bank_mask:0x3
	v_mov_b32_dpp v12, v156 row_ror:8 row_mask:0xf bank_mask:0xc
	v_mov_b32_dpp v13, v157 row_ror:8 row_mask:0xf bank_mask:0xc
	v_mov_b32_dpp v14, v158 row_ror:8 row_mask:0xf bank_mask:0xc
	v_mov_b32_dpp v15, v159 row_ror:8 row_mask:0xf bank_mask:0xc
	s_waitcnt vmcnt(16)
	v_fma_f32 v12, v12, 0.5, v184
	v_fma_f32 v13, v13, 0.5, v185
	v_fma_f32 v14, v14, 0.5, v186
	v_fma_f32 v15, v15, 0.5, v187
	global_store_dwordx4 v148, v[12:15], s[88:89]
	v_mul_f32_e32 v217, v12, v12
	v_fmac_f32_e32 v217, v13, v13
	v_fmac_f32_e32 v217, v14, v14
	v_fmac_f32_e32 v217, v15, v15
	s_waitcnt vmcnt(15)
	v_fma_f32 v8, v8, 0.5, v188
	v_fma_f32 v9, v9, 0.5, v189
	v_fma_f32 v10, v10, 0.5, v190
	v_fma_f32 v11, v11, 0.5, v191
	global_store_dwordx4 v149, v[8:11], s[88:89]
	v_mul_f32_e32 v212, v8, v8
	v_fmac_f32_e32 v212, v9, v9
	v_fmac_f32_e32 v212, v10, v10
	v_fmac_f32_e32 v212, v11, v11
	v_mov_b32_e32 v156, v0
	v_mov_b32_e32 v157, v1
	v_mov_b32_e32 v158, v2
	v_mov_b32_e32 v159, v3
	v_mov_b32_dpp v0, v4 row_ror:8 row_mask:0xf bank_mask:0x3
	v_mov_b32_dpp v1, v5 row_ror:8 row_mask:0xf bank_mask:0x3
	v_mov_b32_dpp v2, v6 row_ror:8 row_mask:0xf bank_mask:0x3
	v_mov_b32_dpp v3, v7 row_ror:8 row_mask:0xf bank_mask:0x3
	v_mov_b32_dpp v4, v156 row_ror:8 row_mask:0xf bank_mask:0xc
	v_mov_b32_dpp v5, v157 row_ror:8 row_mask:0xf bank_mask:0xc
	v_mov_b32_dpp v6, v158 row_ror:8 row_mask:0xf bank_mask:0xc
	v_mov_b32_dpp v7, v159 row_ror:8 row_mask:0xf bank_mask:0xc
	s_waitcnt vmcnt(14)
	v_fma_f32 v4, v4, 0.5, v192
	v_fma_f32 v5, v5, 0.5, v193
	v_fma_f32 v6, v6, 0.5, v194
	v_fma_f32 v7, v7, 0.5, v195
	global_store_dwordx4 v148, v[4:7], s[88:89] offset:512
	v_fmac_f32_e32 v217, v4, v4
	v_fmac_f32_e32 v217, v5, v5
	v_fmac_f32_e32 v217, v6, v6
	v_fmac_f32_e32 v217, v7, v7
	s_waitcnt vmcnt(12)
	v_fma_f32 v0, v0, 0.5, v196
	v_fma_f32 v1, v1, 0.5, v197
	v_fma_f32 v2, v2, 0.5, v198
	v_fma_f32 v3, v3, 0.5, v199
	global_store_dwordx4 v149, v[0:3], s[88:89] offset:512
	v_fmac_f32_e32 v212, v0, v0
	v_fmac_f32_e32 v212, v1, v1
	v_fmac_f32_e32 v212, v2, v2
	v_fmac_f32_e32 v212, v3, v3
	s_nop 1
	v_add_f32_dpp v217, v217, v217 row_ror:8 row_mask:0xf bank_mask:0xf
	v_add_f32_dpp v212, v212, v212 row_ror:8 row_mask:0xf bank_mask:0xf
	s_nop 0
	ds_bpermute_b32 v147, v144, v217
	ds_bpermute_b32 v132, v144, v212
	s_waitcnt lgkmcnt(0)
	v_add_f32_e32 v217, v217, v147
	v_add_f32_e32 v212, v212, v132
	s_nop 0
	ds_bpermute_b32 v147, v145, v217
	ds_bpermute_b32 v132, v145, v212
	s_waitcnt lgkmcnt(0)
	v_add_f32_e32 v217, v217, v147
	v_add_f32_e32 v212, v212, v132
	v_cmp_gt_u32_e32 vcc, 8, v213
	s_nop 1
	v_cndmask_b32_e32 v217, v212, v217, vcc
	v_cmp_eq_u32_e32 vcc, 0, v146
	s_and_saveexec_b64 s[98:99], vcc
	global_store_dword v216, v217, s[100:101]
	s_mov_b64 exec, s[98:99]
	s_and_b64 vcc, exec, s[8:9]
	s_mov_b64 s[8:9], -1
	s_cbranch_vccnz .LBB0_1477
	s_andn2_b64 vcc, exec, s[14:15]
	s_cbranch_vccnz .LBB0_1476
	s_barrier
	s_branch .LBB0_1476
